# merge the 8 GEMM phases into 4 super-phases per 2 K-tiles (32 MFMA per barrier pair, restaged LDS-DMA schedule, vmcnt 8) in all 6 GEMM loops
# speedup vs baseline: 1.0170x; 1.0170x over previous
; #define PG8_STAGE(bufoff, gbase, voff) do { _Pragma("unroll") for (int _i = 0; _i < 2; ++_i) \
;         __builtin_amdgcn_global_load_lds((const unsigned*)((const char*)(gbase) + (voff)[_i]), (LAS unsigned*)(lds + (bufoff) + ldsw + _i * 8192), 16, 0, 0); } while (0)
; #define PG8_WAIT_V(n) asm volatile("s_waitcnt vmcnt(" #n ")" ::: "memory")
; #define PG8_BAR __builtin_amdgcn_s_barrier()
; template <class Epi>
; __device__ __forceinline__ void gemm_phase(LAS unsigned char* lds, const Gemm g, const StaticOrder& S, const Epi& E) {
;     ...
;     for (int i = 0; i < 2; ++i) { int R, C; stage_rc(tid * 16 + i * 8192, R, C); const int Rb = Epi::PERM ? ((R & ~31) + perm32(R & 31)) : R;
;         voffA[i] = (unsigned)(R * BK + C) * 2u; voffB[i] = (unsigned)(Rb * BK + C) * 2u; }
;     const size_t kstepA = (size_t)g.M * BK * 2, kstepB = (size_t)g.N * BK * 2;
;     const size_t hstep = (size_t)HALF * BK * 2;
;     const size_t tstep = 2 * hstep;
;     const unsigned ldsw = (unsigned)wid * 1024u;
;     const int aoff = lds_byte(wr * 64 + fr, fq * 8), boff = lds_byte(wc * 32 + fr, fq * 8);
;     ...
;     Unit cur, nxt; int ui = 0;
;     if (!S.next(0, cur)) return;
;     f32x4 acc[2][2][4][2];
; #pragma unroll
;     for (int a = 0; a < 2; ++a)
; #pragma unroll
;         for (int b = 0; b < 2; ++b)
; #pragma unroll
;             for (int m = 0; m < 4; ++m)
; #pragma unroll
;                 for (int n = 0; n < 2; ++n) acc[a][b][m][n] = (f32x4){0.f, 0.f, 0.f, 0.f};
;     bf16x8 At[4][2], B0[2][2], B1[2][2];
;     const char* cA = (const char*)g.A + (size_t)cur.pm * tstep; const char* cB = (const char*)g.Bt + (size_t)cur.pn * tstep;
;     PG8_STAGE(PG8_SB(0, 0), cB, voffB); PG8_STAGE(PG8_SA(0, 0), cA, voffA); PG8_STAGE(PG8_SB(0, 1), cB + hstep, voffB); PG8_STAGE(PG8_SA(0, 1), cA + hstep, voffA);
;     if (wr == 1) PG8_BAR;
;     PG8_WAIT_V(4); PG8_BAR;
;     PG8_STAGE(PG8_SB(1, 0), cB + kstepB, voffB); PG8_STAGE(PG8_SA(1, 0), cA + kstepA, voffA); PG8_STAGE(PG8_SB(1, 1), cB + hstep + kstepB, voffB);
;     PG8_WAIT_V(6); PG8_BAR;
.LBB0_206:
	s_lshl_b32 s7, s4, 5
	s_and_b32 s49, s7, 0x60
	s_lshl_b32 s6, s1, 13
	s_lshl_b32 s8, s49, 7
	s_add_u32 s4, s28, 0x160000
	s_addc_u32 s5, s29, 0
	s_add_i32 m0, s42, 0x18000
	v_lshl_add_u64 v[8:9], s[4:5], 0, v[130:131]
	s_waitcnt vmcnt(2)
	s_barrier
	global_load_lds_dwordx4 v[8:9], off
	s_add_i32 m0, s42, 0x1a000
	v_lshl_add_u64 v[8:9], s[4:5], 0, v[128:129]
	s_add_u32 s4, s30, 0x400000
	s_addc_u32 s5, s31, 0
	s_add_i32 s50, s42, 0x8000
	global_load_lds_dwordx4 v[8:9], off
	v_lshl_add_u64 v[8:9], s[4:5], 0, v[130:131]
	s_mov_b32 m0, s50
	s_add_i32 s51, s42, 0xa000
	global_load_lds_dwordx4 v[8:9], off
	v_lshl_add_u64 v[8:9], s[4:5], 0, v[128:129]
	s_add_u32 s4, s28, 0x164000
	s_mov_b32 m0, s51
	s_addc_u32 s5, s29, 0
	global_load_lds_dwordx4 v[8:9], off
	s_add_i32 m0, s42, 0x1c000
	v_lshl_add_u64 v[8:9], s[4:5], 0, v[130:131]
	global_load_lds_dwordx4 v[8:9], off
	v_lshl_add_u64 v[8:9], s[4:5], 0, v[128:129]
	s_add_i32 m0, s42, 0x1e000
	v_and_b32_e32 v7, 15, v1
	global_load_lds_dwordx4 v[8:9], off
	v_lshrrev_b32_e32 v8, 1, v1
	v_and_b32_e32 v8, 24, v8
	v_lshlrev_b32_e32 v9, 1, v8
	v_lshlrev_b32_e32 v1, 2, v1
	v_lshl_or_b32 v150, s1, 6, v7
	v_lshl_or_b32 v7, v7, 6, v9
	v_and_b32_e32 v1, 32, v1
	s_waitcnt vmcnt(0)
	v_bitop3_b32 v10, v7, s6, v1 bitop3:0xde
	v_bitop3_b32 v151, v7, s8, v1 bitop3:0xde
	v_and_or_b32 v1, s7, 32, v8
	v_lshlrev_b32_e32 v8, 1, v1
	v_lshlrev_b32_e32 v1, 10, v4
	v_and_b32_e32 v1, 0xfffff800, v1
	v_lshl_add_u32 v1, v5, 7, v1
	v_and_b32_e32 v4, 1, v4
	v_lshl_or_b32 v1, v4, 6, v1
	v_lshl_add_u32 v134, v6, 1, v1
	v_lshlrev_b32_e32 v1, 10, v0
	v_and_b32_e32 v1, 0xfffff800, v1
	s_waitcnt vmcnt(6)
	v_lshl_add_u32 v1, v2, 7, v1
	v_and_b32_e32 v0, 1, v0
	v_mov_b32_e32 v9, v131
	v_lshl_or_b32 v0, v0, 6, v1
	s_add_i32 s54, 0, 0x10000
	s_add_i32 s55, 0, 0x14000
	s_sext_i32_i16 s13, s0
	v_lshl_add_u64 v[132:133], s[2:3], 0, v[8:9]
	s_ashr_i32 s52, s86, 31
	s_mov_b32 s53, s86
	v_mov_b32_e32 v135, v131
	v_lshl_add_u32 v136, v3, 1, v0
	v_mov_b32_e32 v137, v131
	v_mov_b64_e32 v[138:139], 0x1600
	v_mov_b64_e32 v[140:141], 0x15ff
	v_add_u32_e32 v152, s54, v151
	v_add_u32_e32 v153, 0, v10
	v_add_u32_e32 v154, s55, v151
	s_barrier

; #define PG8_STAGE(bufoff, gbase, voff) do { _Pragma("unroll") for (int _i = 0; _i < 2; ++_i) \
;         __builtin_amdgcn_global_load_lds((const unsigned*)((const char*)(gbase) + (voff)[_i]), (LAS unsigned*)(lds + (bufoff) + ldsw + _i * 8192), 16, 0, 0); } while (0)
; #define PG8_LDA(dst, b, h) do { _Pragma("unroll") for (int m = 0; m < 4; ++m) _Pragma("unroll") for (int k = 0; k < 2; ++k) dst[m][k] = *(const LAS bf16x8*)(lds + PG8_SA(b, h) + aoff + m * 2048 + k * 1024); } while (0)
; #define PG8_LDB(dst, b, h) do { _Pragma("unroll") for (int n = 0; n < 2; ++n) _Pragma("unroll") for (int k = 0; k < 2; ++k) dst[n][k] = *(const LAS bf16x8*)(lds + PG8_SB(b, h) + boff + n * 2048 + k * 1024); } while (0)
; #define PG8_MMA(ai, bj, At, Bt) do { __builtin_amdgcn_s_setprio(1); _Pragma("unroll") for (int m = 0; m < 4; ++m) _Pragma("unroll") for (int n = 0; n < 2; ++n) _Pragma("unroll") for (int k = 0; k < 2; ++k) \
;         acc[ai][bj][m][n] = __builtin_amdgcn_mfma_f32_16x16x32_bf16(Bt[n][k], At[m][k], acc[ai][bj][m][n], 0, 0, 0); __builtin_amdgcn_s_setprio(0); } while (0)
; #define PG8_WAIT_V(n) asm volatile("s_waitcnt vmcnt(" #n ")" ::: "memory")
; #define PG8_WAIT_L(n) asm volatile("s_waitcnt lgkmcnt(" #n ")" ::: "memory")
; template <class Epi>
; __device__ __forceinline__ void gemm_phase(LAS unsigned char* lds, const Gemm g, const StaticOrder& S, const Epi& E) {
;     ...
;         for (int t = 0; t < nt; t += 2) {
;             const bool last = (t == nt - 2);
;             const char* a1 = cA + (size_t)(t + 1) * kstepA;
;             const char* a2 = last ? nA : cA + (size_t)(t + 2) * kstepA; const char* b2 = last ? nB : cB + (size_t)(t + 2) * kstepB;
;             const char* a3 = a2 + kstepA; const char* b3 = b2 + kstepB;
;             PG8_LDB(B0, 0, 0); PG8_SCHED; PG8_LDA(At, 0, 0); PG8_STAGE(PG8_SA(1, 1), a1 + hstep, voffA);
;             PG8_WAIT_L(8); PG8_BAR; PG8_WAIT_L(0); PG8_MMA(0, 0, At, B0); PG8_BAR; PG8_SCHED;
;             PG8_LDB(B1, 0, 1); PG8_STAGE(PG8_SB(0, 0), b2, voffB);
;             PG8_BAR; PG8_WAIT_L(0); PG8_MMA(0, 1, At, B1); PG8_BAR;
;             PG8_LDA(At, 0, 1); PG8_STAGE(PG8_SA(0, 0), a2, voffA);
;             PG8_BAR; PG8_WAIT_L(0); PG8_MMA(1, 0, At, B0); PG8_BAR; PG8_SCHED;
;             PG8_STAGE(PG8_SB(0, 1), b2 + hstep, voffB);
;             PG8_WAIT_V(6); PG8_BAR; PG8_MMA(1, 1, At, B1); PG8_BAR;
.LBB0_210:
	ds_read_b128 v[156:159], v152
	ds_read_b128 v[160:163], v152 offset:1024
	ds_read_b128 v[164:167], v152 offset:2048
	ds_read_b128 v[168:171], v152 offset:3072
	s_add_u32 s30, s28, 0x3fc000
	s_addc_u32 s31, s29, 0
	s_cmp_eq_u32 s60, 28
	s_cselect_b32 s36, s56, s30
	s_cselect_b32 s37, s7, s31
	s_cselect_b32 s30, s57, s58
	s_cselect_b32 s31, s5, s59
	s_add_u32 s34, s36, 0x400000
	s_addc_u32 s35, s37, 0
	v_lshl_add_u64 v[142:143], s[28:29], 0, v[134:135]
	s_add_i32 m0, s42, 0xc000
	ds_read_b128 v[172:175], v153
	ds_read_b128 v[176:179], v153 offset:1024
	ds_read_b128 v[184:187], v153 offset:2048
	ds_read_b128 v[188:191], v153 offset:3072
	ds_read_b128 v[192:195], v153 offset:4096
	ds_read_b128 v[196:199], v153 offset:5120
	ds_read_b128 v[200:203], v153 offset:6144
	ds_read_b128 v[204:207], v153 offset:7168
	global_load_lds_dwordx4 v[142:143], off
	v_lshl_add_u64 v[142:143], s[28:29], 0, v[136:137]
	s_add_i32 m0, s42, 0xe000
	s_nop 0
	global_load_lds_dwordx4 v[142:143], off
	ds_read_b128 v[208:211], v154
	ds_read_b128 v[212:215], v154 offset:1024
	ds_read_b128 v[216:219], v154 offset:2048
	ds_read_b128 v[220:223], v154 offset:3072
	s_waitcnt lgkmcnt(0)
	s_waitcnt vmcnt(8)
	s_barrier
	s_setprio 1
	v_mfma_f32_16x16x32_bf16 v[124:127], v[156:159], v[172:175], v[124:127]
	v_mfma_f32_16x16x32_bf16 v[120:123], v[164:167], v[172:175], v[120:123]
	v_mfma_f32_16x16x32_bf16 v[108:111], v[156:159], v[184:187], v[108:111]
	v_mfma_f32_16x16x32_bf16 v[104:107], v[164:167], v[184:187], v[104:107]
	v_mfma_f32_16x16x32_bf16 v[92:95], v[156:159], v[192:195], v[92:95]
	v_mfma_f32_16x16x32_bf16 v[88:91], v[164:167], v[192:195], v[88:91]
	v_mfma_f32_16x16x32_bf16 v[76:79], v[156:159], v[200:203], v[76:79]
	v_mfma_f32_16x16x32_bf16 v[72:75], v[164:167], v[200:203], v[72:75]
	v_mfma_f32_16x16x32_bf16 v[124:127], v[160:163], v[176:179], v[124:127]
	v_mfma_f32_16x16x32_bf16 v[120:123], v[168:171], v[176:179], v[120:123]
	v_mfma_f32_16x16x32_bf16 v[108:111], v[160:163], v[188:191], v[108:111]
	v_mfma_f32_16x16x32_bf16 v[104:107], v[168:171], v[188:191], v[104:107]
	v_mfma_f32_16x16x32_bf16 v[92:95], v[160:163], v[196:199], v[92:95]
	v_mfma_f32_16x16x32_bf16 v[88:91], v[168:171], v[196:199], v[88:91]
	v_mfma_f32_16x16x32_bf16 v[76:79], v[160:163], v[204:207], v[76:79]
	v_mfma_f32_16x16x32_bf16 v[72:75], v[168:171], v[204:207], v[72:75]
	v_mfma_f32_16x16x32_bf16 v[116:119], v[208:211], v[172:175], v[116:119]
	v_mfma_f32_16x16x32_bf16 v[112:115], v[216:219], v[172:175], v[112:115]
	v_mfma_f32_16x16x32_bf16 v[100:103], v[208:211], v[184:187], v[100:103]
	v_mfma_f32_16x16x32_bf16 v[96:99], v[216:219], v[184:187], v[96:99]
	v_mfma_f32_16x16x32_bf16 v[84:87], v[208:211], v[192:195], v[84:87]
	v_mfma_f32_16x16x32_bf16 v[80:83], v[216:219], v[192:195], v[80:83]
	v_mfma_f32_16x16x32_bf16 v[68:71], v[208:211], v[200:203], v[68:71]
	v_mfma_f32_16x16x32_bf16 v[64:67], v[216:219], v[200:203], v[64:67]
	v_mfma_f32_16x16x32_bf16 v[116:119], v[212:215], v[176:179], v[116:119]
	v_mfma_f32_16x16x32_bf16 v[112:115], v[220:223], v[176:179], v[112:115]
	v_mfma_f32_16x16x32_bf16 v[100:103], v[212:215], v[188:191], v[100:103]
	v_mfma_f32_16x16x32_bf16 v[96:99], v[220:223], v[188:191], v[96:99]
	v_mfma_f32_16x16x32_bf16 v[84:87], v[212:215], v[196:199], v[84:87]
	v_mfma_f32_16x16x32_bf16 v[80:83], v[220:223], v[196:199], v[80:83]
	v_mfma_f32_16x16x32_bf16 v[68:71], v[212:215], v[204:207], v[68:71]
	v_mfma_f32_16x16x32_bf16 v[64:67], v[220:223], v[204:207], v[64:67]
	s_setprio 0
	s_barrier
	s_add_i32 s61, s54, s39
	v_lshl_add_u64 v[142:143], s[30:31], 0, v[130:131]
	s_mov_b32 m0, s61
	s_nop 0
	global_load_lds_dwordx4 v[142:143], off
	v_lshl_add_u64 v[142:143], s[30:31], 0, v[128:129]
	s_add_i32 m0, s61, 0x2000
	s_nop 0
	global_load_lds_dwordx4 v[142:143], off
	s_mov_b32 m0, s42
	v_lshl_add_u64 v[142:143], s[36:37], 0, v[130:131]
	ds_read_b128 v[172:175], v153 offset:16384
	ds_read_b128 v[176:179], v153 offset:17408
	ds_read_b128 v[184:187], v153 offset:18432
	ds_read_b128 v[188:191], v153 offset:19456
	ds_read_b128 v[192:195], v153 offset:20480
	ds_read_b128 v[196:199], v153 offset:21504
	ds_read_b128 v[200:203], v153 offset:22528
	ds_read_b128 v[204:207], v153 offset:23552
	global_load_lds_dwordx4 v[142:143], off
	v_lshl_add_u64 v[142:143], s[36:37], 0, v[128:129]
	s_mov_b32 m0, s43
	s_nop 0
	global_load_lds_dwordx4 v[142:143], off
	s_add_u32 s94, s30, 0x4000
	s_addc_u32 s95, s31, 0
	s_add_i32 s61, s55, s39
	v_lshl_add_u64 v[142:143], s[94:95], 0, v[130:131]
	s_mov_b32 m0, s61
	s_nop 0
	global_load_lds_dwordx4 v[142:143], off
	v_lshl_add_u64 v[142:143], s[94:95], 0, v[128:129]
	s_add_i32 m0, s61, 0x2000
	s_nop 0
	global_load_lds_dwordx4 v[142:143], off
	s_waitcnt lgkmcnt(0)
	s_waitcnt vmcnt(8)
	s_barrier
; #define PG8_STAGE(bufoff, gbase, voff) do { _Pragma("unroll") for (int _i = 0; _i < 2; ++_i) \
;         __builtin_amdgcn_global_load_lds((const unsigned*)((const char*)(gbase) + (voff)[_i]), (LAS unsigned*)(lds + (bufoff) + ldsw + _i * 8192), 16, 0, 0); } while (0)
; #define PG8_LDA(dst, b, h) do { _Pragma("unroll") for (int m = 0; m < 4; ++m) _Pragma("unroll") for (int k = 0; k < 2; ++k) dst[m][k] = *(const LAS bf16x8*)(lds + PG8_SA(b, h) + aoff + m * 2048 + k * 1024); } while (0)
; #define PG8_LDB(dst, b, h) do { _Pragma("unroll") for (int n = 0; n < 2; ++n) _Pragma("unroll") for (int k = 0; k < 2; ++k) dst[n][k] = *(const LAS bf16x8*)(lds + PG8_SB(b, h) + boff + n * 2048 + k * 1024); } while (0)
; #define PG8_MMA(ai, bj, At, Bt) do { __builtin_amdgcn_s_setprio(1); _Pragma("unroll") for (int m = 0; m < 4; ++m) _Pragma("unroll") for (int n = 0; n < 2; ++n) _Pragma("unroll") for (int k = 0; k < 2; ++k) \
;         acc[ai][bj][m][n] = __builtin_amdgcn_mfma_f32_16x16x32_bf16(Bt[n][k], At[m][k], acc[ai][bj][m][n], 0, 0, 0); __builtin_amdgcn_s_setprio(0); } while (0)
; #define PG8_WAIT_V(n) asm volatile("s_waitcnt vmcnt(" #n ")" ::: "memory")
; #define PG8_WAIT_L(n) asm volatile("s_waitcnt lgkmcnt(" #n ")" ::: "memory")
; #define PG8_BAR __builtin_amdgcn_s_barrier()
; #define PG8_SCHED __builtin_amdgcn_sched_barrier(0)
; template <class Epi>
; __device__ __forceinline__ void gemm_phase(LAS unsigned char* lds, const Gemm g, const StaticOrder& S, const Epi& E) {
;     ...
;             PG8_BAR; PG8_WAIT_L(0); PG8_MMA(1, 0, At, B0); PG8_BAR; PG8_SCHED;
;             PG8_STAGE(PG8_SB(0, 1), b2 + hstep, voffB);
;             PG8_WAIT_V(6); PG8_BAR; PG8_MMA(1, 1, At, B1); PG8_BAR;
;             PG8_LDB(B0, 1, 0); PG8_SCHED; PG8_LDA(At, 1, 0); PG8_STAGE(PG8_SA(0, 1), a2 + hstep, voffA);
;             PG8_WAIT_L(8); PG8_BAR; PG8_WAIT_L(0); PG8_MMA(0, 0, At, B0); PG8_BAR; PG8_SCHED;
;             PG8_LDB(B1, 1, 1); PG8_STAGE(PG8_SB(1, 0), b3, voffB);
;             PG8_BAR; PG8_WAIT_L(0); PG8_MMA(0, 1, At, B1); PG8_BAR;
;             PG8_LDA(At, 1, 1); PG8_STAGE(PG8_SA(1, 0), a3, voffA);
;             PG8_BAR; PG8_WAIT_L(0); PG8_MMA(1, 0, At, B0); PG8_BAR; PG8_SCHED;
	s_setprio 1
	v_mfma_f32_16x16x32_bf16 v[60:63], v[156:159], v[172:175], v[60:63]
	v_mfma_f32_16x16x32_bf16 v[56:59], v[164:167], v[172:175], v[56:59]
	v_mfma_f32_16x16x32_bf16 v[44:47], v[156:159], v[184:187], v[44:47]
	v_mfma_f32_16x16x32_bf16 v[40:43], v[164:167], v[184:187], v[40:43]
	v_mfma_f32_16x16x32_bf16 v[28:31], v[156:159], v[192:195], v[28:31]
	v_mfma_f32_16x16x32_bf16 v[24:27], v[164:167], v[192:195], v[24:27]
	v_mfma_f32_16x16x32_bf16 v[12:15], v[156:159], v[200:203], v[12:15]
	v_mfma_f32_16x16x32_bf16 v[8:11], v[164:167], v[200:203], v[8:11]
	v_mfma_f32_16x16x32_bf16 v[60:63], v[160:163], v[176:179], v[60:63]
	v_mfma_f32_16x16x32_bf16 v[56:59], v[168:171], v[176:179], v[56:59]
	v_mfma_f32_16x16x32_bf16 v[44:47], v[160:163], v[188:191], v[44:47]
	v_mfma_f32_16x16x32_bf16 v[40:43], v[168:171], v[188:191], v[40:43]
	v_mfma_f32_16x16x32_bf16 v[28:31], v[160:163], v[196:199], v[28:31]
	v_mfma_f32_16x16x32_bf16 v[24:27], v[168:171], v[196:199], v[24:27]
	v_mfma_f32_16x16x32_bf16 v[12:15], v[160:163], v[204:207], v[12:15]
	v_mfma_f32_16x16x32_bf16 v[8:11], v[168:171], v[204:207], v[8:11]
	v_mfma_f32_16x16x32_bf16 v[52:55], v[208:211], v[172:175], v[52:55]
	v_mfma_f32_16x16x32_bf16 v[48:51], v[216:219], v[172:175], v[48:51]
	v_mfma_f32_16x16x32_bf16 v[36:39], v[208:211], v[184:187], v[36:39]
	v_mfma_f32_16x16x32_bf16 v[32:35], v[216:219], v[184:187], v[32:35]
	v_mfma_f32_16x16x32_bf16 v[20:23], v[208:211], v[192:195], v[20:23]
	v_mfma_f32_16x16x32_bf16 v[16:19], v[216:219], v[192:195], v[16:19]
	v_mfma_f32_16x16x32_bf16 v[4:7], v[208:211], v[200:203], v[4:7]
	v_mfma_f32_16x16x32_bf16 v[0:3], v[216:219], v[200:203], v[0:3]
	v_mfma_f32_16x16x32_bf16 v[52:55], v[212:215], v[176:179], v[52:55]
	v_mfma_f32_16x16x32_bf16 v[48:51], v[220:223], v[176:179], v[48:51]
	v_mfma_f32_16x16x32_bf16 v[36:39], v[212:215], v[188:191], v[36:39]
	v_mfma_f32_16x16x32_bf16 v[32:35], v[220:223], v[188:191], v[32:35]
	v_mfma_f32_16x16x32_bf16 v[20:23], v[212:215], v[196:199], v[20:23]
	v_mfma_f32_16x16x32_bf16 v[16:19], v[220:223], v[196:199], v[16:19]
	v_mfma_f32_16x16x32_bf16 v[4:7], v[212:215], v[204:207], v[4:7]
	v_mfma_f32_16x16x32_bf16 v[0:3], v[220:223], v[204:207], v[0:3]
	s_setprio 0
	s_add_i32 s61, 0, 0x18000
	v_add_u32_e32 v142, s61, v151
	s_barrier
	ds_read_b128 v[156:159], v142
	ds_read_b128 v[160:163], v142 offset:1024
	ds_read_b128 v[164:167], v142 offset:2048
	ds_read_b128 v[168:171], v142 offset:3072
	s_add_u32 s36, s36, 0x4000
	s_addc_u32 s37, s37, 0
	s_mov_b32 m0, s44
	v_lshl_add_u64 v[142:143], s[36:37], 0, v[130:131]
	ds_read_b128 v[172:175], v153 offset:32768
	ds_read_b128 v[176:179], v153 offset:33792
	ds_read_b128 v[184:187], v153 offset:34816
	ds_read_b128 v[188:191], v153 offset:35840
	ds_read_b128 v[192:195], v153 offset:36864
	ds_read_b128 v[196:199], v153 offset:37888
	ds_read_b128 v[200:203], v153 offset:38912
	ds_read_b128 v[204:207], v153 offset:39936
	global_load_lds_dwordx4 v[142:143], off
	v_lshl_add_u64 v[142:143], s[36:37], 0, v[128:129]
	s_mov_b32 m0, s45
	s_nop 0
	global_load_lds_dwordx4 v[142:143], off
	v_add_u32_e32 v253, 0x1c000, v151
	ds_read_b128 v[208:211], v253
	ds_read_b128 v[212:215], v253 offset:1024
	ds_read_b128 v[216:219], v253 offset:2048
	ds_read_b128 v[220:223], v253 offset:3072
	s_waitcnt lgkmcnt(0)
	s_waitcnt vmcnt(8)
	s_barrier
	s_setprio 1
	v_mfma_f32_16x16x32_bf16 v[124:127], v[156:159], v[172:175], v[124:127]
	v_mfma_f32_16x16x32_bf16 v[120:123], v[164:167], v[172:175], v[120:123]
	v_mfma_f32_16x16x32_bf16 v[108:111], v[156:159], v[184:187], v[108:111]
	v_mfma_f32_16x16x32_bf16 v[104:107], v[164:167], v[184:187], v[104:107]
	v_mfma_f32_16x16x32_bf16 v[92:95], v[156:159], v[192:195], v[92:95]
	v_mfma_f32_16x16x32_bf16 v[88:91], v[164:167], v[192:195], v[88:91]
	v_mfma_f32_16x16x32_bf16 v[76:79], v[156:159], v[200:203], v[76:79]
	v_mfma_f32_16x16x32_bf16 v[72:75], v[164:167], v[200:203], v[72:75]
	v_mfma_f32_16x16x32_bf16 v[124:127], v[160:163], v[176:179], v[124:127]
	v_mfma_f32_16x16x32_bf16 v[120:123], v[168:171], v[176:179], v[120:123]
	v_mfma_f32_16x16x32_bf16 v[108:111], v[160:163], v[188:191], v[108:111]
	v_mfma_f32_16x16x32_bf16 v[104:107], v[168:171], v[188:191], v[104:107]
	v_mfma_f32_16x16x32_bf16 v[92:95], v[160:163], v[196:199], v[92:95]
	v_mfma_f32_16x16x32_bf16 v[88:91], v[168:171], v[196:199], v[88:91]
	v_mfma_f32_16x16x32_bf16 v[76:79], v[160:163], v[204:207], v[76:79]
	v_mfma_f32_16x16x32_bf16 v[72:75], v[168:171], v[204:207], v[72:75]
	v_mfma_f32_16x16x32_bf16 v[116:119], v[208:211], v[172:175], v[116:119]
	v_mfma_f32_16x16x32_bf16 v[112:115], v[216:219], v[172:175], v[112:115]
	v_mfma_f32_16x16x32_bf16 v[100:103], v[208:211], v[184:187], v[100:103]
	v_mfma_f32_16x16x32_bf16 v[96:99], v[216:219], v[184:187], v[96:99]
	v_mfma_f32_16x16x32_bf16 v[84:87], v[208:211], v[192:195], v[84:87]
	v_mfma_f32_16x16x32_bf16 v[80:83], v[216:219], v[192:195], v[80:83]
	v_mfma_f32_16x16x32_bf16 v[68:71], v[208:211], v[200:203], v[68:71]
	v_mfma_f32_16x16x32_bf16 v[64:67], v[216:219], v[200:203], v[64:67]
	v_mfma_f32_16x16x32_bf16 v[116:119], v[212:215], v[176:179], v[116:119]
	v_mfma_f32_16x16x32_bf16 v[112:115], v[220:223], v[176:179], v[112:115]
	v_mfma_f32_16x16x32_bf16 v[100:103], v[212:215], v[188:191], v[100:103]
	v_mfma_f32_16x16x32_bf16 v[96:99], v[220:223], v[188:191], v[96:99]
	v_mfma_f32_16x16x32_bf16 v[84:87], v[212:215], v[196:199], v[84:87]
	v_mfma_f32_16x16x32_bf16 v[80:83], v[220:223], v[196:199], v[80:83]
	v_mfma_f32_16x16x32_bf16 v[68:71], v[212:215], v[204:207], v[68:71]
	v_mfma_f32_16x16x32_bf16 v[64:67], v[220:223], v[204:207], v[64:67]
	s_setprio 0
	s_barrier
; __device__ __forceinline__ unsigned pk_bf16(float lo, float hi) { unsigned r; asm("v_cvt_pk_bf16_f32 %0, %1, %2" : "=v"(r) : "v"(lo), "v"(hi)); return r; }
; __device__ __forceinline__ size_t blk_off(int row, int col, int nrows) { return ((size_t)(col >> 6) * nrows + row) * 64 + (col & 63); }
; __device__ __forceinline__ float sigmoidf_fast(float v) { return __builtin_amdgcn_rcpf(1.0f + __expf(-v)); }
; #define PG8_STAGE(bufoff, gbase, voff) do { _Pragma("unroll") for (int _i = 0; _i < 2; ++_i) \
;         __builtin_amdgcn_global_load_lds((const unsigned*)((const char*)(gbase) + (voff)[_i]), (LAS unsigned*)(lds + (bufoff) + ldsw + _i * 8192), 16, 0, 0); } while (0)
; #define PG8_LDA(dst, b, h) do { _Pragma("unroll") for (int m = 0; m < 4; ++m) _Pragma("unroll") for (int k = 0; k < 2; ++k) dst[m][k] = *(const LAS bf16x8*)(lds + PG8_SA(b, h) + aoff + m * 2048 + k * 1024); } while (0)
; #define PG8_BAR __builtin_amdgcn_s_barrier()
;     __device__ __forceinline__ void operator()(const f32x4 (&acc)[2][2][4][2], const Unit& u, int wr, int wc, int fr, int fq) const {
;         const int row0 = u.pm * BM + wr * 64 + fr; const int col0 = u.pn * HALF + wc * 32 + 8 * fq;
; #pragma unroll
;         for (int ai = 0; ai < 2; ++ai)
; #pragma unroll
;             for (int m = 0; m < 4; ++m) { bf16_t* rowp = O + blk_off(row0 + ai * HALF + m * 16, col0, nrows);
;                 float v[8];
; #pragma unroll
;                 for (int bj = 0; bj < 2; ++bj)
; #pragma unroll
;                     for (int j = 0; j < 4; ++j) { const float g = acc[ai][bj][m][0][j], up = acc[ai][bj][m][1][j]; v[bj * 4 + j] = g * sigmoidf_fast(g) * up; }
;                 u32x4 w; w.x = pk_bf16(v[0], v[1]); w.y = pk_bf16(v[2], v[3]); w.z = pk_bf16(v[4], v[5]); w.w = pk_bf16(v[6], v[7]);
;                 *(u32x4*)rowp = w; }
; template <class Epi>
; __device__ __forceinline__ void gemm_phase(LAS unsigned char* lds, const Gemm g, const StaticOrder& S, const Epi& E) {
;     ...
;             PG8_LDB(B1, 1, 1); PG8_STAGE(PG8_SB(1, 0), b3, voffB);
;             PG8_BAR; PG8_WAIT_L(0); PG8_MMA(0, 1, At, B1); PG8_BAR;
;             PG8_LDA(At, 1, 1); PG8_STAGE(PG8_SA(1, 0), a3, voffA);
;             PG8_BAR; PG8_WAIT_L(0); PG8_MMA(1, 0, At, B0); PG8_BAR; PG8_SCHED;
;             PG8_STAGE(PG8_SB(1, 1), b3 + hstep, voffB);
;             PG8_WAIT_V(6); PG8_BAR; PG8_MMA(1, 1, At, B1); PG8_BAR;
;         }
	s_add_i32 s63, 0, 0x1c000
	s_add_u32 s36, s30, 0x160000
	v_add_u32_e32 v142, s63, v151
	s_addc_u32 s37, s31, 0
	s_add_i32 s61, s61, s39
	s_nop 0
	v_lshl_add_u64 v[142:143], s[36:37], 0, v[130:131]
	s_mov_b32 m0, s61
	s_nop 0
	global_load_lds_dwordx4 v[142:143], off
	v_lshl_add_u64 v[142:143], s[36:37], 0, v[128:129]
	s_add_i32 m0, s61, 0x2000
	s_nop 0
	global_load_lds_dwordx4 v[142:143], off
	s_mov_b32 m0, s50
	v_lshl_add_u64 v[142:143], s[34:35], 0, v[130:131]
	ds_read_b128 v[172:175], v153 offset:49152
	ds_read_b128 v[176:179], v153 offset:50176
	ds_read_b128 v[184:187], v153 offset:51200
	ds_read_b128 v[188:191], v153 offset:52224
	ds_read_b128 v[192:195], v153 offset:53248
	ds_read_b128 v[196:199], v153 offset:54272
	ds_read_b128 v[200:203], v153 offset:55296
	ds_read_b128 v[204:207], v153 offset:56320
	global_load_lds_dwordx4 v[142:143], off
	v_lshl_add_u64 v[142:143], s[34:35], 0, v[128:129]
	s_mov_b32 m0, s51
	s_nop 0
	global_load_lds_dwordx4 v[142:143], off
	s_add_u32 s30, s30, 0x164000
	s_addc_u32 s31, s31, 0
	s_add_i32 s34, s63, s39
	v_lshl_add_u64 v[142:143], s[30:31], 0, v[130:131]
	s_mov_b32 m0, s34
	s_nop 0
	global_load_lds_dwordx4 v[142:143], off
	v_lshl_add_u64 v[142:143], s[30:31], 0, v[128:129]
	s_add_i32 m0, s34, 0x2000
	s_nop 0
	global_load_lds_dwordx4 v[142:143], off
	s_waitcnt lgkmcnt(0)
	s_waitcnt vmcnt(8)
	s_barrier
	s_setprio 1
	v_mfma_f32_16x16x32_bf16 v[60:63], v[156:159], v[172:175], v[60:63]
	v_mfma_f32_16x16x32_bf16 v[56:59], v[164:167], v[172:175], v[56:59]
	v_mfma_f32_16x16x32_bf16 v[44:47], v[156:159], v[184:187], v[44:47]
	v_mfma_f32_16x16x32_bf16 v[40:43], v[164:167], v[184:187], v[40:43]
	v_mfma_f32_16x16x32_bf16 v[28:31], v[156:159], v[192:195], v[28:31]
	v_mfma_f32_16x16x32_bf16 v[24:27], v[164:167], v[192:195], v[24:27]
	v_mfma_f32_16x16x32_bf16 v[12:15], v[156:159], v[200:203], v[12:15]
	v_mfma_f32_16x16x32_bf16 v[8:11], v[164:167], v[200:203], v[8:11]
	v_mfma_f32_16x16x32_bf16 v[60:63], v[160:163], v[176:179], v[60:63]
	v_mfma_f32_16x16x32_bf16 v[56:59], v[168:171], v[176:179], v[56:59]
	v_mfma_f32_16x16x32_bf16 v[44:47], v[160:163], v[188:191], v[44:47]
	v_mfma_f32_16x16x32_bf16 v[40:43], v[168:171], v[188:191], v[40:43]
	v_mfma_f32_16x16x32_bf16 v[28:31], v[160:163], v[196:199], v[28:31]
	v_mfma_f32_16x16x32_bf16 v[24:27], v[168:171], v[196:199], v[24:27]
	v_mfma_f32_16x16x32_bf16 v[12:15], v[160:163], v[204:207], v[12:15]
	v_mfma_f32_16x16x32_bf16 v[8:11], v[168:171], v[204:207], v[8:11]
	v_mfma_f32_16x16x32_bf16 v[52:55], v[208:211], v[172:175], v[52:55]
	v_mfma_f32_16x16x32_bf16 v[48:51], v[216:219], v[172:175], v[48:51]
	v_mfma_f32_16x16x32_bf16 v[36:39], v[208:211], v[184:187], v[36:39]
	v_mfma_f32_16x16x32_bf16 v[32:35], v[216:219], v[184:187], v[32:35]
	v_mfma_f32_16x16x32_bf16 v[20:23], v[208:211], v[192:195], v[20:23]
	v_mfma_f32_16x16x32_bf16 v[16:19], v[216:219], v[192:195], v[16:19]
	v_mfma_f32_16x16x32_bf16 v[4:7], v[208:211], v[200:203], v[4:7]
	v_mfma_f32_16x16x32_bf16 v[0:3], v[216:219], v[200:203], v[0:3]
	v_mfma_f32_16x16x32_bf16 v[52:55], v[212:215], v[176:179], v[52:55]
	v_mfma_f32_16x16x32_bf16 v[48:51], v[220:223], v[176:179], v[48:51]
	v_mfma_f32_16x16x32_bf16 v[36:39], v[212:215], v[188:191], v[36:39]
	v_mfma_f32_16x16x32_bf16 v[32:35], v[220:223], v[188:191], v[32:35]
	v_mfma_f32_16x16x32_bf16 v[20:23], v[212:215], v[196:199], v[20:23]
	v_mfma_f32_16x16x32_bf16 v[16:19], v[220:223], v[196:199], v[16:19]
	v_mfma_f32_16x16x32_bf16 v[4:7], v[212:215], v[204:207], v[4:7]
	v_mfma_f32_16x16x32_bf16 v[0:3], v[220:223], v[204:207], v[0:3]
	s_setprio 0
	s_add_i32 s60, s60, 2
	s_add_u32 s58, s58, 0x2c0000
	s_addc_u32 s59, s59, 0
	s_add_u32 s28, s28, 0x800000
	s_addc_u32 s29, s29, 0
	s_cmp_gt_u32 s60, 29
	s_barrier
	s_cbranch_scc0 .LBB0_210
	s_lshl_b32 s5, s13, 7
	v_mul_f32_e32 v155, 0xbfb8aa3b, v124
	s_or_b32 s5, s5, s49
	v_exp_f32_e32 v155, v155
	v_mul_f32_e32 v156, 0xbfb8aa3b, v125
	v_lshl_add_u32 v142, s12, 8, v150
	s_ashr_i32 s12, s5, 6
	v_exp_f32_e32 v158, v156
	s_ashr_i32 s13, s12, 31
	s_lshl_b64 s[12:13], s[12:13], 15
	v_ashrrev_i32_e32 v143, 31, v142
	v_lshl_add_u64 v[156:157], s[12:13], 0, v[142:143]
	v_add_f32_e32 v143, 1.0, v155
	v_rcp_f32_e32 v143, v143
	v_add_f32_e32 v155, 1.0, v158
	v_rcp_f32_e32 v155, v155
	v_lshlrev_b64 v[156:157], 7, v[156:157]
	v_mul_f32_e32 v124, v124, v143
	v_mul_f32_e32 v120, v120, v124
	v_mul_f32_e32 v124, v125, v155
	v_mul_f32_e32 v125, 0xbfb8aa3b, v126
	v_exp_f32_e32 v125, v125
	v_mul_f32_e32 v143, 0xbfb8aa3b, v127
	v_exp_f32_e32 v143, v143
	v_mul_f32_e32 v121, v121, v124
	v_add_f32_e32 v124, 1.0, v125
	v_rcp_f32_e32 v124, v124
	v_add_f32_e32 v125, 1.0, v143
	v_mul_f32_e32 v143, 0xbfb8aa3b, v116
	v_rcp_f32_e32 v125, v125
	v_exp_f32_e32 v143, v143
	v_mul_f32_e32 v124, v126, v124
	v_mul_f32_e32 v122, v122, v124
	v_mul_f32_e32 v124, v127, v125
	v_add_f32_e32 v125, 1.0, v143
	v_rcp_f32_e32 v125, v125
	v_mul_f32_e32 v126, 0xbfb8aa3b, v117
	v_exp_f32_e32 v126, v126
	v_mul_f32_e32 v123, v123, v124
	v_mul_f32_e32 v116, v116, v125
	v_mul_f32_e32 v124, v112, v116
	v_mul_f32_e32 v116, 0xbfb8aa3b, v118
	v_add_f32_e32 v112, 1.0, v126
	v_exp_f32_e32 v116, v116
	v_mul_f32_e32 v125, 0xbfb8aa3b, v119
	v_rcp_f32_e32 v112, v112
	v_exp_f32_e32 v125, v125
	v_add_f32_e32 v116, 1.0, v116
	v_rcp_f32_e32 v116, v116
	v_mul_f32_e32 v112, v117, v112
	v_add_f32_e32 v117, 1.0, v125
	v_rcp_f32_e32 v117, v117
	v_mul_f32_e32 v125, v113, v112
	v_mul_f32_e32 v112, v118, v116
	v_mul_f32_e32 v118, v114, v112
	v_mul_f32_e32 v112, v119, v117
	v_mul_f32_e32 v115, v115, v112
	v_lshl_add_u64 v[116:117], v[132:133], 0, v[156:157]
	v_cvt_pk_bf16_f32 v114, v124, v125
; __device__ __forceinline__ unsigned pk_bf16(float lo, float hi) { unsigned r; asm("v_cvt_pk_bf16_f32 %0, %1, %2" : "=v"(r) : "v"(lo), "v"(hi)); return r; }
; __device__ __forceinline__ size_t blk_off(int row, int col, int nrows) { return ((size_t)(col >> 6) * nrows + row) * 64 + (col & 63); }
; __device__ __forceinline__ float sigmoidf_fast(float v) { return __builtin_amdgcn_rcpf(1.0f + __expf(-v)); }
;     __device__ __forceinline__ void operator()(const f32x4 (&acc)[2][2][4][2], const Unit& u, int wr, int wc, int fr, int fq) const {
;         const int row0 = u.pm * BM + wr * 64 + fr; const int col0 = u.pn * HALF + wc * 32 + 8 * fq;
; #pragma unroll
;         for (int ai = 0; ai < 2; ++ai)
; #pragma unroll
;             for (int m = 0; m < 4; ++m) { bf16_t* rowp = O + blk_off(row0 + ai * HALF + m * 16, col0, nrows);
;                 float v[8];
; #pragma unroll
;                 for (int bj = 0; bj < 2; ++bj)
; #pragma unroll
;                     for (int j = 0; j < 4; ++j) { const float g = acc[ai][bj][m][0][j], up = acc[ai][bj][m][1][j]; v[bj * 4 + j] = g * sigmoidf_fast(g) * up; }
;                 u32x4 w; w.x = pk_bf16(v[0], v[1]); w.y = pk_bf16(v[2], v[3]); w.z = pk_bf16(v[4], v[5]); w.w = pk_bf16(v[6], v[7]);
;                 *(u32x4*)rowp = w; }
	v_cvt_pk_bf16_f32 v112, v120, v121
	v_cvt_pk_bf16_f32 v113, v122, v123
	v_cvt_pk_bf16_f32 v115, v118, v115
	global_store_dwordx4 v[116:117], v[112:115], off
	s_and_b64 vcc, exec, s[0:1]
	s_mov_b64 s[28:29], s[10:11]
	v_mul_f32_e32 v114, 0xbfb8aa3b, v108
	v_exp_f32_e32 v114, v114
	v_mul_f32_e32 v115, 0xbfb8aa3b, v109
	v_exp_f32_e32 v115, v115
	v_or_b32_e32 v112, 16, v142
	v_add_f32_e32 v114, 1.0, v114
	v_rcp_f32_e32 v114, v114
	v_add_f32_e32 v115, 1.0, v115
	v_rcp_f32_e32 v115, v115
	v_ashrrev_i32_e32 v113, 31, v112
	v_mul_f32_e32 v108, v108, v114
	v_mul_f32_e32 v104, v104, v108
	v_mul_f32_e32 v108, v109, v115
	v_mul_f32_e32 v109, 0xbfb8aa3b, v110
	v_exp_f32_e32 v109, v109
	v_mul_f32_e32 v114, 0xbfb8aa3b, v111
	v_exp_f32_e32 v114, v114
	v_mul_f32_e32 v105, v105, v108
	v_add_f32_e32 v108, 1.0, v109
	v_rcp_f32_e32 v108, v108
	v_add_f32_e32 v109, 1.0, v114
	v_mul_f32_e32 v114, 0xbfb8aa3b, v100
	v_rcp_f32_e32 v109, v109
	v_exp_f32_e32 v114, v114
	v_mul_f32_e32 v108, v110, v108
	v_mul_f32_e32 v106, v106, v108
	v_mul_f32_e32 v108, v111, v109
	v_add_f32_e32 v109, 1.0, v114
	v_rcp_f32_e32 v109, v109
	v_mul_f32_e32 v110, 0xbfb8aa3b, v101
	v_exp_f32_e32 v110, v110
	v_mul_f32_e32 v107, v107, v108
	v_mul_f32_e32 v100, v100, v109
	v_mul_f32_e32 v108, v96, v100
	v_mul_f32_e32 v100, 0xbfb8aa3b, v102
	v_add_f32_e32 v96, 1.0, v110
	v_exp_f32_e32 v100, v100
	v_mul_f32_e32 v109, 0xbfb8aa3b, v103
	v_rcp_f32_e32 v96, v96
	v_exp_f32_e32 v109, v109
	v_add_f32_e32 v100, 1.0, v100
	v_rcp_f32_e32 v100, v100
	v_mul_f32_e32 v96, v101, v96
	v_add_f32_e32 v101, 1.0, v109
	v_rcp_f32_e32 v101, v101
	v_lshl_add_u64 v[112:113], s[12:13], 0, v[112:113]
	v_mul_f32_e32 v109, v97, v96
	v_mul_f32_e32 v96, v102, v100
	v_lshlrev_b64 v[112:113], 7, v[112:113]
	v_mul_f32_e32 v102, v98, v96
	v_mul_f32_e32 v96, v103, v101
	v_mul_f32_e32 v99, v99, v96
	v_lshl_add_u64 v[100:101], v[132:133], 0, v[112:113]
	v_cvt_pk_bf16_f32 v98, v108, v109
	v_cvt_pk_bf16_f32 v96, v104, v105
	v_cvt_pk_bf16_f32 v97, v106, v107
	v_cvt_pk_bf16_f32 v99, v102, v99
	global_store_dwordx4 v[100:101], v[96:99], off
	s_mov_b64 s[30:31], s[8:9]
	s_nop 0
	v_mul_f32_e32 v98, 0xbfb8aa3b, v92
	v_exp_f32_e32 v98, v98
	v_mul_f32_e32 v99, 0xbfb8aa3b, v93
	v_exp_f32_e32 v99, v99
	v_or_b32_e32 v96, 32, v142
	v_add_f32_e32 v98, 1.0, v98
	v_rcp_f32_e32 v98, v98
	v_add_f32_e32 v99, 1.0, v99
	v_rcp_f32_e32 v99, v99
	v_ashrrev_i32_e32 v97, 31, v96
	v_mul_f32_e32 v92, v92, v98
	v_mul_f32_e32 v88, v88, v92
	v_mul_f32_e32 v92, v93, v99
	v_mul_f32_e32 v93, 0xbfb8aa3b, v94
	v_exp_f32_e32 v93, v93
	v_mul_f32_e32 v98, 0xbfb8aa3b, v95
	v_exp_f32_e32 v98, v98
	v_mul_f32_e32 v89, v89, v92
	v_add_f32_e32 v92, 1.0, v93
	v_rcp_f32_e32 v92, v92
	v_add_f32_e32 v93, 1.0, v98
	v_mul_f32_e32 v98, 0xbfb8aa3b, v84
	v_rcp_f32_e32 v93, v93
	v_exp_f32_e32 v98, v98
	v_mul_f32_e32 v92, v94, v92
	v_mul_f32_e32 v90, v90, v92
	v_mul_f32_e32 v92, v95, v93
	v_add_f32_e32 v93, 1.0, v98
	v_rcp_f32_e32 v93, v93
	v_mul_f32_e32 v94, 0xbfb8aa3b, v85
	v_exp_f32_e32 v94, v94
	v_mul_f32_e32 v91, v91, v92
	v_mul_f32_e32 v84, v84, v93
	v_mul_f32_e32 v92, v80, v84
	v_mul_f32_e32 v84, 0xbfb8aa3b, v86
	v_add_f32_e32 v80, 1.0, v94
	v_exp_f32_e32 v84, v84
	v_mul_f32_e32 v93, 0xbfb8aa3b, v87
	v_rcp_f32_e32 v80, v80
	v_exp_f32_e32 v93, v93
	v_add_f32_e32 v84, 1.0, v84
	v_rcp_f32_e32 v84, v84
	v_mul_f32_e32 v80, v85, v80
	v_add_f32_e32 v85, 1.0, v93
	v_rcp_f32_e32 v85, v85
	v_lshl_add_u64 v[96:97], s[12:13], 0, v[96:97]
	v_mul_f32_e32 v93, v81, v80
	v_mul_f32_e32 v80, v86, v84
	v_lshlrev_b64 v[96:97], 7, v[96:97]
	v_mul_f32_e32 v86, v82, v80
	v_mul_f32_e32 v80, v87, v85
	v_mul_f32_e32 v83, v83, v80
	v_lshl_add_u64 v[84:85], v[132:133], 0, v[96:97]
	v_cvt_pk_bf16_f32 v82, v92, v93
	v_cvt_pk_bf16_f32 v80, v88, v89
	v_cvt_pk_bf16_f32 v81, v90, v91
	v_cvt_pk_bf16_f32 v83, v86, v83
	global_store_dwordx4 v[84:85], v[80:83], off
	s_nop 1
	v_mul_f32_e32 v82, 0xbfb8aa3b, v76
	v_exp_f32_e32 v82, v82
	v_mul_f32_e32 v83, 0xbfb8aa3b, v77
	v_exp_f32_e32 v83, v83
	v_or_b32_e32 v80, 48, v142
	v_add_f32_e32 v82, 1.0, v82
	v_rcp_f32_e32 v82, v82
	v_add_f32_e32 v83, 1.0, v83
	v_rcp_f32_e32 v83, v83
	v_ashrrev_i32_e32 v81, 31, v80
	v_mul_f32_e32 v76, v76, v82
	v_mul_f32_e32 v72, v72, v76
	v_mul_f32_e32 v76, v77, v83
	v_mul_f32_e32 v77, 0xbfb8aa3b, v78
	v_exp_f32_e32 v77, v77
	v_mul_f32_e32 v82, 0xbfb8aa3b, v79
	v_exp_f32_e32 v82, v82
	v_mul_f32_e32 v73, v73, v76
	v_add_f32_e32 v76, 1.0, v77
	v_rcp_f32_e32 v76, v76
	v_add_f32_e32 v77, 1.0, v82
	v_mul_f32_e32 v82, 0xbfb8aa3b, v68
	v_rcp_f32_e32 v77, v77
	v_exp_f32_e32 v82, v82
	v_mul_f32_e32 v76, v78, v76
	v_mul_f32_e32 v74, v74, v76
	v_mul_f32_e32 v76, v79, v77
	v_add_f32_e32 v77, 1.0, v82
	v_rcp_f32_e32 v77, v77
	v_mul_f32_e32 v78, 0xbfb8aa3b, v69
	v_exp_f32_e32 v78, v78
	v_mul_f32_e32 v75, v75, v76
	v_mul_f32_e32 v68, v68, v77
	v_mul_f32_e32 v76, v64, v68
	v_mul_f32_e32 v68, 0xbfb8aa3b, v70
	v_add_f32_e32 v64, 1.0, v78
	v_exp_f32_e32 v68, v68
	v_mul_f32_e32 v77, 0xbfb8aa3b, v71
	v_rcp_f32_e32 v64, v64
	v_exp_f32_e32 v77, v77
	v_add_f32_e32 v68, 1.0, v68
	v_rcp_f32_e32 v68, v68
	v_mul_f32_e32 v64, v69, v64
	v_add_f32_e32 v69, 1.0, v77
	v_rcp_f32_e32 v69, v69
	v_lshl_add_u64 v[80:81], s[12:13], 0, v[80:81]
	v_mul_f32_e32 v77, v65, v64
	v_mul_f32_e32 v64, v70, v68
	v_lshlrev_b64 v[80:81], 7, v[80:81]
	v_mul_f32_e32 v70, v66, v64
	v_mul_f32_e32 v64, v71, v69
	v_mul_f32_e32 v67, v67, v64
	v_lshl_add_u64 v[68:69], v[132:133], 0, v[80:81]
	v_cvt_pk_bf16_f32 v66, v76, v77
	v_cvt_pk_bf16_f32 v64, v72, v73
	v_cvt_pk_bf16_f32 v65, v74, v75
	v_cvt_pk_bf16_f32 v67, v70, v67
	global_store_dwordx4 v[68:69], v[64:67], off
	s_nop 1
	v_mul_f32_e32 v66, 0xbfb8aa3b, v60
; __device__ __forceinline__ unsigned pk_bf16(float lo, float hi) { unsigned r; asm("v_cvt_pk_bf16_f32 %0, %1, %2" : "=v"(r) : "v"(lo), "v"(hi)); return r; }
; __device__ __forceinline__ size_t blk_off(int row, int col, int nrows) { return ((size_t)(col >> 6) * nrows + row) * 64 + (col & 63); }
; __device__ __forceinline__ float sigmoidf_fast(float v) { return __builtin_amdgcn_rcpf(1.0f + __expf(-v)); }
;     __device__ __forceinline__ void operator()(const f32x4 (&acc)[2][2][4][2], const Unit& u, int wr, int wc, int fr, int fq) const {
;         const int row0 = u.pm * BM + wr * 64 + fr; const int col0 = u.pn * HALF + wc * 32 + 8 * fq;
; #pragma unroll
;         for (int ai = 0; ai < 2; ++ai)
; #pragma unroll
;             for (int m = 0; m < 4; ++m) { bf16_t* rowp = O + blk_off(row0 + ai * HALF + m * 16, col0, nrows);
;                 float v[8];
; #pragma unroll
;                 for (int bj = 0; bj < 2; ++bj)
; #pragma unroll
;                     for (int j = 0; j < 4; ++j) { const float g = acc[ai][bj][m][0][j], up = acc[ai][bj][m][1][j]; v[bj * 4 + j] = g * sigmoidf_fast(g) * up; }
;                 u32x4 w; w.x = pk_bf16(v[0], v[1]); w.y = pk_bf16(v[2], v[3]); w.z = pk_bf16(v[4], v[5]); w.w = pk_bf16(v[6], v[7]);
;                 *(u32x4*)rowp = w; }
	v_exp_f32_e32 v66, v66
	v_mul_f32_e32 v67, 0xbfb8aa3b, v61
	v_exp_f32_e32 v67, v67
	v_add_u32_e32 v64, 0x80, v142
	v_add_f32_e32 v66, 1.0, v66
	v_rcp_f32_e32 v66, v66
	v_add_f32_e32 v67, 1.0, v67
	v_rcp_f32_e32 v67, v67
	v_ashrrev_i32_e32 v65, 31, v64
	v_mul_f32_e32 v60, v60, v66
	v_mul_f32_e32 v56, v56, v60
	v_mul_f32_e32 v60, v61, v67
	v_mul_f32_e32 v61, 0xbfb8aa3b, v62
	v_exp_f32_e32 v61, v61
	v_mul_f32_e32 v66, 0xbfb8aa3b, v63
	v_exp_f32_e32 v66, v66
	v_mul_f32_e32 v57, v57, v60
	v_add_f32_e32 v60, 1.0, v61
	v_rcp_f32_e32 v60, v60
	v_add_f32_e32 v61, 1.0, v66
	v_mul_f32_e32 v66, 0xbfb8aa3b, v52
	v_rcp_f32_e32 v61, v61
	v_exp_f32_e32 v66, v66
	v_mul_f32_e32 v60, v62, v60
	v_mul_f32_e32 v58, v58, v60
	v_mul_f32_e32 v60, v63, v61
	v_add_f32_e32 v61, 1.0, v66
	v_rcp_f32_e32 v61, v61
	v_mul_f32_e32 v62, 0xbfb8aa3b, v53
	v_exp_f32_e32 v62, v62
	v_mul_f32_e32 v59, v59, v60
	v_mul_f32_e32 v52, v52, v61
	v_mul_f32_e32 v60, v48, v52
	v_mul_f32_e32 v52, 0xbfb8aa3b, v54
	v_add_f32_e32 v48, 1.0, v62
	v_exp_f32_e32 v52, v52
	v_mul_f32_e32 v61, 0xbfb8aa3b, v55
	v_rcp_f32_e32 v48, v48
	v_exp_f32_e32 v61, v61
	v_add_f32_e32 v52, 1.0, v52
	v_rcp_f32_e32 v52, v52
	v_mul_f32_e32 v48, v53, v48
	v_add_f32_e32 v53, 1.0, v61
	v_rcp_f32_e32 v53, v53
	v_lshl_add_u64 v[64:65], s[12:13], 0, v[64:65]
	v_mul_f32_e32 v61, v49, v48
	v_mul_f32_e32 v48, v54, v52
	v_lshlrev_b64 v[64:65], 7, v[64:65]
	v_mul_f32_e32 v54, v50, v48
	v_mul_f32_e32 v48, v55, v53
	v_mul_f32_e32 v51, v51, v48
	v_lshl_add_u64 v[52:53], v[132:133], 0, v[64:65]
	v_cvt_pk_bf16_f32 v50, v60, v61
	v_cvt_pk_bf16_f32 v48, v56, v57
	v_cvt_pk_bf16_f32 v49, v58, v59
	v_cvt_pk_bf16_f32 v51, v54, v51
	global_store_dwordx4 v[52:53], v[48:51], off
	s_nop 1
	v_mul_f32_e32 v50, 0xbfb8aa3b, v44
	v_exp_f32_e32 v50, v50
	v_mul_f32_e32 v51, 0xbfb8aa3b, v45
	v_exp_f32_e32 v51, v51
	v_add_u32_e32 v48, 0x90, v142
	v_add_f32_e32 v50, 1.0, v50
	v_rcp_f32_e32 v50, v50
	v_add_f32_e32 v51, 1.0, v51
	v_rcp_f32_e32 v51, v51
	v_ashrrev_i32_e32 v49, 31, v48
	v_mul_f32_e32 v44, v44, v50
	v_mul_f32_e32 v40, v40, v44
	v_mul_f32_e32 v44, v45, v51
	v_mul_f32_e32 v45, 0xbfb8aa3b, v46
	v_exp_f32_e32 v45, v45
	v_mul_f32_e32 v50, 0xbfb8aa3b, v47
	v_exp_f32_e32 v50, v50
	v_mul_f32_e32 v41, v41, v44
	v_add_f32_e32 v44, 1.0, v45
	v_rcp_f32_e32 v44, v44
	v_add_f32_e32 v45, 1.0, v50
	v_mul_f32_e32 v50, 0xbfb8aa3b, v36
	v_rcp_f32_e32 v45, v45
	v_exp_f32_e32 v50, v50
	v_mul_f32_e32 v44, v46, v44
	v_mul_f32_e32 v42, v42, v44
	v_mul_f32_e32 v44, v47, v45
	v_add_f32_e32 v45, 1.0, v50
	v_rcp_f32_e32 v45, v45
	v_mul_f32_e32 v46, 0xbfb8aa3b, v37
	v_exp_f32_e32 v46, v46
	v_mul_f32_e32 v43, v43, v44
	v_mul_f32_e32 v36, v36, v45
	v_mul_f32_e32 v44, v32, v36
	v_mul_f32_e32 v36, 0xbfb8aa3b, v38
	v_add_f32_e32 v32, 1.0, v46
	v_exp_f32_e32 v36, v36
	v_mul_f32_e32 v45, 0xbfb8aa3b, v39
	v_rcp_f32_e32 v32, v32
	v_exp_f32_e32 v45, v45
	v_add_f32_e32 v36, 1.0, v36
	v_rcp_f32_e32 v36, v36
	v_mul_f32_e32 v32, v37, v32
	v_add_f32_e32 v37, 1.0, v45
	v_rcp_f32_e32 v37, v37
	v_lshl_add_u64 v[48:49], s[12:13], 0, v[48:49]
	v_mul_f32_e32 v45, v33, v32
	v_mul_f32_e32 v32, v38, v36
	v_lshlrev_b64 v[48:49], 7, v[48:49]
	v_mul_f32_e32 v38, v34, v32
	v_mul_f32_e32 v32, v39, v37
	v_mul_f32_e32 v35, v35, v32
	v_lshl_add_u64 v[36:37], v[132:133], 0, v[48:49]
	v_cvt_pk_bf16_f32 v34, v44, v45
	v_cvt_pk_bf16_f32 v32, v40, v41
	v_cvt_pk_bf16_f32 v33, v42, v43
	v_cvt_pk_bf16_f32 v35, v38, v35
	global_store_dwordx4 v[36:37], v[32:35], off
	s_nop 1
	v_mul_f32_e32 v34, 0xbfb8aa3b, v28
	v_exp_f32_e32 v34, v34
	v_mul_f32_e32 v35, 0xbfb8aa3b, v29
	v_exp_f32_e32 v35, v35
	v_add_u32_e32 v32, 0xa0, v142
	v_add_f32_e32 v34, 1.0, v34
	v_rcp_f32_e32 v34, v34
	v_add_f32_e32 v35, 1.0, v35
	v_rcp_f32_e32 v35, v35
	v_ashrrev_i32_e32 v33, 31, v32
	v_mul_f32_e32 v28, v28, v34
	v_mul_f32_e32 v24, v24, v28
	v_mul_f32_e32 v28, v29, v35
	v_mul_f32_e32 v29, 0xbfb8aa3b, v30
	v_exp_f32_e32 v29, v29
	v_mul_f32_e32 v34, 0xbfb8aa3b, v31
	v_exp_f32_e32 v34, v34
	v_mul_f32_e32 v25, v25, v28
	v_add_f32_e32 v28, 1.0, v29
	v_rcp_f32_e32 v28, v28
	v_add_f32_e32 v29, 1.0, v34
	v_mul_f32_e32 v34, 0xbfb8aa3b, v20
	v_rcp_f32_e32 v29, v29
	v_exp_f32_e32 v34, v34
	v_mul_f32_e32 v28, v30, v28
	v_mul_f32_e32 v26, v26, v28
	v_mul_f32_e32 v28, v31, v29
	v_add_f32_e32 v29, 1.0, v34
	v_rcp_f32_e32 v29, v29
	v_mul_f32_e32 v30, 0xbfb8aa3b, v21
	v_exp_f32_e32 v30, v30
	v_mul_f32_e32 v27, v27, v28
	v_mul_f32_e32 v20, v20, v29
	v_mul_f32_e32 v28, v16, v20
	v_mul_f32_e32 v20, 0xbfb8aa3b, v22
	v_add_f32_e32 v16, 1.0, v30
	v_exp_f32_e32 v20, v20
	v_mul_f32_e32 v29, 0xbfb8aa3b, v23
	v_rcp_f32_e32 v16, v16
	v_exp_f32_e32 v29, v29
	v_add_f32_e32 v20, 1.0, v20
	v_rcp_f32_e32 v20, v20
	v_mul_f32_e32 v16, v21, v16
	v_add_f32_e32 v21, 1.0, v29
	v_rcp_f32_e32 v21, v21
	v_lshl_add_u64 v[32:33], s[12:13], 0, v[32:33]
	v_mul_f32_e32 v29, v17, v16
	v_mul_f32_e32 v16, v22, v20
	v_lshlrev_b64 v[32:33], 7, v[32:33]
	v_mul_f32_e32 v22, v18, v16
	v_mul_f32_e32 v16, v23, v21
	v_mul_f32_e32 v19, v19, v16
	v_lshl_add_u64 v[20:21], v[132:133], 0, v[32:33]
	v_cvt_pk_bf16_f32 v18, v28, v29
	v_cvt_pk_bf16_f32 v16, v24, v25
	v_cvt_pk_bf16_f32 v17, v26, v27
	v_cvt_pk_bf16_f32 v19, v22, v19
	global_store_dwordx4 v[20:21], v[16:19], off
	s_nop 1
	v_mul_f32_e32 v18, 0xbfb8aa3b, v12
	v_exp_f32_e32 v18, v18
	v_mul_f32_e32 v19, 0xbfb8aa3b, v13
	v_exp_f32_e32 v19, v19
	v_add_u32_e32 v16, 0xb0, v142
	v_add_f32_e32 v18, 1.0, v18
	v_rcp_f32_e32 v18, v18
	v_add_f32_e32 v19, 1.0, v19
	v_rcp_f32_e32 v19, v19
	v_ashrrev_i32_e32 v17, 31, v16
	v_mul_f32_e32 v12, v12, v18
	v_mul_f32_e32 v8, v8, v12
	v_mul_f32_e32 v12, v13, v19
	v_mul_f32_e32 v13, 0xbfb8aa3b, v14
	v_exp_f32_e32 v13, v13
	v_mul_f32_e32 v18, 0xbfb8aa3b, v15
	v_exp_f32_e32 v18, v18
	v_mul_f32_e32 v9, v9, v12
	v_add_f32_e32 v12, 1.0, v13
	v_rcp_f32_e32 v12, v12
	v_add_f32_e32 v13, 1.0, v18
	v_mul_f32_e32 v18, 0xbfb8aa3b, v4
	v_rcp_f32_e32 v13, v13
	v_exp_f32_e32 v18, v18
	v_mul_f32_e32 v12, v14, v12
	v_mul_f32_e32 v10, v10, v12
	v_mul_f32_e32 v12, v15, v13
	v_add_f32_e32 v13, 1.0, v18
	v_rcp_f32_e32 v13, v13
	v_mul_f32_e32 v14, 0xbfb8aa3b, v5
	v_exp_f32_e32 v14, v14
	v_mul_f32_e32 v11, v11, v12
	v_mul_f32_e32 v4, v4, v13
	v_mul_f32_e32 v12, v0, v4
	v_mul_f32_e32 v4, 0xbfb8aa3b, v6
	v_add_f32_e32 v0, 1.0, v14
	v_exp_f32_e32 v4, v4
	v_mul_f32_e32 v13, 0xbfb8aa3b, v7
	v_rcp_f32_e32 v0, v0
	v_exp_f32_e32 v13, v13
	v_add_f32_e32 v4, 1.0, v4
	v_rcp_f32_e32 v4, v4
	v_mul_f32_e32 v0, v5, v0
	v_add_f32_e32 v5, 1.0, v13
	v_rcp_f32_e32 v5, v5
	v_lshl_add_u64 v[16:17], s[12:13], 0, v[16:17]
	v_mul_f32_e32 v13, v1, v0
	v_mul_f32_e32 v0, v6, v4
	v_lshlrev_b64 v[16:17], 7, v[16:17]
	v_mul_f32_e32 v6, v2, v0
	v_mul_f32_e32 v0, v7, v5
	v_mul_f32_e32 v3, v3, v0
	v_lshl_add_u64 v[4:5], v[132:133], 0, v[16:17]
	s_mov_b32 s13, s4
	s_mov_b32 s12, s6
	v_cvt_pk_bf16_f32 v0, v8, v9
	v_cvt_pk_bf16_f32 v1, v10, v11
	v_cvt_pk_bf16_f32 v2, v12, v13
	v_cvt_pk_bf16_f32 v3, v6, v3
	global_store_dwordx4 v[4:5], v[0:3], off
	s_cbranch_vccz .LBB0_207
; #define PG8_WAIT_V(n) asm volatile("s_waitcnt vmcnt(" #n ")" ::: "memory")
; #define PG8_BAR __builtin_amdgcn_s_barrier()
; template <class Epi>
; __device__ __forceinline__ void gemm_phase(LAS unsigned char* lds, const Gemm g, const StaticOrder& S, const Epi& E) {
;     ...
;     PG8_WAIT_V(0);
;     if (wr == 0) PG8_BAR;
;     PG8_BAR;
	s_waitcnt vmcnt(0)
	s_cmpk_gt_u32 s38, 0xff
	s_cbranch_scc1 .LBB0_214
	s_barrier

; #define PG8_STAGE(bufoff, gbase, voff) do { _Pragma("unroll") for (int _i = 0; _i < 2; ++_i) \
;         __builtin_amdgcn_global_load_lds((const unsigned*)((const char*)(gbase) + (voff)[_i]), (LAS unsigned*)(lds + (bufoff) + ldsw + _i * 8192), 16, 0, 0); } while (0)
; #define PG8_WAIT_V(n) asm volatile("s_waitcnt vmcnt(" #n ")" ::: "memory")
; #define PG8_BAR __builtin_amdgcn_s_barrier()
; template <class Epi>
; __device__ __forceinline__ void gemm_phase(LAS unsigned char* lds, const Gemm g, const StaticOrder& S, const Epi& E) {
;     ...
;     for (int i = 0; i < 2; ++i) { int R, C; stage_rc(tid * 16 + i * 8192, R, C); const int Rb = Epi::PERM ? ((R & ~31) + perm32(R & 31)) : R;
;         voffA[i] = (unsigned)(R * BK + C) * 2u; voffB[i] = (unsigned)(Rb * BK + C) * 2u; }
;     const size_t kstepA = (size_t)g.M * BK * 2, kstepB = (size_t)g.N * BK * 2;
;     const size_t hstep = (size_t)HALF * BK * 2;
;     const size_t tstep = 2 * hstep;
;     const unsigned ldsw = (unsigned)wid * 1024u;
;     const int aoff = lds_byte(wr * 64 + fr, fq * 8), boff = lds_byte(wc * 32 + fr, fq * 8);
;     ...
;     Unit cur, nxt; int ui = 0;
;     if (!S.next(0, cur)) return;
;     f32x4 acc[2][2][4][2];
; #pragma unroll
;     for (int a = 0; a < 2; ++a)
; #pragma unroll
;         for (int b = 0; b < 2; ++b)
; #pragma unroll
;             for (int m = 0; m < 4; ++m)
; #pragma unroll
;                 for (int n = 0; n < 2; ++n) acc[a][b][m][n] = (f32x4){0.f, 0.f, 0.f, 0.f};
;     bf16x8 At[4][2], B0[2][2], B1[2][2];
;     const char* cA = (const char*)g.A + (size_t)cur.pm * tstep; const char* cB = (const char*)g.Bt + (size_t)cur.pn * tstep;
;     PG8_STAGE(PG8_SB(0, 0), cB, voffB); PG8_STAGE(PG8_SA(0, 0), cA, voffA); PG8_STAGE(PG8_SB(0, 1), cB + hstep, voffB); PG8_STAGE(PG8_SA(0, 1), cA + hstep, voffA);
;     if (wr == 1) PG8_BAR;
;     PG8_WAIT_V(4); PG8_BAR;
;     PG8_STAGE(PG8_SB(1, 0), cB + kstepB, voffB); PG8_STAGE(PG8_SA(1, 0), cA + kstepA, voffA); PG8_STAGE(PG8_SB(1, 1), cB + hstep + kstepB, voffB);
;     PG8_WAIT_V(6); PG8_BAR;
.LBB0_431:
	s_lshl_b32 s1, s1, 5
	s_and_b32 s1, s1, 0x60
	s_lshl_b32 s5, s4, 13
	s_lshl_b32 s8, s1, 7
	s_add_u32 s6, s20, 0x40000
	s_addc_u32 s7, s21, 0
	s_add_i32 m0, s19, 0x18000
	v_lshl_add_u64 v[8:9], s[6:7], 0, v[130:131]
	s_waitcnt vmcnt(2)
	s_barrier
	global_load_lds_dwordx4 v[8:9], off
	s_add_i32 m0, s19, 0x1a000
	v_lshl_add_u64 v[8:9], s[6:7], 0, v[134:135]
	s_add_u32 s6, s24, 0x400000
	s_addc_u32 s7, s25, 0
	s_add_i32 s41, s19, 0x8000
	global_load_lds_dwordx4 v[8:9], off
	v_lshl_add_u64 v[8:9], s[6:7], 0, v[128:129]
	s_mov_b32 m0, s41
	s_add_i32 s42, s19, 0xa000
	global_load_lds_dwordx4 v[8:9], off
	v_lshl_add_u64 v[8:9], s[6:7], 0, v[132:133]
	s_add_u32 s6, s20, 0x44000
	s_mov_b32 m0, s42
	s_addc_u32 s7, s21, 0
	global_load_lds_dwordx4 v[8:9], off
	s_add_i32 m0, s19, 0x1c000
	v_lshl_add_u64 v[8:9], s[6:7], 0, v[130:131]
	global_load_lds_dwordx4 v[8:9], off
	v_lshl_add_u64 v[8:9], s[6:7], 0, v[134:135]
	s_add_i32 m0, s19, 0x1e000
	v_and_b32_e32 v7, 15, v0
	global_load_lds_dwordx4 v[8:9], off
	v_lshrrev_b32_e32 v8, 1, v0
	v_and_b32_e32 v8, 24, v8
	v_lshlrev_b32_e32 v9, 1, v8
	v_lshlrev_b32_e32 v0, 2, v0
	v_lshl_or_b32 v147, s4, 6, v7
	v_lshl_or_b32 v7, v7, 6, v9
	v_and_b32_e32 v0, 32, v0
	v_bitop3_b32 v9, v7, s5, v0 bitop3:0xde
	v_bitop3_b32 v148, v7, s8, v0 bitop3:0xde
	v_lshlrev_b32_e32 v0, 10, v1
	v_and_b32_e32 v0, 0xfffff800, v0
	v_lshl_add_u32 v0, v2, 7, v0
	v_and_b32_e32 v1, 1, v1
	v_lshl_or_b32 v0, v1, 6, v0
	v_lshl_add_u32 v136, v3, 1, v0
	v_lshlrev_b32_e32 v0, 10, v4
	v_and_b32_e32 v0, 0xfffff800, v0
	s_waitcnt vmcnt(6)
	v_lshl_add_u32 v0, v5, 7, v0
	v_and_b32_e32 v1, 1, v4
	v_lshl_or_b32 v0, v1, 6, v0
	s_add_i32 s45, 0, 0x10000
	s_add_i32 s48, 0, 0x14000
	s_sext_i32_i8 s54, s0
	s_ashr_i32 s43, s86, 31
	s_mov_b32 s44, s86
	v_or_b32_e32 v149, s1, v8
	v_mov_b32_e32 v137, v131
	v_lshl_add_u32 v138, v6, 1, v0
	v_mov_b32_e32 v139, v131
	v_mov_b64_e32 v[140:141], 0x400
	v_mov_b64_e32 v[142:143], 0x3ff
	v_add_u32_e32 v150, s45, v148
	v_add_u32_e32 v151, 0, v9
	v_add_u32_e32 v152, s48, v148
	s_mov_b64 s[4:5], 0x90000
	s_mov_b32 s49, 0x90000
	s_mov_b64 s[6:7], 0xa0000
	s_mov_b32 s50, 0xa0000
	s_mov_b64 s[8:9], 0xb0000
	s_mov_b32 s51, 0xb0000
	s_barrier
	s_waitcnt vmcnt(0)

; #define PG8_STAGE(bufoff, gbase, voff) do { _Pragma("unroll") for (int _i = 0; _i < 2; ++_i) \
;         __builtin_amdgcn_global_load_lds((const unsigned*)((const char*)(gbase) + (voff)[_i]), (LAS unsigned*)(lds + (bufoff) + ldsw + _i * 8192), 16, 0, 0); } while (0)
; #define PG8_LDA(dst, b, h) do { _Pragma("unroll") for (int m = 0; m < 4; ++m) _Pragma("unroll") for (int k = 0; k < 2; ++k) dst[m][k] = *(const LAS bf16x8*)(lds + PG8_SA(b, h) + aoff + m * 2048 + k * 1024); } while (0)
; #define PG8_LDB(dst, b, h) do { _Pragma("unroll") for (int n = 0; n < 2; ++n) _Pragma("unroll") for (int k = 0; k < 2; ++k) dst[n][k] = *(const LAS bf16x8*)(lds + PG8_SB(b, h) + boff + n * 2048 + k * 1024); } while (0)
; #define PG8_MMA(ai, bj, At, Bt) do { __builtin_amdgcn_s_setprio(1); _Pragma("unroll") for (int m = 0; m < 4; ++m) _Pragma("unroll") for (int n = 0; n < 2; ++n) _Pragma("unroll") for (int k = 0; k < 2; ++k) \
;         acc[ai][bj][m][n] = __builtin_amdgcn_mfma_f32_16x16x32_bf16(Bt[n][k], At[m][k], acc[ai][bj][m][n], 0, 0, 0); __builtin_amdgcn_s_setprio(0); } while (0)
; #define PG8_WAIT_V(n) asm volatile("s_waitcnt vmcnt(" #n ")" ::: "memory")
; #define PG8_WAIT_L(n) asm volatile("s_waitcnt lgkmcnt(" #n ")" ::: "memory")
; template <class Epi>
; __device__ __forceinline__ void gemm_phase(LAS unsigned char* lds, const Gemm g, const StaticOrder& S, const Epi& E) {
;     ...
;         for (int t = 0; t < nt; t += 2) {
;             const bool last = (t == nt - 2);
;             const char* a1 = cA + (size_t)(t + 1) * kstepA;
;             const char* a2 = last ? nA : cA + (size_t)(t + 2) * kstepA; const char* b2 = last ? nB : cB + (size_t)(t + 2) * kstepB;
;             const char* a3 = a2 + kstepA; const char* b3 = b2 + kstepB;
;             PG8_LDB(B0, 0, 0); PG8_SCHED; PG8_LDA(At, 0, 0); PG8_STAGE(PG8_SA(1, 1), a1 + hstep, voffA);
;             PG8_WAIT_L(8); PG8_BAR; PG8_WAIT_L(0); PG8_MMA(0, 0, At, B0); PG8_BAR; PG8_SCHED;
;             PG8_LDB(B1, 0, 1); PG8_STAGE(PG8_SB(0, 0), b2, voffB);
;             PG8_BAR; PG8_WAIT_L(0); PG8_MMA(0, 1, At, B1); PG8_BAR;
;             PG8_LDA(At, 0, 1); PG8_STAGE(PG8_SA(0, 0), a2, voffA);
;             PG8_BAR; PG8_WAIT_L(0); PG8_MMA(1, 0, At, B0); PG8_BAR; PG8_SCHED;
;             PG8_STAGE(PG8_SB(0, 1), b2 + hstep, voffB);
;             PG8_WAIT_V(6); PG8_BAR; PG8_MMA(1, 1, At, B1); PG8_BAR;
.LBB0_439:
	ds_read_b128 v[154:157], v150
	ds_read_b128 v[158:161], v150 offset:1024
	ds_read_b128 v[162:165], v150 offset:2048
	ds_read_b128 v[166:169], v150 offset:3072
	s_add_u32 s24, s20, 0x3fc000
	s_addc_u32 s25, s21, 0
	s_cmpk_eq_i32 s68, 0x54
	s_cselect_b32 s28, s55, s24
	s_cselect_b32 s29, s13, s25
	s_cselect_b32 s25, s11, s63
	s_cselect_b32 s24, s60, s61
	s_add_u32 s26, s28, 0x400000
	s_addc_u32 s27, s29, 0
	v_lshl_add_u64 v[144:145], s[20:21], 0, v[136:137]
	s_add_i32 m0, s19, 0xc000
	ds_read_b128 v[170:173], v151
	ds_read_b128 v[174:177], v151 offset:1024
	ds_read_b128 v[186:189], v151 offset:2048
	ds_read_b128 v[190:193], v151 offset:3072
	ds_read_b128 v[194:197], v151 offset:4096
	ds_read_b128 v[198:201], v151 offset:5120
	ds_read_b128 v[202:205], v151 offset:6144
	ds_read_b128 v[206:209], v151 offset:7168
	global_load_lds_dwordx4 v[144:145], off
	v_lshl_add_u64 v[144:145], s[20:21], 0, v[138:139]
	s_add_i32 m0, s19, 0xe000
	s_nop 0
	global_load_lds_dwordx4 v[144:145], off
	ds_read_b128 v[210:213], v152
	ds_read_b128 v[214:217], v152 offset:1024
	ds_read_b128 v[218:221], v152 offset:2048
	ds_read_b128 v[222:225], v152 offset:3072
	s_waitcnt lgkmcnt(0)
	s_waitcnt vmcnt(8)
	s_barrier
	s_setprio 1
	v_mfma_f32_16x16x32_bf16 v[124:127], v[154:157], v[170:173], v[124:127]
	v_mfma_f32_16x16x32_bf16 v[120:123], v[162:165], v[170:173], v[120:123]
	v_mfma_f32_16x16x32_bf16 v[112:115], v[154:157], v[186:189], v[112:115]
	v_mfma_f32_16x16x32_bf16 v[104:107], v[162:165], v[186:189], v[104:107]
	v_mfma_f32_16x16x32_bf16 v[96:99], v[154:157], v[194:197], v[96:99]
	v_mfma_f32_16x16x32_bf16 v[88:91], v[162:165], v[194:197], v[88:91]
	v_mfma_f32_16x16x32_bf16 v[80:83], v[154:157], v[202:205], v[80:83]
	v_mfma_f32_16x16x32_bf16 v[72:75], v[162:165], v[202:205], v[72:75]
	v_mfma_f32_16x16x32_bf16 v[124:127], v[158:161], v[174:177], v[124:127]
	v_mfma_f32_16x16x32_bf16 v[120:123], v[166:169], v[174:177], v[120:123]
	v_mfma_f32_16x16x32_bf16 v[112:115], v[158:161], v[190:193], v[112:115]
	v_mfma_f32_16x16x32_bf16 v[104:107], v[166:169], v[190:193], v[104:107]
	v_mfma_f32_16x16x32_bf16 v[96:99], v[158:161], v[198:201], v[96:99]
	v_mfma_f32_16x16x32_bf16 v[88:91], v[166:169], v[198:201], v[88:91]
	v_mfma_f32_16x16x32_bf16 v[80:83], v[158:161], v[206:209], v[80:83]
	v_mfma_f32_16x16x32_bf16 v[72:75], v[166:169], v[206:209], v[72:75]
	v_mfma_f32_16x16x32_bf16 v[116:119], v[210:213], v[170:173], v[116:119]
	v_mfma_f32_16x16x32_bf16 v[108:111], v[218:221], v[170:173], v[108:111]
	v_mfma_f32_16x16x32_bf16 v[100:103], v[210:213], v[186:189], v[100:103]
	v_mfma_f32_16x16x32_bf16 v[92:95], v[218:221], v[186:189], v[92:95]
	v_mfma_f32_16x16x32_bf16 v[84:87], v[210:213], v[194:197], v[84:87]
	v_mfma_f32_16x16x32_bf16 v[76:79], v[218:221], v[194:197], v[76:79]
	v_mfma_f32_16x16x32_bf16 v[68:71], v[210:213], v[202:205], v[68:71]
	v_mfma_f32_16x16x32_bf16 v[64:67], v[218:221], v[202:205], v[64:67]
	v_mfma_f32_16x16x32_bf16 v[116:119], v[214:217], v[174:177], v[116:119]
	v_mfma_f32_16x16x32_bf16 v[108:111], v[222:225], v[174:177], v[108:111]
	v_mfma_f32_16x16x32_bf16 v[100:103], v[214:217], v[190:193], v[100:103]
	v_mfma_f32_16x16x32_bf16 v[92:95], v[222:225], v[190:193], v[92:95]
	v_mfma_f32_16x16x32_bf16 v[84:87], v[214:217], v[198:201], v[84:87]
	v_mfma_f32_16x16x32_bf16 v[76:79], v[222:225], v[198:201], v[76:79]
	v_mfma_f32_16x16x32_bf16 v[68:71], v[214:217], v[206:209], v[68:71]
	v_mfma_f32_16x16x32_bf16 v[64:67], v[222:225], v[206:209], v[64:67]
	s_setprio 0
	s_barrier
	s_add_i32 s69, s45, s36
	v_lshl_add_u64 v[144:145], s[24:25], 0, v[130:131]
	s_mov_b32 m0, s69
	s_nop 0
	global_load_lds_dwordx4 v[144:145], off
	v_lshl_add_u64 v[144:145], s[24:25], 0, v[134:135]
	s_add_i32 m0, s69, 0x2000
	s_nop 0
	global_load_lds_dwordx4 v[144:145], off
	s_mov_b32 m0, s19
	v_lshl_add_u64 v[144:145], s[28:29], 0, v[128:129]
	ds_read_b128 v[170:173], v151 offset:16384
	ds_read_b128 v[174:177], v151 offset:17408
	ds_read_b128 v[186:189], v151 offset:18432
	ds_read_b128 v[190:193], v151 offset:19456
	ds_read_b128 v[194:197], v151 offset:20480
	ds_read_b128 v[198:201], v151 offset:21504
	ds_read_b128 v[202:205], v151 offset:22528
	ds_read_b128 v[206:209], v151 offset:23552
	global_load_lds_dwordx4 v[144:145], off
	v_lshl_add_u64 v[144:145], s[28:29], 0, v[132:133]
	s_mov_b32 m0, s37
	s_nop 0
	global_load_lds_dwordx4 v[144:145], off
	s_add_u32 s72, s24, 0x4000
	s_addc_u32 s73, s25, 0
	s_add_i32 s69, s48, s36
	v_lshl_add_u64 v[144:145], s[72:73], 0, v[130:131]
	s_mov_b32 m0, s69
	s_nop 0
	global_load_lds_dwordx4 v[144:145], off
	v_lshl_add_u64 v[144:145], s[72:73], 0, v[134:135]
	s_add_i32 m0, s69, 0x2000
	s_nop 0
	global_load_lds_dwordx4 v[144:145], off
	s_waitcnt lgkmcnt(0)
	s_waitcnt vmcnt(8)
	s_barrier
; #define PG8_STAGE(bufoff, gbase, voff) do { _Pragma("unroll") for (int _i = 0; _i < 2; ++_i) \
;         __builtin_amdgcn_global_load_lds((const unsigned*)((const char*)(gbase) + (voff)[_i]), (LAS unsigned*)(lds + (bufoff) + ldsw + _i * 8192), 16, 0, 0); } while (0)
; #define PG8_LDA(dst, b, h) do { _Pragma("unroll") for (int m = 0; m < 4; ++m) _Pragma("unroll") for (int k = 0; k < 2; ++k) dst[m][k] = *(const LAS bf16x8*)(lds + PG8_SA(b, h) + aoff + m * 2048 + k * 1024); } while (0)
; #define PG8_LDB(dst, b, h) do { _Pragma("unroll") for (int n = 0; n < 2; ++n) _Pragma("unroll") for (int k = 0; k < 2; ++k) dst[n][k] = *(const LAS bf16x8*)(lds + PG8_SB(b, h) + boff + n * 2048 + k * 1024); } while (0)
; #define PG8_MMA(ai, bj, At, Bt) do { __builtin_amdgcn_s_setprio(1); _Pragma("unroll") for (int m = 0; m < 4; ++m) _Pragma("unroll") for (int n = 0; n < 2; ++n) _Pragma("unroll") for (int k = 0; k < 2; ++k) \
;         acc[ai][bj][m][n] = __builtin_amdgcn_mfma_f32_16x16x32_bf16(Bt[n][k], At[m][k], acc[ai][bj][m][n], 0, 0, 0); __builtin_amdgcn_s_setprio(0); } while (0)
; #define PG8_WAIT_V(n) asm volatile("s_waitcnt vmcnt(" #n ")" ::: "memory")
; #define PG8_WAIT_L(n) asm volatile("s_waitcnt lgkmcnt(" #n ")" ::: "memory")
; #define PG8_BAR __builtin_amdgcn_s_barrier()
; #define PG8_SCHED __builtin_amdgcn_sched_barrier(0)
; template <class Epi>
; __device__ __forceinline__ void gemm_phase(LAS unsigned char* lds, const Gemm g, const StaticOrder& S, const Epi& E) {
;     ...
;             PG8_BAR; PG8_WAIT_L(0); PG8_MMA(1, 0, At, B0); PG8_BAR; PG8_SCHED;
;             PG8_STAGE(PG8_SB(0, 1), b2 + hstep, voffB);
;             PG8_WAIT_V(6); PG8_BAR; PG8_MMA(1, 1, At, B1); PG8_BAR;
;             PG8_LDB(B0, 1, 0); PG8_SCHED; PG8_LDA(At, 1, 0); PG8_STAGE(PG8_SA(0, 1), a2 + hstep, voffA);
;             PG8_WAIT_L(8); PG8_BAR; PG8_WAIT_L(0); PG8_MMA(0, 0, At, B0); PG8_BAR; PG8_SCHED;
;             PG8_LDB(B1, 1, 1); PG8_STAGE(PG8_SB(1, 0), b3, voffB);
;             PG8_BAR; PG8_WAIT_L(0); PG8_MMA(0, 1, At, B1); PG8_BAR;
;             PG8_LDA(At, 1, 1); PG8_STAGE(PG8_SA(1, 0), a3, voffA);
;             PG8_BAR; PG8_WAIT_L(0); PG8_MMA(1, 0, At, B0); PG8_BAR; PG8_SCHED;
	s_setprio 1
	v_mfma_f32_16x16x32_bf16 v[60:63], v[154:157], v[170:173], v[60:63]
	v_mfma_f32_16x16x32_bf16 v[56:59], v[162:165], v[170:173], v[56:59]
	v_mfma_f32_16x16x32_bf16 v[52:55], v[154:157], v[186:189], v[52:55]
	v_mfma_f32_16x16x32_bf16 v[44:47], v[162:165], v[186:189], v[44:47]
	v_mfma_f32_16x16x32_bf16 v[36:39], v[154:157], v[194:197], v[36:39]
	v_mfma_f32_16x16x32_bf16 v[28:31], v[162:165], v[194:197], v[28:31]
	v_mfma_f32_16x16x32_bf16 v[20:23], v[154:157], v[202:205], v[20:23]
	v_mfma_f32_16x16x32_bf16 v[12:15], v[162:165], v[202:205], v[12:15]
	v_mfma_f32_16x16x32_bf16 v[60:63], v[158:161], v[174:177], v[60:63]
	v_mfma_f32_16x16x32_bf16 v[56:59], v[166:169], v[174:177], v[56:59]
	v_mfma_f32_16x16x32_bf16 v[52:55], v[158:161], v[190:193], v[52:55]
	v_mfma_f32_16x16x32_bf16 v[44:47], v[166:169], v[190:193], v[44:47]
	v_mfma_f32_16x16x32_bf16 v[36:39], v[158:161], v[198:201], v[36:39]
	v_mfma_f32_16x16x32_bf16 v[28:31], v[166:169], v[198:201], v[28:31]
	v_mfma_f32_16x16x32_bf16 v[20:23], v[158:161], v[206:209], v[20:23]
	v_mfma_f32_16x16x32_bf16 v[12:15], v[166:169], v[206:209], v[12:15]
	v_mfma_f32_16x16x32_bf16 v[48:51], v[210:213], v[170:173], v[48:51]
	v_mfma_f32_16x16x32_bf16 v[40:43], v[218:221], v[170:173], v[40:43]
	v_mfma_f32_16x16x32_bf16 v[32:35], v[210:213], v[186:189], v[32:35]
	v_mfma_f32_16x16x32_bf16 v[24:27], v[218:221], v[186:189], v[24:27]
	v_mfma_f32_16x16x32_bf16 v[16:19], v[210:213], v[194:197], v[16:19]
	v_mfma_f32_16x16x32_bf16 v[8:11], v[218:221], v[194:197], v[8:11]
	v_mfma_f32_16x16x32_bf16 v[4:7], v[210:213], v[202:205], v[4:7]
	v_mfma_f32_16x16x32_bf16 v[0:3], v[218:221], v[202:205], v[0:3]
	v_mfma_f32_16x16x32_bf16 v[48:51], v[214:217], v[174:177], v[48:51]
	v_mfma_f32_16x16x32_bf16 v[40:43], v[222:225], v[174:177], v[40:43]
	v_mfma_f32_16x16x32_bf16 v[32:35], v[214:217], v[190:193], v[32:35]
	v_mfma_f32_16x16x32_bf16 v[24:27], v[222:225], v[190:193], v[24:27]
	v_mfma_f32_16x16x32_bf16 v[16:19], v[214:217], v[198:201], v[16:19]
	v_mfma_f32_16x16x32_bf16 v[8:11], v[222:225], v[198:201], v[8:11]
	v_mfma_f32_16x16x32_bf16 v[4:7], v[214:217], v[206:209], v[4:7]
	v_mfma_f32_16x16x32_bf16 v[0:3], v[222:225], v[206:209], v[0:3]
	s_setprio 0
	s_add_i32 s69, 0, 0x18000
	v_add_u32_e32 v144, s69, v148
	s_barrier
	ds_read_b128 v[154:157], v144
	ds_read_b128 v[158:161], v144 offset:1024
	ds_read_b128 v[162:165], v144 offset:2048
	ds_read_b128 v[166:169], v144 offset:3072
	s_add_u32 s28, s28, 0x4000
	s_addc_u32 s29, s29, 0
	s_mov_b32 m0, s38
	v_lshl_add_u64 v[144:145], s[28:29], 0, v[128:129]
	ds_read_b128 v[170:173], v151 offset:32768
	ds_read_b128 v[174:177], v151 offset:33792
	ds_read_b128 v[186:189], v151 offset:34816
	ds_read_b128 v[190:193], v151 offset:35840
	ds_read_b128 v[194:197], v151 offset:36864
	ds_read_b128 v[198:201], v151 offset:37888
	ds_read_b128 v[202:205], v151 offset:38912
	ds_read_b128 v[206:209], v151 offset:39936
	global_load_lds_dwordx4 v[144:145], off
	v_lshl_add_u64 v[144:145], s[28:29], 0, v[132:133]
	s_mov_b32 m0, s39
	s_nop 0
	global_load_lds_dwordx4 v[144:145], off
	v_add_u32_e32 v253, 0x1c000, v148
	ds_read_b128 v[210:213], v253
	ds_read_b128 v[214:217], v253 offset:1024
	ds_read_b128 v[218:221], v253 offset:2048
	ds_read_b128 v[222:225], v253 offset:3072
	s_waitcnt lgkmcnt(0)
	s_waitcnt vmcnt(8)
	s_barrier
	s_setprio 1
	v_mfma_f32_16x16x32_bf16 v[124:127], v[154:157], v[170:173], v[124:127]
	v_mfma_f32_16x16x32_bf16 v[120:123], v[162:165], v[170:173], v[120:123]
	v_mfma_f32_16x16x32_bf16 v[112:115], v[154:157], v[186:189], v[112:115]
	v_mfma_f32_16x16x32_bf16 v[104:107], v[162:165], v[186:189], v[104:107]
	v_mfma_f32_16x16x32_bf16 v[96:99], v[154:157], v[194:197], v[96:99]
	v_mfma_f32_16x16x32_bf16 v[88:91], v[162:165], v[194:197], v[88:91]
	v_mfma_f32_16x16x32_bf16 v[80:83], v[154:157], v[202:205], v[80:83]
	v_mfma_f32_16x16x32_bf16 v[72:75], v[162:165], v[202:205], v[72:75]
	v_mfma_f32_16x16x32_bf16 v[124:127], v[158:161], v[174:177], v[124:127]
	v_mfma_f32_16x16x32_bf16 v[120:123], v[166:169], v[174:177], v[120:123]
	v_mfma_f32_16x16x32_bf16 v[112:115], v[158:161], v[190:193], v[112:115]
	v_mfma_f32_16x16x32_bf16 v[104:107], v[166:169], v[190:193], v[104:107]
	v_mfma_f32_16x16x32_bf16 v[96:99], v[158:161], v[198:201], v[96:99]
	v_mfma_f32_16x16x32_bf16 v[88:91], v[166:169], v[198:201], v[88:91]
	v_mfma_f32_16x16x32_bf16 v[80:83], v[158:161], v[206:209], v[80:83]
	v_mfma_f32_16x16x32_bf16 v[72:75], v[166:169], v[206:209], v[72:75]
	v_mfma_f32_16x16x32_bf16 v[116:119], v[210:213], v[170:173], v[116:119]
	v_mfma_f32_16x16x32_bf16 v[108:111], v[218:221], v[170:173], v[108:111]
	v_mfma_f32_16x16x32_bf16 v[100:103], v[210:213], v[186:189], v[100:103]
	v_mfma_f32_16x16x32_bf16 v[92:95], v[218:221], v[186:189], v[92:95]
	v_mfma_f32_16x16x32_bf16 v[84:87], v[210:213], v[194:197], v[84:87]
	v_mfma_f32_16x16x32_bf16 v[76:79], v[218:221], v[194:197], v[76:79]
	v_mfma_f32_16x16x32_bf16 v[68:71], v[210:213], v[202:205], v[68:71]
	v_mfma_f32_16x16x32_bf16 v[64:67], v[218:221], v[202:205], v[64:67]
	v_mfma_f32_16x16x32_bf16 v[116:119], v[214:217], v[174:177], v[116:119]
	v_mfma_f32_16x16x32_bf16 v[108:111], v[222:225], v[174:177], v[108:111]
	v_mfma_f32_16x16x32_bf16 v[100:103], v[214:217], v[190:193], v[100:103]
	v_mfma_f32_16x16x32_bf16 v[92:95], v[222:225], v[190:193], v[92:95]
	v_mfma_f32_16x16x32_bf16 v[84:87], v[214:217], v[198:201], v[84:87]
	v_mfma_f32_16x16x32_bf16 v[76:79], v[222:225], v[198:201], v[76:79]
	v_mfma_f32_16x16x32_bf16 v[68:71], v[214:217], v[206:209], v[68:71]
	v_mfma_f32_16x16x32_bf16 v[64:67], v[222:225], v[206:209], v[64:67]
	s_setprio 0
	s_barrier
; #define PG8_STAGE(bufoff, gbase, voff) do { _Pragma("unroll") for (int _i = 0; _i < 2; ++_i) \
;         __builtin_amdgcn_global_load_lds((const unsigned*)((const char*)(gbase) + (voff)[_i]), (LAS unsigned*)(lds + (bufoff) + ldsw + _i * 8192), 16, 0, 0); } while (0)
; #define PG8_LDA(dst, b, h) do { _Pragma("unroll") for (int m = 0; m < 4; ++m) _Pragma("unroll") for (int k = 0; k < 2; ++k) dst[m][k] = *(const LAS bf16x8*)(lds + PG8_SA(b, h) + aoff + m * 2048 + k * 1024); } while (0)
; #define PG8_LDB(dst, b, h) do { _Pragma("unroll") for (int n = 0; n < 2; ++n) _Pragma("unroll") for (int k = 0; k < 2; ++k) dst[n][k] = *(const LAS bf16x8*)(lds + PG8_SB(b, h) + boff + n * 2048 + k * 1024); } while (0)
; #define PG8_MMA(ai, bj, At, Bt) do { __builtin_amdgcn_s_setprio(1); _Pragma("unroll") for (int m = 0; m < 4; ++m) _Pragma("unroll") for (int n = 0; n < 2; ++n) _Pragma("unroll") for (int k = 0; k < 2; ++k) \
;         acc[ai][bj][m][n] = __builtin_amdgcn_mfma_f32_16x16x32_bf16(Bt[n][k], At[m][k], acc[ai][bj][m][n], 0, 0, 0); __builtin_amdgcn_s_setprio(0); } while (0)
; #define PG8_WAIT_V(n) asm volatile("s_waitcnt vmcnt(" #n ")" ::: "memory")
; #define PG8_WAIT_L(n) asm volatile("s_waitcnt lgkmcnt(" #n ")" ::: "memory")
; #define PG8_BAR __builtin_amdgcn_s_barrier()
; #define PG8_SCHED __builtin_amdgcn_sched_barrier(0)
; template <class Epi>
; __device__ __forceinline__ void gemm_phase(LAS unsigned char* lds, const Gemm g, const StaticOrder& S, const Epi& E) {
;     ...
;             PG8_LDB(B1, 1, 1); PG8_STAGE(PG8_SB(1, 0), b3, voffB);
;             PG8_BAR; PG8_WAIT_L(0); PG8_MMA(0, 1, At, B1); PG8_BAR;
;             PG8_LDA(At, 1, 1); PG8_STAGE(PG8_SA(1, 0), a3, voffA);
;             PG8_BAR; PG8_WAIT_L(0); PG8_MMA(1, 0, At, B0); PG8_BAR; PG8_SCHED;
;             PG8_STAGE(PG8_SB(1, 1), b3 + hstep, voffB);
;             PG8_WAIT_V(6); PG8_BAR; PG8_MMA(1, 1, At, B1); PG8_BAR;
;         }
	s_add_i32 s72, 0, 0x1c000
	s_add_u32 s28, s24, 0x40000
	v_add_u32_e32 v144, s72, v148
	s_addc_u32 s29, s25, 0
	s_add_i32 s69, s69, s36
	s_nop 0
	v_lshl_add_u64 v[144:145], s[28:29], 0, v[130:131]
	s_mov_b32 m0, s69
	s_nop 0
	global_load_lds_dwordx4 v[144:145], off
	v_lshl_add_u64 v[144:145], s[28:29], 0, v[134:135]
	s_add_i32 m0, s69, 0x2000
	s_nop 0
	global_load_lds_dwordx4 v[144:145], off
	s_mov_b32 m0, s41
	v_lshl_add_u64 v[144:145], s[26:27], 0, v[128:129]
	ds_read_b128 v[170:173], v151 offset:49152
	ds_read_b128 v[174:177], v151 offset:50176
	ds_read_b128 v[186:189], v151 offset:51200
	ds_read_b128 v[190:193], v151 offset:52224
	ds_read_b128 v[194:197], v151 offset:53248
	ds_read_b128 v[198:201], v151 offset:54272
	ds_read_b128 v[202:205], v151 offset:55296
	ds_read_b128 v[206:209], v151 offset:56320
	global_load_lds_dwordx4 v[144:145], off
	v_lshl_add_u64 v[144:145], s[26:27], 0, v[132:133]
	s_mov_b32 m0, s42
	s_nop 0
	global_load_lds_dwordx4 v[144:145], off
	s_add_u32 s24, s24, 0x44000
	s_addc_u32 s25, s25, 0
	s_add_i32 s26, s72, s36
	v_lshl_add_u64 v[144:145], s[24:25], 0, v[130:131]
	s_mov_b32 m0, s26
	s_nop 0
	global_load_lds_dwordx4 v[144:145], off
	v_lshl_add_u64 v[144:145], s[24:25], 0, v[134:135]
	s_add_i32 m0, s26, 0x2000
	s_nop 0
	global_load_lds_dwordx4 v[144:145], off
	s_waitcnt lgkmcnt(0)
	s_waitcnt vmcnt(8)
	s_barrier
	s_setprio 1
	v_mfma_f32_16x16x32_bf16 v[60:63], v[154:157], v[170:173], v[60:63]
	v_mfma_f32_16x16x32_bf16 v[56:59], v[162:165], v[170:173], v[56:59]
	v_mfma_f32_16x16x32_bf16 v[52:55], v[154:157], v[186:189], v[52:55]
	v_mfma_f32_16x16x32_bf16 v[44:47], v[162:165], v[186:189], v[44:47]
	v_mfma_f32_16x16x32_bf16 v[36:39], v[154:157], v[194:197], v[36:39]
	v_mfma_f32_16x16x32_bf16 v[28:31], v[162:165], v[194:197], v[28:31]
	v_mfma_f32_16x16x32_bf16 v[20:23], v[154:157], v[202:205], v[20:23]
	v_mfma_f32_16x16x32_bf16 v[12:15], v[162:165], v[202:205], v[12:15]
	v_mfma_f32_16x16x32_bf16 v[60:63], v[158:161], v[174:177], v[60:63]
	v_mfma_f32_16x16x32_bf16 v[56:59], v[166:169], v[174:177], v[56:59]
	v_mfma_f32_16x16x32_bf16 v[52:55], v[158:161], v[190:193], v[52:55]
	v_mfma_f32_16x16x32_bf16 v[44:47], v[166:169], v[190:193], v[44:47]
	v_mfma_f32_16x16x32_bf16 v[36:39], v[158:161], v[198:201], v[36:39]
	v_mfma_f32_16x16x32_bf16 v[28:31], v[166:169], v[198:201], v[28:31]
	v_mfma_f32_16x16x32_bf16 v[20:23], v[158:161], v[206:209], v[20:23]
	v_mfma_f32_16x16x32_bf16 v[12:15], v[166:169], v[206:209], v[12:15]
	v_mfma_f32_16x16x32_bf16 v[48:51], v[210:213], v[170:173], v[48:51]
	v_mfma_f32_16x16x32_bf16 v[40:43], v[218:221], v[170:173], v[40:43]
	v_mfma_f32_16x16x32_bf16 v[32:35], v[210:213], v[186:189], v[32:35]
	v_mfma_f32_16x16x32_bf16 v[24:27], v[218:221], v[186:189], v[24:27]
	v_mfma_f32_16x16x32_bf16 v[16:19], v[210:213], v[194:197], v[16:19]
	v_mfma_f32_16x16x32_bf16 v[8:11], v[218:221], v[194:197], v[8:11]
	v_mfma_f32_16x16x32_bf16 v[4:7], v[210:213], v[202:205], v[4:7]
	v_mfma_f32_16x16x32_bf16 v[0:3], v[218:221], v[202:205], v[0:3]
	v_mfma_f32_16x16x32_bf16 v[48:51], v[214:217], v[174:177], v[48:51]
	v_mfma_f32_16x16x32_bf16 v[40:43], v[222:225], v[174:177], v[40:43]
	v_mfma_f32_16x16x32_bf16 v[32:35], v[214:217], v[190:193], v[32:35]
	v_mfma_f32_16x16x32_bf16 v[24:27], v[222:225], v[190:193], v[24:27]
	v_mfma_f32_16x16x32_bf16 v[16:19], v[214:217], v[198:201], v[16:19]
	v_mfma_f32_16x16x32_bf16 v[8:11], v[222:225], v[198:201], v[8:11]
	v_mfma_f32_16x16x32_bf16 v[4:7], v[214:217], v[206:209], v[4:7]
	v_mfma_f32_16x16x32_bf16 v[0:3], v[222:225], v[206:209], v[0:3]
	s_setprio 0
	s_add_i32 s68, s68, 2
	s_add_u32 s61, s61, 0x80000
	s_addc_u32 s63, s63, 0
	s_add_u32 s20, s20, 0x800000
	s_addc_u32 s21, s21, 0
	s_cmpk_gt_u32 s68, 0x55
	s_barrier
	s_cbranch_scc0 .LBB0_439
; __device__ __forceinline__ unsigned pk_bf16(float lo, float hi) { unsigned r; asm("v_cvt_pk_bf16_f32 %0, %1, %2" : "=v"(r) : "v"(lo), "v"(hi)); return r; }
; #define PG8_WAIT_V(n) asm volatile("s_waitcnt vmcnt(" #n ")" ::: "memory")
; #define PG8_BAR __builtin_amdgcn_s_barrier()
;     __device__ __forceinline__ void operator()(const f32x4 (&acc)[2][2][4][2], const Unit& u, int wr, int wc, int fr, int fq) const {
;         const int row0 = u.pm * BM + wr * 64 + fr; const int col0 = u.pn * BM + wc * 32 + 8 * fq;
; #pragma unroll
;         for (int ai = 0; ai < 2; ++ai)
; #pragma unroll
;             for (int m = 0; m < 4; ++m) { bf16_t* rowp = O + (size_t)(row0 + ai * HALF + m * 16) * ldc + col0;
; #pragma unroll
;                 for (int bj = 0; bj < 2; ++bj) { const f32x4 v0 = acc[ai][bj][m][0], v1 = acc[ai][bj][m][1];
;                     u32x4 w; w.x = pk_bf16(v0[0], v0[1]); w.y = pk_bf16(v0[2], v0[3]); w.z = pk_bf16(v1[0], v1[1]); w.w = pk_bf16(v1[2], v1[3]);
;                     *(u32x4*)(rowp + bj * HALF) = w; } }
; template <class Epi>
; __device__ __forceinline__ void gemm_phase(LAS unsigned char* lds, const Gemm g, const StaticOrder& S, const Epi& E) {
;     ...
;         cur = nxt; cA = nA; cB = nB; ++ui;
;     }
;     PG8_WAIT_V(0);
;     if (wr == 0) PG8_BAR;
;     PG8_BAR;
	v_lshl_add_u32 v154, s18, 8, v147
	v_lshl_or_b32 v144, s54, 8, v149
	v_ashrrev_i32_e32 v155, 31, v154
	v_ashrrev_i32_e32 v145, 31, v144
	v_lshlrev_b64 v[156:157], 12, v[154:155]
	v_lshl_add_u64 v[156:157], s[52:53], 0, v[156:157]
	v_lshlrev_b64 v[158:159], 1, v[144:145]
	v_lshl_add_u64 v[144:145], v[156:157], 0, v[158:159]
	s_mov_b32 s11, 0x80000
	v_cvt_pk_bf16_f32 v60, v60, v61
	v_cvt_pk_bf16_f32 v61, v62, v63
	v_cvt_pk_bf16_f32 v62, v56, v57
	v_add_co_u32_e32 v56, vcc, s11, v144
	v_cvt_pk_bf16_f32 v116, v116, v117
	v_cvt_pk_bf16_f32 v117, v118, v119
	v_cvt_pk_bf16_f32 v118, v108, v109
	v_or_b32_e32 v108, 16, v154
	s_nop 0
	v_addc_co_u32_e32 v57, vcc, 0, v145, vcc
	v_cvt_pk_bf16_f32 v48, v48, v49
	v_cvt_pk_bf16_f32 v49, v50, v51
	v_cvt_pk_bf16_f32 v51, v42, v43
	v_cvt_pk_bf16_f32 v42, v44, v45
	v_add_co_u32_e32 v44, vcc, s49, v144
	v_ashrrev_i32_e32 v109, 31, v108
	v_cvt_pk_bf16_f32 v100, v100, v101
	v_cvt_pk_bf16_f32 v101, v102, v103
	v_cvt_pk_bf16_f32 v102, v92, v93
	v_or_b32_e32 v92, 32, v154
	v_addc_co_u32_e32 v45, vcc, 0, v145, vcc
	v_lshlrev_b64 v[108:109], 12, v[108:109]
	v_ashrrev_i32_e32 v93, 31, v92
	v_cvt_pk_bf16_f32 v84, v84, v85
	v_cvt_pk_bf16_f32 v85, v86, v87
	v_cvt_pk_bf16_f32 v86, v76, v77
	v_or_b32_e32 v76, 48, v154
	s_mov_b64 s[20:21], 0x80000
	v_cvt_pk_bf16_f32 v32, v32, v33
	v_cvt_pk_bf16_f32 v33, v34, v35
	v_cvt_pk_bf16_f32 v35, v26, v27
	v_cvt_pk_bf16_f32 v26, v28, v29
	v_add_co_u32_e32 v28, vcc, s50, v144
	v_lshl_add_u64 v[108:109], s[52:53], 0, v[108:109]
	v_lshlrev_b64 v[92:93], 12, v[92:93]
	v_ashrrev_i32_e32 v77, 31, v76
	v_cvt_pk_bf16_f32 v68, v68, v69
	v_cvt_pk_bf16_f32 v69, v70, v71
	v_cvt_pk_bf16_f32 v70, v64, v65
	v_lshl_add_u64 v[64:65], v[144:145], 0, s[20:21]
	v_addc_co_u32_e32 v29, vcc, 0, v145, vcc
	v_cvt_pk_bf16_f32 v119, v110, v111
	global_store_dwordx4 v[144:145], v[116:119], off offset:256
	v_lshl_add_u64 v[92:93], s[52:53], 0, v[92:93]
	v_lshlrev_b64 v[76:77], 12, v[76:77]
	v_lshl_add_u64 v[116:117], v[108:109], 0, v[158:159]
	v_cvt_pk_bf16_f32 v50, v40, v41
	global_store_dwordx4 v[64:65], v[48:51], off offset:256
	v_cvt_pk_bf16_f32 v16, v16, v17
	v_cvt_pk_bf16_f32 v17, v18, v19
	v_cvt_pk_bf16_f32 v19, v10, v11
	v_cvt_pk_bf16_f32 v10, v12, v13
	v_add_co_u32_e32 v12, vcc, s51, v144
	s_nop 0
	v_lshl_add_u64 v[48:49], v[144:145], 0, s[4:5]
	v_cvt_pk_bf16_f32 v103, v94, v95
	global_store_dwordx4 v[116:117], v[100:103], off offset:256
	v_lshl_add_u64 v[76:77], s[52:53], 0, v[76:77]
	v_cvt_pk_bf16_f32 v34, v24, v25
	global_store_dwordx4 v[48:49], v[32:35], off offset:256
	v_lshl_add_u64 v[100:101], v[92:93], 0, v[158:159]
	v_addc_co_u32_e32 v13, vcc, 0, v145, vcc
	v_lshl_add_u64 v[32:33], v[144:145], 0, s[6:7]
	v_cvt_pk_bf16_f32 v87, v78, v79
	global_store_dwordx4 v[100:101], v[84:87], off offset:256
	v_cvt_pk_bf16_f32 v18, v8, v9
	global_store_dwordx4 v[32:33], v[16:19], off offset:256
	s_and_b64 vcc, exec, s[0:1]
	v_lshl_add_u64 v[84:85], v[76:77], 0, v[158:159]
	v_lshl_add_u64 v[16:17], v[144:145], 0, s[8:9]
	s_mov_b32 s54, s10
	s_mov_b32 s18, s12
	s_mov_b64 s[20:21], s[16:17]
	s_mov_b64 s[24:25], s[14:15]
	v_cvt_pk_bf16_f32 v124, v124, v125
	v_cvt_pk_bf16_f32 v125, v126, v127
	v_cvt_pk_bf16_f32 v126, v120, v121
	v_cvt_pk_bf16_f32 v127, v122, v123
	global_store_dwordx4 v[144:145], v[124:127], off
	v_cvt_pk_bf16_f32 v108, v112, v113
	v_cvt_pk_bf16_f32 v109, v114, v115
	v_cvt_pk_bf16_f32 v110, v104, v105
	v_cvt_pk_bf16_f32 v111, v106, v107
	global_store_dwordx4 v[116:117], v[108:111], off
	v_cvt_pk_bf16_f32 v92, v96, v97
	v_cvt_pk_bf16_f32 v93, v98, v99
	v_cvt_pk_bf16_f32 v94, v88, v89
	v_cvt_pk_bf16_f32 v95, v90, v91
	global_store_dwordx4 v[100:101], v[92:95], off
	v_cvt_pk_bf16_f32 v76, v80, v81
	v_cvt_pk_bf16_f32 v77, v82, v83
	v_cvt_pk_bf16_f32 v78, v72, v73
	v_cvt_pk_bf16_f32 v79, v74, v75
	global_store_dwordx4 v[84:85], v[76:79], off
	v_cvt_pk_bf16_f32 v71, v66, v67
	global_store_dwordx4 v[84:85], v[68:71], off offset:256
	v_cvt_pk_bf16_f32 v63, v58, v59
	global_store_dwordx4 v[56:57], v[60:63], off
	v_cvt_pk_bf16_f32 v40, v52, v53
	v_cvt_pk_bf16_f32 v41, v54, v55
	v_cvt_pk_bf16_f32 v43, v46, v47
	global_store_dwordx4 v[44:45], v[40:43], off
	v_cvt_pk_bf16_f32 v24, v36, v37
	v_cvt_pk_bf16_f32 v25, v38, v39
	v_cvt_pk_bf16_f32 v27, v30, v31
	global_store_dwordx4 v[28:29], v[24:27], off
	v_cvt_pk_bf16_f32 v8, v20, v21
	v_cvt_pk_bf16_f32 v9, v22, v23
	v_cvt_pk_bf16_f32 v11, v14, v15
	global_store_dwordx4 v[12:13], v[8:11], off
	v_cvt_pk_bf16_f32 v4, v4, v5
	v_cvt_pk_bf16_f32 v5, v6, v7
	v_cvt_pk_bf16_f32 v6, v0, v1
	v_cvt_pk_bf16_f32 v7, v2, v3
	global_store_dwordx4 v[16:17], v[4:7], off offset:256
	s_cbranch_vccz .LBB0_432
	s_waitcnt vmcnt(0)
	s_cmpk_gt_u32 s30, 0xff
	s_cbranch_scc1 .LBB0_443
	s_barrier

;     __device__ __forceinline__ void operator()(const f32x4 (&acc)[2][2][4][2], const Unit& u, int wr, int wc, int fr, int fq) const {
;         const int row0 = u.pm * BM + wr * 64 + fr; const int col0 = u.pn * BM + wc * 32 + 8 * fq;
; #pragma unroll
;         for (int ai = 0; ai < 2; ++ai)
; #pragma unroll
;             for (int m = 0; m < 4; ++m) { bf16_t* rowp = O + (size_t)(row0 + ai * HALF + m * 16) * ldc + col0;
; #pragma unroll
;                 for (int bj = 0; bj < 2; ++bj) { const f32x4 v0 = acc[ai][bj][m][0], v1 = acc[ai][bj][m][1];
;                     u32x4 w; w.x = pk_bf16(v0[0], v0[1]); w.y = pk_bf16(v0[2], v0[3]); w.z = pk_bf16(v1[0], v1[1]); w.w = pk_bf16(v1[2], v1[3]);
;                     *(u32x4*)(rowp + bj * HALF) = w; } }
; template <class Epi>
; __device__ __forceinline__ void gemm_phase(LAS unsigned char* lds, const Gemm g, const StaticOrder& S, const Epi& E) {
;     ...
;     for (int i = 0; i < 2; ++i) { int R, C; stage_rc(tid * 16 + i * 8192, R, C); const int Rb = Epi::PERM ? ((R & ~31) + perm32(R & 31)) : R;
;         voffA[i] = (unsigned)(R * BK + C) * 2u; voffB[i] = (unsigned)(Rb * BK + C) * 2u; }
;     const size_t kstepA = (size_t)g.M * BK * 2, kstepB = (size_t)g.N * BK * 2;
;     const size_t hstep = (size_t)HALF * BK * 2;
;     const size_t tstep = 2 * hstep;
;     const unsigned ldsw = (unsigned)wid * 1024u;
;     const int aoff = lds_byte(wr * 64 + fr, fq * 8), boff = lds_byte(wc * 32 + fr, fq * 8);
;     ...
;     Unit cur, nxt; int ui = 0;
;     if (!S.next(0, cur)) return;
;     f32x4 acc[2][2][4][2];
; #pragma unroll
;     for (int a = 0; a < 2; ++a)
; #pragma unroll
;         for (int b = 0; b < 2; ++b)
; #pragma unroll
;             for (int m = 0; m < 4; ++m)
; #pragma unroll
;                 for (int n = 0; n < 2; ++n) acc[a][b][m][n] = (f32x4){0.f, 0.f, 0.f, 0.f};
;     bf16x8 At[4][2], B0[2][2], B1[2][2];
;     const char* cA = (const char*)g.A + (size_t)cur.pm * tstep; const char* cB = (const char*)g.Bt + (size_t)cur.pn * tstep;
;     PG8_STAGE(PG8_SB(0, 0), cB, voffB); PG8_STAGE(PG8_SA(0, 0), cA, voffA); PG8_STAGE(PG8_SB(0, 1), cB + hstep, voffB); PG8_STAGE(PG8_SA(0, 1), cA + hstep, voffA);
;     if (wr == 1) PG8_BAR;
;     PG8_WAIT_V(4); PG8_BAR;
;     PG8_STAGE(PG8_SB(1, 0), cB + kstepB, voffB); PG8_STAGE(PG8_SA(1, 0), cA + kstepA, voffA); PG8_STAGE(PG8_SB(1, 1), cB + hstep + kstepB, voffB);
;     PG8_WAIT_V(6); PG8_BAR;
.LBB0_558:
	s_lshl_b32 s4, s4, 5
	s_and_b32 s7, s4, 0x60
	s_lshl_b32 s6, s1, 13
	s_lshl_b32 s8, s7, 7
	s_add_u32 s4, s16, 0xa0000
	s_addc_u32 s5, s17, 0
	s_add_i32 m0, s13, 0x18000
	v_lshl_add_u64 v[8:9], s[4:5], 0, v[138:139]
	s_waitcnt vmcnt(2)
	s_barrier
	global_load_lds_dwordx4 v[8:9], off
	s_add_i32 m0, s13, 0x1a000
	v_lshl_add_u64 v[8:9], s[4:5], 0, v[134:135]
	s_add_u32 s4, s18, 0x400000
	s_addc_u32 s5, s19, 0
	s_add_i32 s38, s13, 0x8000
	global_load_lds_dwordx4 v[8:9], off
	v_lshl_add_u64 v[8:9], s[4:5], 0, v[140:141]
	s_mov_b32 m0, s38
	s_add_i32 s39, s13, 0xa000
	global_load_lds_dwordx4 v[8:9], off
	v_lshl_add_u64 v[8:9], s[4:5], 0, v[136:137]
	s_add_u32 s4, s16, 0xa4000
	s_mov_b32 m0, s39
	s_addc_u32 s5, s17, 0
	global_load_lds_dwordx4 v[8:9], off
	s_add_i32 m0, s13, 0x1c000
	v_lshl_add_u64 v[8:9], s[4:5], 0, v[138:139]
	global_load_lds_dwordx4 v[8:9], off
	v_lshl_add_u64 v[8:9], s[4:5], 0, v[134:135]
	s_add_i32 m0, s13, 0x1e000
	v_and_b32_e32 v7, 15, v1
	global_load_lds_dwordx4 v[8:9], off
	v_lshrrev_b32_e32 v8, 1, v1
	v_and_b32_e32 v8, 24, v8
	v_lshlrev_b32_e32 v9, 1, v8
	v_lshlrev_b32_e32 v1, 2, v1
	v_lshl_or_b32 v131, s1, 6, v7
	v_lshl_or_b32 v7, v7, 6, v9
	v_and_b32_e32 v1, 32, v1
	v_bitop3_b32 v9, v7, s6, v1 bitop3:0xde
	v_bitop3_b32 v133, v7, s8, v1 bitop3:0xde
	v_lshlrev_b32_e32 v1, 10, v5
	v_and_b32_e32 v1, 0xfffff800, v1
	v_lshl_add_u32 v1, v4, 7, v1
	v_and_b32_e32 v4, 1, v5
	v_lshl_or_b32 v1, v4, 6, v1
	v_lshl_add_u32 v142, v6, 1, v1
	v_lshlrev_b32_e32 v1, 10, v0
	v_and_b32_e32 v1, 0xfffff800, v1
	s_waitcnt vmcnt(6)
	v_lshl_add_u32 v1, v2, 7, v1
	v_and_b32_e32 v0, 1, v0
	v_lshl_or_b32 v0, v0, 6, v1
	s_sext_i32_i16 s45, s0
	s_ashr_i32 s40, s86, 31
	s_mov_b32 s41, s86
	v_or_b32_e32 v154, s7, v8
	v_mov_b32_e32 v143, v139
	v_lshl_add_u32 v144, v3, 1, v0
	v_mov_b32_e32 v145, v139
	v_mov_b64_e32 v[146:147], 0xa00
	v_mov_b64_e32 v[148:149], 0x9ff
	s_add_i32 s42, 0, 0x10000
	v_add_u32_e32 v155, 0, v9
	s_add_i32 s43, 0, 0x14000
	s_movk_i32 s44, 0x2800
	s_barrier
	s_branch .LBB0_560
.LBB0_559:
	v_lshl_add_u32 v158, s12, 8, v131
	v_lshl_or_b32 v152, s45, 8, v154
	v_ashrrev_i32_e32 v153, 31, v152
	v_mov_b64_e32 v[150:151], s[2:3]
	v_cvt_pk_bf16_f32 v68, v68, v69
	v_cvt_pk_bf16_f32 v69, v70, v71
	v_cvt_pk_bf16_f32 v70, v64, v65
	v_add_u32_e32 v64, 0x80, v158
	v_mad_i64_i32 v[156:157], s[14:15], v158, s44, v[150:151]
	v_lshlrev_b64 v[152:153], 1, v[152:153]
	v_cvt_pk_bf16_f32 v112, v112, v113
	v_cvt_pk_bf16_f32 v113, v114, v115
	v_cvt_pk_bf16_f32 v114, v104, v105
	v_or_b32_e32 v104, 16, v158
	v_mad_i64_i32 v[64:65], s[14:15], v64, s44, v[150:151]
	v_cvt_pk_bf16_f32 v48, v48, v49
	v_cvt_pk_bf16_f32 v49, v50, v51
	v_cvt_pk_bf16_f32 v50, v40, v41
	v_add_u32_e32 v40, 0x90, v158
	v_lshl_add_u64 v[156:157], v[156:157], 0, v[152:153]
	v_mad_i64_i32 v[104:105], s[14:15], v104, s44, v[150:151]
	v_cvt_pk_bf16_f32 v96, v96, v97
	v_cvt_pk_bf16_f32 v97, v98, v99
	v_cvt_pk_bf16_f32 v98, v88, v89
	v_or_b32_e32 v88, 32, v158
	v_lshl_add_u64 v[64:65], v[64:65], 0, v[152:153]
	v_mad_i64_i32 v[40:41], s[14:15], v40, s44, v[150:151]
	v_cvt_pk_bf16_f32 v32, v32, v33
	v_cvt_pk_bf16_f32 v33, v34, v35
	v_cvt_pk_bf16_f32 v34, v24, v25
	v_add_u32_e32 v24, 0xa0, v158
	v_cvt_pk_bf16_f32 v115, v106, v107
	global_store_dwordx4 v[156:157], v[112:115], off offset:256
	v_mad_i64_i32 v[88:89], s[14:15], v88, s44, v[150:151]
	s_nop 0
	v_lshl_add_u64 v[112:113], v[104:105], 0, v[152:153]
	v_cvt_pk_bf16_f32 v80, v80, v81
	v_cvt_pk_bf16_f32 v81, v82, v83
	v_cvt_pk_bf16_f32 v82, v72, v73
	v_or_b32_e32 v72, 48, v158
	v_cvt_pk_bf16_f32 v51, v42, v43
	global_store_dwordx4 v[64:65], v[48:51], off offset:256
	v_mad_i64_i32 v[24:25], s[14:15], v24, s44, v[150:151]
	s_nop 0
	v_lshl_add_u64 v[48:49], v[40:41], 0, v[152:153]
	v_cvt_pk_bf16_f32 v16, v16, v17
	v_cvt_pk_bf16_f32 v17, v18, v19
	v_cvt_pk_bf16_f32 v18, v8, v9
	v_add_u32_e32 v8, 0xb0, v158
	v_cvt_pk_bf16_f32 v99, v90, v91
	global_store_dwordx4 v[112:113], v[96:99], off offset:256
	v_mad_i64_i32 v[72:73], s[14:15], v72, s44, v[150:151]
	s_nop 0
	v_lshl_add_u64 v[96:97], v[88:89], 0, v[152:153]
	v_cvt_pk_bf16_f32 v35, v26, v27
	global_store_dwordx4 v[48:49], v[32:35], off offset:256
	v_mad_i64_i32 v[8:9], s[14:15], v8, s44, v[150:151]
	s_nop 0
	v_lshl_add_u64 v[32:33], v[24:25], 0, v[152:153]
	v_cvt_pk_bf16_f32 v83, v74, v75
	global_store_dwordx4 v[96:97], v[80:83], off offset:256
	v_cvt_pk_bf16_f32 v19, v10, v11
	global_store_dwordx4 v[32:33], v[16:19], off offset:256
	s_and_b64 vcc, exec, s[4:5]
	v_lshl_add_u64 v[80:81], v[72:73], 0, v[152:153]
	v_lshl_add_u64 v[16:17], v[8:9], 0, v[152:153]
	s_mov_b32 s45, s0
	s_mov_b32 s12, s6
	s_mov_b64 s[16:17], s[10:11]
	s_mov_b64 s[18:19], s[8:9]
	v_cvt_pk_bf16_f32 v124, v124, v125
	v_cvt_pk_bf16_f32 v125, v126, v127
	v_cvt_pk_bf16_f32 v126, v120, v121
	v_cvt_pk_bf16_f32 v127, v122, v123
	global_store_dwordx4 v[156:157], v[124:127], off
	v_cvt_pk_bf16_f32 v104, v116, v117
	v_cvt_pk_bf16_f32 v105, v118, v119
	v_cvt_pk_bf16_f32 v106, v108, v109
	v_cvt_pk_bf16_f32 v107, v110, v111
	global_store_dwordx4 v[112:113], v[104:107], off
	v_cvt_pk_bf16_f32 v88, v100, v101
	v_cvt_pk_bf16_f32 v89, v102, v103
	v_cvt_pk_bf16_f32 v90, v92, v93
	v_cvt_pk_bf16_f32 v91, v94, v95
	global_store_dwordx4 v[96:97], v[88:91], off
	v_cvt_pk_bf16_f32 v72, v84, v85
	v_cvt_pk_bf16_f32 v73, v86, v87
	v_cvt_pk_bf16_f32 v74, v76, v77
	v_cvt_pk_bf16_f32 v75, v78, v79
	global_store_dwordx4 v[80:81], v[72:75], off
	v_cvt_pk_bf16_f32 v71, v66, v67
	global_store_dwordx4 v[80:81], v[68:71], off offset:256
	v_cvt_pk_bf16_f32 v60, v60, v61
	v_cvt_pk_bf16_f32 v61, v62, v63
	v_cvt_pk_bf16_f32 v62, v56, v57
	v_cvt_pk_bf16_f32 v63, v58, v59
	global_store_dwordx4 v[64:65], v[60:63], off
	v_cvt_pk_bf16_f32 v40, v52, v53
	v_cvt_pk_bf16_f32 v41, v54, v55
	v_cvt_pk_bf16_f32 v42, v44, v45
	v_cvt_pk_bf16_f32 v43, v46, v47
	global_store_dwordx4 v[48:49], v[40:43], off
	v_cvt_pk_bf16_f32 v24, v36, v37
	v_cvt_pk_bf16_f32 v25, v38, v39
	v_cvt_pk_bf16_f32 v26, v28, v29
	v_cvt_pk_bf16_f32 v27, v30, v31
	global_store_dwordx4 v[32:33], v[24:27], off
	v_cvt_pk_bf16_f32 v8, v20, v21
	v_cvt_pk_bf16_f32 v9, v22, v23
	v_cvt_pk_bf16_f32 v10, v12, v13
	v_cvt_pk_bf16_f32 v11, v14, v15
	global_store_dwordx4 v[16:17], v[8:11], off
	v_cvt_pk_bf16_f32 v4, v4, v5
	v_cvt_pk_bf16_f32 v5, v6, v7
	v_cvt_pk_bf16_f32 v6, v0, v1
	v_cvt_pk_bf16_f32 v7, v2, v3
	global_store_dwordx4 v[16:17], v[4:7], off offset:256
	s_cbranch_vccnz .LBB0_566

; #define PG8_STAGE(bufoff, gbase, voff) do { _Pragma("unroll") for (int _i = 0; _i < 2; ++_i) \
;         __builtin_amdgcn_global_load_lds((const unsigned*)((const char*)(gbase) + (voff)[_i]), (LAS unsigned*)(lds + (bufoff) + ldsw + _i * 8192), 16, 0, 0); } while (0)
; #define PG8_LDA(dst, b, h) do { _Pragma("unroll") for (int m = 0; m < 4; ++m) _Pragma("unroll") for (int k = 0; k < 2; ++k) dst[m][k] = *(const LAS bf16x8*)(lds + PG8_SA(b, h) + aoff + m * 2048 + k * 1024); } while (0)
; #define PG8_LDB(dst, b, h) do { _Pragma("unroll") for (int n = 0; n < 2; ++n) _Pragma("unroll") for (int k = 0; k < 2; ++k) dst[n][k] = *(const LAS bf16x8*)(lds + PG8_SB(b, h) + boff + n * 2048 + k * 1024); } while (0)
; #define PG8_MMA(ai, bj, At, Bt) do { __builtin_amdgcn_s_setprio(1); _Pragma("unroll") for (int m = 0; m < 4; ++m) _Pragma("unroll") for (int n = 0; n < 2; ++n) _Pragma("unroll") for (int k = 0; k < 2; ++k) \
;         acc[ai][bj][m][n] = __builtin_amdgcn_mfma_f32_16x16x32_bf16(Bt[n][k], At[m][k], acc[ai][bj][m][n], 0, 0, 0); __builtin_amdgcn_s_setprio(0); } while (0)
; #define PG8_WAIT_L(n) asm volatile("s_waitcnt lgkmcnt(" #n ")" ::: "memory")
; #define PG8_BAR __builtin_amdgcn_s_barrier()
; #define PG8_SCHED __builtin_amdgcn_sched_barrier(0)
; template <class Epi>
; __device__ __forceinline__ void gemm_phase(LAS unsigned char* lds, const Gemm g, const StaticOrder& S, const Epi& E) {
;     ...
;         for (int t = 0; t < nt; t += 2) {
;             const bool last = (t == nt - 2);
;             const char* a1 = cA + (size_t)(t + 1) * kstepA;
;             const char* a2 = last ? nA : cA + (size_t)(t + 2) * kstepA; const char* b2 = last ? nB : cB + (size_t)(t + 2) * kstepB;
;             const char* a3 = a2 + kstepA; const char* b3 = b2 + kstepB;
;             PG8_LDB(B0, 0, 0); PG8_SCHED; PG8_LDA(At, 0, 0); PG8_STAGE(PG8_SA(1, 1), a1 + hstep, voffA);
;             PG8_WAIT_L(8); PG8_BAR; PG8_WAIT_L(0); PG8_MMA(0, 0, At, B0); PG8_BAR; PG8_SCHED;
;     ...
; #pragma unroll
;         for (int a = 0; a < 2; ++a)
; #pragma unroll
;             for (int b = 0; b < 2; ++b)
; #pragma unroll
;                 for (int m = 0; m < 4; ++m)
; #pragma unroll
;                     for (int n = 0; n < 2; ++n) acc[a][b][m][n] = (f32x4){0.f, 0.f, 0.f, 0.f};
;         cur = nxt; cA = nA; cB = nB; ++ui;
.LBB0_562:
	s_ashr_i32 s7, s6, 31
	v_cmp_lt_i64_e32 vcc, s[8:9], v[146:147]
	s_lshl_b64 s[8:9], s[6:7], 15
	s_add_u32 s8, s88, s8
	s_addc_u32 s9, s89, s9
	s_and_b64 s[10:11], vcc, exec
	s_cselect_b32 s7, s9, s19
	s_cselect_b32 s48, s8, s18
	s_ashr_i32 s1, s0, 31
	s_lshl_b64 s[10:11], s[0:1], 15
	s_add_u32 s10, s27, s10
	s_addc_u32 s11, s28, s11
	s_and_b64 s[14:15], vcc, exec
	s_cselect_b32 s15, s11, s17
	s_cselect_b32 s14, s10, s16
	s_add_u32 s16, s16, 0x140000
	s_addc_u32 s17, s17, 0
	s_add_u32 s18, s18, 0x404000
	v_mov_b32_e32 v0, 0
	s_addc_u32 s19, s19, 0
	s_mov_b32 s1, -2
	v_mov_b32_e32 v1, v0
	v_mov_b32_e32 v2, v0
	v_mov_b32_e32 v3, v0
	v_mov_b32_e32 v4, v0
	v_mov_b32_e32 v5, v0
	v_mov_b32_e32 v6, v0
	v_mov_b32_e32 v7, v0
	v_mov_b32_e32 v8, v0
	v_mov_b32_e32 v9, v0
	v_mov_b32_e32 v10, v0
	v_mov_b32_e32 v11, v0
	v_mov_b32_e32 v16, v0
	v_mov_b32_e32 v17, v0
	v_mov_b32_e32 v18, v0
	v_mov_b32_e32 v19, v0
	v_mov_b32_e32 v24, v0
	v_mov_b32_e32 v25, v0
	v_mov_b32_e32 v26, v0
	v_mov_b32_e32 v27, v0
	v_mov_b32_e32 v32, v0
	v_mov_b32_e32 v33, v0
	v_mov_b32_e32 v34, v0
	v_mov_b32_e32 v35, v0
	v_mov_b32_e32 v40, v0
	v_mov_b32_e32 v41, v0
	v_mov_b32_e32 v42, v0
	v_mov_b32_e32 v43, v0
	v_mov_b32_e32 v48, v0
	v_mov_b32_e32 v49, v0
	v_mov_b32_e32 v50, v0
	v_mov_b32_e32 v51, v0
	v_mov_b32_e32 v12, v0
	v_mov_b32_e32 v13, v0
	v_mov_b32_e32 v14, v0
	v_mov_b32_e32 v15, v0
	v_mov_b32_e32 v20, v0
	v_mov_b32_e32 v21, v0
	v_mov_b32_e32 v22, v0
	v_mov_b32_e32 v23, v0
	v_mov_b32_e32 v28, v0
	v_mov_b32_e32 v29, v0
	v_mov_b32_e32 v30, v0
	v_mov_b32_e32 v31, v0
	v_mov_b32_e32 v36, v0
	v_mov_b32_e32 v37, v0
	v_mov_b32_e32 v38, v0
	v_mov_b32_e32 v39, v0
	v_mov_b32_e32 v44, v0
	v_mov_b32_e32 v45, v0
	v_mov_b32_e32 v46, v0
	v_mov_b32_e32 v47, v0
	v_mov_b32_e32 v52, v0
	v_mov_b32_e32 v53, v0
	v_mov_b32_e32 v54, v0
	v_mov_b32_e32 v55, v0
	v_mov_b32_e32 v56, v0
	v_mov_b32_e32 v57, v0
	v_mov_b32_e32 v58, v0
	v_mov_b32_e32 v59, v0
	v_mov_b32_e32 v60, v0
	v_mov_b32_e32 v61, v0
	v_mov_b32_e32 v62, v0
	v_mov_b32_e32 v63, v0
	v_mov_b32_e32 v64, v0
	v_mov_b32_e32 v65, v0
	v_mov_b32_e32 v66, v0
	v_mov_b32_e32 v67, v0
	v_mov_b32_e32 v68, v0
	v_mov_b32_e32 v69, v0
	v_mov_b32_e32 v70, v0
	v_mov_b32_e32 v71, v0
	v_mov_b32_e32 v72, v0
	v_mov_b32_e32 v73, v0
	v_mov_b32_e32 v74, v0
	v_mov_b32_e32 v75, v0
	v_mov_b32_e32 v80, v0
	v_mov_b32_e32 v81, v0
	v_mov_b32_e32 v82, v0
	v_mov_b32_e32 v83, v0
	v_mov_b32_e32 v88, v0
	v_mov_b32_e32 v89, v0
	v_mov_b32_e32 v90, v0
	v_mov_b32_e32 v91, v0
	v_mov_b32_e32 v96, v0
	v_mov_b32_e32 v97, v0
	v_mov_b32_e32 v98, v0
	v_mov_b32_e32 v99, v0
	v_mov_b32_e32 v104, v0
	v_mov_b32_e32 v105, v0
	v_mov_b32_e32 v106, v0
	v_mov_b32_e32 v107, v0
	v_mov_b32_e32 v112, v0
	v_mov_b32_e32 v113, v0
	v_mov_b32_e32 v114, v0
	v_mov_b32_e32 v115, v0
	v_mov_b32_e32 v76, v0
	v_mov_b32_e32 v77, v0
	v_mov_b32_e32 v78, v0
	v_mov_b32_e32 v79, v0
	v_mov_b32_e32 v84, v0
	v_mov_b32_e32 v85, v0
	v_mov_b32_e32 v86, v0
	v_mov_b32_e32 v87, v0
	v_mov_b32_e32 v92, v0
	v_mov_b32_e32 v93, v0
	v_mov_b32_e32 v94, v0
	v_mov_b32_e32 v95, v0
	v_mov_b32_e32 v100, v0
	v_mov_b32_e32 v101, v0
	v_mov_b32_e32 v102, v0
	v_mov_b32_e32 v103, v0
	v_mov_b32_e32 v108, v0
	v_mov_b32_e32 v109, v0
	v_mov_b32_e32 v110, v0
	v_mov_b32_e32 v111, v0
	v_mov_b32_e32 v116, v0
	v_mov_b32_e32 v117, v0
	v_mov_b32_e32 v118, v0
	v_mov_b32_e32 v119, v0
	v_mov_b32_e32 v120, v0
	v_mov_b32_e32 v121, v0
	v_mov_b32_e32 v122, v0
	v_mov_b32_e32 v123, v0
	v_mov_b32_e32 v124, v0
	v_mov_b32_e32 v125, v0
	v_mov_b32_e32 v126, v0
	v_mov_b32_e32 v127, v0
	s_branch .LBB0_564
.LBB0_563:
	v_add_u32_e32 v164, s42, v133
	ds_read_b128 v[150:153], v164
	ds_read_b128 v[156:159], v164 offset:1024
	ds_read_b128 v[160:163], v164 offset:2048
	ds_read_b128 v[164:167], v164 offset:3072
	s_add_u32 s24, s18, 0x3fc000
	s_addc_u32 s25, s19, 0
	s_and_b64 s[22:23], exec, s[22:23]
	s_cselect_b32 s24, s48, s24
	s_cselect_b32 s25, s7, s25
	s_add_u32 s22, s24, 0x400000
	s_addc_u32 s23, s25, 0
	v_lshl_add_u64 v[206:207], s[18:19], 0, v[142:143]
	s_add_i32 m0, s13, 0xc000
	ds_read_b128 v[168:171], v155
	ds_read_b128 v[172:175], v155 offset:1024
	ds_read_b128 v[176:179], v155 offset:2048
	ds_read_b128 v[186:189], v155 offset:3072
	ds_read_b128 v[190:193], v155 offset:4096
	ds_read_b128 v[194:197], v155 offset:5120
	ds_read_b128 v[198:201], v155 offset:6144
	ds_read_b128 v[202:205], v155 offset:7168
	global_load_lds_dwordx4 v[206:207], off
	v_lshl_add_u64 v[206:207], s[18:19], 0, v[144:145]
	s_add_i32 m0, s13, 0xe000
	s_nop 0
	global_load_lds_dwordx4 v[206:207], off
	v_add_u32_e32 v253, 0x14000, v133
	ds_read_b128 v[206:209], v253
	ds_read_b128 v[210:213], v253 offset:1024
	ds_read_b128 v[214:217], v253 offset:2048
	ds_read_b128 v[218:221], v253 offset:3072
	s_waitcnt lgkmcnt(0)
	s_waitcnt vmcnt(8)
	s_barrier
; #define PG8_STAGE(bufoff, gbase, voff) do { _Pragma("unroll") for (int _i = 0; _i < 2; ++_i) \
;         __builtin_amdgcn_global_load_lds((const unsigned*)((const char*)(gbase) + (voff)[_i]), (LAS unsigned*)(lds + (bufoff) + ldsw + _i * 8192), 16, 0, 0); } while (0)
; #define PG8_LDA(dst, b, h) do { _Pragma("unroll") for (int m = 0; m < 4; ++m) _Pragma("unroll") for (int k = 0; k < 2; ++k) dst[m][k] = *(const LAS bf16x8*)(lds + PG8_SA(b, h) + aoff + m * 2048 + k * 1024); } while (0)
; #define PG8_LDB(dst, b, h) do { _Pragma("unroll") for (int n = 0; n < 2; ++n) _Pragma("unroll") for (int k = 0; k < 2; ++k) dst[n][k] = *(const LAS bf16x8*)(lds + PG8_SB(b, h) + boff + n * 2048 + k * 1024); } while (0)
; #define PG8_MMA(ai, bj, At, Bt) do { __builtin_amdgcn_s_setprio(1); _Pragma("unroll") for (int m = 0; m < 4; ++m) _Pragma("unroll") for (int n = 0; n < 2; ++n) _Pragma("unroll") for (int k = 0; k < 2; ++k) \
;         acc[ai][bj][m][n] = __builtin_amdgcn_mfma_f32_16x16x32_bf16(Bt[n][k], At[m][k], acc[ai][bj][m][n], 0, 0, 0); __builtin_amdgcn_s_setprio(0); } while (0)
; #define PG8_WAIT_V(n) asm volatile("s_waitcnt vmcnt(" #n ")" ::: "memory")
; #define PG8_WAIT_L(n) asm volatile("s_waitcnt lgkmcnt(" #n ")" ::: "memory")
; template <class Epi>
; __device__ __forceinline__ void gemm_phase(LAS unsigned char* lds, const Gemm g, const StaticOrder& S, const Epi& E) {
;     ...
;             PG8_WAIT_L(8); PG8_BAR; PG8_WAIT_L(0); PG8_MMA(0, 0, At, B0); PG8_BAR; PG8_SCHED;
;             PG8_LDB(B1, 0, 1); PG8_STAGE(PG8_SB(0, 0), b2, voffB);
;             PG8_BAR; PG8_WAIT_L(0); PG8_MMA(0, 1, At, B1); PG8_BAR;
;             PG8_LDA(At, 0, 1); PG8_STAGE(PG8_SA(0, 0), a2, voffA);
;             PG8_BAR; PG8_WAIT_L(0); PG8_MMA(1, 0, At, B0); PG8_BAR; PG8_SCHED;
;             PG8_STAGE(PG8_SB(0, 1), b2 + hstep, voffB);
;             PG8_WAIT_V(6); PG8_BAR; PG8_MMA(1, 1, At, B1); PG8_BAR;
;             PG8_LDB(B0, 1, 0); PG8_SCHED; PG8_LDA(At, 1, 0); PG8_STAGE(PG8_SA(0, 1), a2 + hstep, voffA);
;             PG8_WAIT_L(8); PG8_BAR; PG8_WAIT_L(0); PG8_MMA(0, 0, At, B0); PG8_BAR; PG8_SCHED;
;             PG8_LDB(B1, 1, 1); PG8_STAGE(PG8_SB(1, 0), b3, voffB);
;             PG8_BAR; PG8_WAIT_L(0); PG8_MMA(0, 1, At, B1); PG8_BAR;
;             PG8_LDA(At, 1, 1); PG8_STAGE(PG8_SA(1, 0), a3, voffA);
;             PG8_BAR; PG8_WAIT_L(0); PG8_MMA(1, 0, At, B0); PG8_BAR; PG8_SCHED;
	s_setprio 1
	v_mfma_f32_16x16x32_bf16 v[124:127], v[150:153], v[168:171], v[124:127]
	v_mfma_f32_16x16x32_bf16 v[120:123], v[160:163], v[168:171], v[120:123]
	v_mfma_f32_16x16x32_bf16 v[116:119], v[150:153], v[176:179], v[116:119]
	v_mfma_f32_16x16x32_bf16 v[108:111], v[160:163], v[176:179], v[108:111]
	v_mfma_f32_16x16x32_bf16 v[100:103], v[150:153], v[190:193], v[100:103]
	v_mfma_f32_16x16x32_bf16 v[92:95], v[160:163], v[190:193], v[92:95]
	v_mfma_f32_16x16x32_bf16 v[84:87], v[150:153], v[198:201], v[84:87]
	v_mfma_f32_16x16x32_bf16 v[76:79], v[160:163], v[198:201], v[76:79]
	v_mfma_f32_16x16x32_bf16 v[124:127], v[156:159], v[172:175], v[124:127]
	v_mfma_f32_16x16x32_bf16 v[120:123], v[164:167], v[172:175], v[120:123]
	v_mfma_f32_16x16x32_bf16 v[116:119], v[156:159], v[186:189], v[116:119]
	v_mfma_f32_16x16x32_bf16 v[108:111], v[164:167], v[186:189], v[108:111]
	v_mfma_f32_16x16x32_bf16 v[100:103], v[156:159], v[194:197], v[100:103]
	v_mfma_f32_16x16x32_bf16 v[92:95], v[164:167], v[194:197], v[92:95]
	v_mfma_f32_16x16x32_bf16 v[84:87], v[156:159], v[202:205], v[84:87]
	v_mfma_f32_16x16x32_bf16 v[76:79], v[164:167], v[202:205], v[76:79]
	v_mfma_f32_16x16x32_bf16 v[112:115], v[206:209], v[168:171], v[112:115]
	v_mfma_f32_16x16x32_bf16 v[104:107], v[214:217], v[168:171], v[104:107]
	v_mfma_f32_16x16x32_bf16 v[96:99], v[206:209], v[176:179], v[96:99]
	v_mfma_f32_16x16x32_bf16 v[88:91], v[214:217], v[176:179], v[88:91]
	v_mfma_f32_16x16x32_bf16 v[80:83], v[206:209], v[190:193], v[80:83]
	v_mfma_f32_16x16x32_bf16 v[72:75], v[214:217], v[190:193], v[72:75]
	v_mfma_f32_16x16x32_bf16 v[68:71], v[206:209], v[198:201], v[68:71]
	v_mfma_f32_16x16x32_bf16 v[64:67], v[214:217], v[198:201], v[64:67]
	v_mfma_f32_16x16x32_bf16 v[112:115], v[210:213], v[172:175], v[112:115]
	v_mfma_f32_16x16x32_bf16 v[104:107], v[218:221], v[172:175], v[104:107]
	v_mfma_f32_16x16x32_bf16 v[96:99], v[210:213], v[186:189], v[96:99]
	v_mfma_f32_16x16x32_bf16 v[88:91], v[218:221], v[186:189], v[88:91]
	v_mfma_f32_16x16x32_bf16 v[80:83], v[210:213], v[194:197], v[80:83]
	v_mfma_f32_16x16x32_bf16 v[72:75], v[218:221], v[194:197], v[72:75]
	v_mfma_f32_16x16x32_bf16 v[68:71], v[210:213], v[202:205], v[68:71]
	v_mfma_f32_16x16x32_bf16 v[64:67], v[218:221], v[202:205], v[64:67]
	s_setprio 0
	s_barrier
	s_add_i32 s49, s42, s29
	v_add_u32_e32 v185, s43, v133
	v_lshl_add_u64 v[222:223], s[20:21], 0, v[138:139]
	s_mov_b32 m0, s49
	s_nop 0
	global_load_lds_dwordx4 v[222:223], off
	v_lshl_add_u64 v[222:223], s[20:21], 0, v[134:135]
	s_add_i32 m0, s49, 0x2000
	s_nop 0
	global_load_lds_dwordx4 v[222:223], off
	s_mov_b32 m0, s13
	v_lshl_add_u64 v[222:223], s[24:25], 0, v[140:141]
	ds_read_b128 v[168:171], v155 offset:16384
	ds_read_b128 v[172:175], v155 offset:17408
	ds_read_b128 v[176:179], v155 offset:18432
	ds_read_b128 v[186:189], v155 offset:19456
	ds_read_b128 v[190:193], v155 offset:20480
	ds_read_b128 v[194:197], v155 offset:21504
	ds_read_b128 v[198:201], v155 offset:22528
	ds_read_b128 v[202:205], v155 offset:23552
	global_load_lds_dwordx4 v[222:223], off
	v_lshl_add_u64 v[222:223], s[24:25], 0, v[136:137]
	s_mov_b32 m0, s34
	s_nop 0
	global_load_lds_dwordx4 v[222:223], off
	s_add_u32 s50, s20, 0x4000
	s_addc_u32 s51, s21, 0
	s_add_i32 s49, s43, s29
	v_lshl_add_u64 v[254:255], s[50:51], 0, v[138:139]
	s_mov_b32 m0, s49
	s_nop 0
	global_load_lds_dwordx4 v[254:255], off
	v_lshl_add_u64 v[254:255], s[50:51], 0, v[134:135]
	s_add_i32 m0, s49, 0x2000
	s_nop 0
	global_load_lds_dwordx4 v[254:255], off
	s_waitcnt lgkmcnt(0)
	s_waitcnt vmcnt(8)
	s_barrier
	s_setprio 1
	v_mfma_f32_16x16x32_bf16 v[60:63], v[150:153], v[168:171], v[60:63]
	v_mfma_f32_16x16x32_bf16 v[56:59], v[160:163], v[168:171], v[56:59]
	v_mfma_f32_16x16x32_bf16 v[52:55], v[150:153], v[176:179], v[52:55]
	v_mfma_f32_16x16x32_bf16 v[44:47], v[160:163], v[176:179], v[44:47]
	v_mfma_f32_16x16x32_bf16 v[36:39], v[150:153], v[190:193], v[36:39]
	v_mfma_f32_16x16x32_bf16 v[28:31], v[160:163], v[190:193], v[28:31]
	v_mfma_f32_16x16x32_bf16 v[20:23], v[150:153], v[198:201], v[20:23]
	v_mfma_f32_16x16x32_bf16 v[12:15], v[160:163], v[198:201], v[12:15]
	v_mfma_f32_16x16x32_bf16 v[60:63], v[156:159], v[172:175], v[60:63]
	v_mfma_f32_16x16x32_bf16 v[56:59], v[164:167], v[172:175], v[56:59]
	v_mfma_f32_16x16x32_bf16 v[52:55], v[156:159], v[186:189], v[52:55]
	v_mfma_f32_16x16x32_bf16 v[44:47], v[164:167], v[186:189], v[44:47]
	v_mfma_f32_16x16x32_bf16 v[36:39], v[156:159], v[194:197], v[36:39]
	v_mfma_f32_16x16x32_bf16 v[28:31], v[164:167], v[194:197], v[28:31]
	v_mfma_f32_16x16x32_bf16 v[20:23], v[156:159], v[202:205], v[20:23]
	v_mfma_f32_16x16x32_bf16 v[12:15], v[164:167], v[202:205], v[12:15]
	v_mfma_f32_16x16x32_bf16 v[48:51], v[206:209], v[168:171], v[48:51]
	v_mfma_f32_16x16x32_bf16 v[40:43], v[214:217], v[168:171], v[40:43]
	v_mfma_f32_16x16x32_bf16 v[32:35], v[206:209], v[176:179], v[32:35]
	v_mfma_f32_16x16x32_bf16 v[24:27], v[214:217], v[176:179], v[24:27]
	v_mfma_f32_16x16x32_bf16 v[16:19], v[206:209], v[190:193], v[16:19]
	v_mfma_f32_16x16x32_bf16 v[8:11], v[214:217], v[190:193], v[8:11]
	v_mfma_f32_16x16x32_bf16 v[4:7], v[206:209], v[198:201], v[4:7]
	v_mfma_f32_16x16x32_bf16 v[0:3], v[214:217], v[198:201], v[0:3]
	v_mfma_f32_16x16x32_bf16 v[48:51], v[210:213], v[172:175], v[48:51]
	v_mfma_f32_16x16x32_bf16 v[40:43], v[218:221], v[172:175], v[40:43]
	v_mfma_f32_16x16x32_bf16 v[32:35], v[210:213], v[186:189], v[32:35]
	v_mfma_f32_16x16x32_bf16 v[24:27], v[218:221], v[186:189], v[24:27]
	v_mfma_f32_16x16x32_bf16 v[16:19], v[210:213], v[194:197], v[16:19]
	v_mfma_f32_16x16x32_bf16 v[8:11], v[218:221], v[194:197], v[8:11]
	v_mfma_f32_16x16x32_bf16 v[4:7], v[210:213], v[202:205], v[4:7]
	v_mfma_f32_16x16x32_bf16 v[0:3], v[218:221], v[202:205], v[0:3]
	s_setprio 0
	s_add_i32 s49, 0, 0x18000
	v_add_u32_e32 v164, s49, v133
	s_barrier
; #define PG8_STAGE(bufoff, gbase, voff) do { _Pragma("unroll") for (int _i = 0; _i < 2; ++_i) \
;         __builtin_amdgcn_global_load_lds((const unsigned*)((const char*)(gbase) + (voff)[_i]), (LAS unsigned*)(lds + (bufoff) + ldsw + _i * 8192), 16, 0, 0); } while (0)
; #define PG8_LDA(dst, b, h) do { _Pragma("unroll") for (int m = 0; m < 4; ++m) _Pragma("unroll") for (int k = 0; k < 2; ++k) dst[m][k] = *(const LAS bf16x8*)(lds + PG8_SA(b, h) + aoff + m * 2048 + k * 1024); } while (0)
; #define PG8_LDB(dst, b, h) do { _Pragma("unroll") for (int n = 0; n < 2; ++n) _Pragma("unroll") for (int k = 0; k < 2; ++k) dst[n][k] = *(const LAS bf16x8*)(lds + PG8_SB(b, h) + boff + n * 2048 + k * 1024); } while (0)
; #define PG8_MMA(ai, bj, At, Bt) do { __builtin_amdgcn_s_setprio(1); _Pragma("unroll") for (int m = 0; m < 4; ++m) _Pragma("unroll") for (int n = 0; n < 2; ++n) _Pragma("unroll") for (int k = 0; k < 2; ++k) \
;         acc[ai][bj][m][n] = __builtin_amdgcn_mfma_f32_16x16x32_bf16(Bt[n][k], At[m][k], acc[ai][bj][m][n], 0, 0, 0); __builtin_amdgcn_s_setprio(0); } while (0)
; #define PG8_WAIT_V(n) asm volatile("s_waitcnt vmcnt(" #n ")" ::: "memory")
; #define PG8_WAIT_L(n) asm volatile("s_waitcnt lgkmcnt(" #n ")" ::: "memory")
; #define PG8_BAR __builtin_amdgcn_s_barrier()
; #define PG8_SCHED __builtin_amdgcn_sched_barrier(0)
; template <class Epi>
; __device__ __forceinline__ void gemm_phase(LAS unsigned char* lds, const Gemm g, const StaticOrder& S, const Epi& E) {
;     ...
;             PG8_WAIT_V(6); PG8_BAR; PG8_MMA(1, 1, At, B1); PG8_BAR;
;             PG8_LDB(B0, 1, 0); PG8_SCHED; PG8_LDA(At, 1, 0); PG8_STAGE(PG8_SA(0, 1), a2 + hstep, voffA);
;             PG8_WAIT_L(8); PG8_BAR; PG8_WAIT_L(0); PG8_MMA(0, 0, At, B0); PG8_BAR; PG8_SCHED;
;             PG8_LDB(B1, 1, 1); PG8_STAGE(PG8_SB(1, 0), b3, voffB);
;             PG8_BAR; PG8_WAIT_L(0); PG8_MMA(0, 1, At, B1); PG8_BAR;
;             PG8_LDA(At, 1, 1); PG8_STAGE(PG8_SA(1, 0), a3, voffA);
;             PG8_BAR; PG8_WAIT_L(0); PG8_MMA(1, 0, At, B0); PG8_BAR; PG8_SCHED;
	ds_read_b128 v[150:153], v164
	ds_read_b128 v[156:159], v164 offset:1024
	ds_read_b128 v[160:163], v164 offset:2048
	ds_read_b128 v[164:167], v164 offset:3072
	s_add_u32 s24, s24, 0x4000
	s_addc_u32 s25, s25, 0
	s_mov_b32 m0, s35
	v_lshl_add_u64 v[206:207], s[24:25], 0, v[140:141]
	ds_read_b128 v[168:171], v155 offset:32768
	ds_read_b128 v[172:175], v155 offset:33792
	ds_read_b128 v[176:179], v155 offset:34816
	ds_read_b128 v[186:189], v155 offset:35840
	ds_read_b128 v[190:193], v155 offset:36864
	ds_read_b128 v[194:197], v155 offset:37888
	ds_read_b128 v[198:201], v155 offset:38912
	ds_read_b128 v[202:205], v155 offset:39936
	global_load_lds_dwordx4 v[206:207], off
	v_lshl_add_u64 v[206:207], s[24:25], 0, v[136:137]
	s_mov_b32 m0, s36
	s_nop 0
	global_load_lds_dwordx4 v[206:207], off
	v_add_u32_e32 v253, 0x1c000, v133
	ds_read_b128 v[206:209], v253
	ds_read_b128 v[210:213], v253 offset:1024
	ds_read_b128 v[214:217], v253 offset:2048
	ds_read_b128 v[218:221], v253 offset:3072
	s_waitcnt lgkmcnt(0)
	s_waitcnt vmcnt(8)
	s_barrier
	s_setprio 1
	v_mfma_f32_16x16x32_bf16 v[124:127], v[150:153], v[168:171], v[124:127]
	v_mfma_f32_16x16x32_bf16 v[120:123], v[160:163], v[168:171], v[120:123]
	v_mfma_f32_16x16x32_bf16 v[116:119], v[150:153], v[176:179], v[116:119]
	v_mfma_f32_16x16x32_bf16 v[108:111], v[160:163], v[176:179], v[108:111]
	v_mfma_f32_16x16x32_bf16 v[100:103], v[150:153], v[190:193], v[100:103]
	v_mfma_f32_16x16x32_bf16 v[92:95], v[160:163], v[190:193], v[92:95]
	v_mfma_f32_16x16x32_bf16 v[84:87], v[150:153], v[198:201], v[84:87]
	v_mfma_f32_16x16x32_bf16 v[76:79], v[160:163], v[198:201], v[76:79]
	v_mfma_f32_16x16x32_bf16 v[124:127], v[156:159], v[172:175], v[124:127]
	v_mfma_f32_16x16x32_bf16 v[120:123], v[164:167], v[172:175], v[120:123]
	v_mfma_f32_16x16x32_bf16 v[116:119], v[156:159], v[186:189], v[116:119]
	v_mfma_f32_16x16x32_bf16 v[108:111], v[164:167], v[186:189], v[108:111]
	v_mfma_f32_16x16x32_bf16 v[100:103], v[156:159], v[194:197], v[100:103]
	v_mfma_f32_16x16x32_bf16 v[92:95], v[164:167], v[194:197], v[92:95]
	v_mfma_f32_16x16x32_bf16 v[84:87], v[156:159], v[202:205], v[84:87]
	v_mfma_f32_16x16x32_bf16 v[76:79], v[164:167], v[202:205], v[76:79]
	v_mfma_f32_16x16x32_bf16 v[112:115], v[206:209], v[168:171], v[112:115]
	v_mfma_f32_16x16x32_bf16 v[104:107], v[214:217], v[168:171], v[104:107]
	v_mfma_f32_16x16x32_bf16 v[96:99], v[206:209], v[176:179], v[96:99]
	v_mfma_f32_16x16x32_bf16 v[88:91], v[214:217], v[176:179], v[88:91]
	v_mfma_f32_16x16x32_bf16 v[80:83], v[206:209], v[190:193], v[80:83]
	v_mfma_f32_16x16x32_bf16 v[72:75], v[214:217], v[190:193], v[72:75]
	v_mfma_f32_16x16x32_bf16 v[68:71], v[206:209], v[198:201], v[68:71]
	v_mfma_f32_16x16x32_bf16 v[64:67], v[214:217], v[198:201], v[64:67]
	v_mfma_f32_16x16x32_bf16 v[112:115], v[210:213], v[172:175], v[112:115]
	v_mfma_f32_16x16x32_bf16 v[104:107], v[218:221], v[172:175], v[104:107]
	v_mfma_f32_16x16x32_bf16 v[96:99], v[210:213], v[186:189], v[96:99]
	v_mfma_f32_16x16x32_bf16 v[88:91], v[218:221], v[186:189], v[88:91]
	v_mfma_f32_16x16x32_bf16 v[80:83], v[210:213], v[194:197], v[80:83]
	v_mfma_f32_16x16x32_bf16 v[72:75], v[218:221], v[194:197], v[72:75]
	v_mfma_f32_16x16x32_bf16 v[68:71], v[210:213], v[202:205], v[68:71]
	v_mfma_f32_16x16x32_bf16 v[64:67], v[218:221], v[202:205], v[64:67]
	s_setprio 0
	s_barrier
; #define PG8_STAGE(bufoff, gbase, voff) do { _Pragma("unroll") for (int _i = 0; _i < 2; ++_i) \
;         __builtin_amdgcn_global_load_lds((const unsigned*)((const char*)(gbase) + (voff)[_i]), (LAS unsigned*)(lds + (bufoff) + ldsw + _i * 8192), 16, 0, 0); } while (0)
; #define PG8_LDA(dst, b, h) do { _Pragma("unroll") for (int m = 0; m < 4; ++m) _Pragma("unroll") for (int k = 0; k < 2; ++k) dst[m][k] = *(const LAS bf16x8*)(lds + PG8_SA(b, h) + aoff + m * 2048 + k * 1024); } while (0)
; #define PG8_LDB(dst, b, h) do { _Pragma("unroll") for (int n = 0; n < 2; ++n) _Pragma("unroll") for (int k = 0; k < 2; ++k) dst[n][k] = *(const LAS bf16x8*)(lds + PG8_SB(b, h) + boff + n * 2048 + k * 1024); } while (0)
; #define PG8_MMA(ai, bj, At, Bt) do { __builtin_amdgcn_s_setprio(1); _Pragma("unroll") for (int m = 0; m < 4; ++m) _Pragma("unroll") for (int n = 0; n < 2; ++n) _Pragma("unroll") for (int k = 0; k < 2; ++k) \
;         acc[ai][bj][m][n] = __builtin_amdgcn_mfma_f32_16x16x32_bf16(Bt[n][k], At[m][k], acc[ai][bj][m][n], 0, 0, 0); __builtin_amdgcn_s_setprio(0); } while (0)
; #define PG8_WAIT_V(n) asm volatile("s_waitcnt vmcnt(" #n ")" ::: "memory")
; #define PG8_WAIT_L(n) asm volatile("s_waitcnt lgkmcnt(" #n ")" ::: "memory")
; #define PG8_BAR __builtin_amdgcn_s_barrier()
; #define PG8_SCHED __builtin_amdgcn_sched_barrier(0)
; template <class Epi>
; __device__ __forceinline__ void gemm_phase(LAS unsigned char* lds, const Gemm g, const StaticOrder& S, const Epi& E) {
;     ...
;             PG8_LDB(B1, 1, 1); PG8_STAGE(PG8_SB(1, 0), b3, voffB);
;             PG8_BAR; PG8_WAIT_L(0); PG8_MMA(0, 1, At, B1); PG8_BAR;
;             PG8_LDA(At, 1, 1); PG8_STAGE(PG8_SA(1, 0), a3, voffA);
;             PG8_BAR; PG8_WAIT_L(0); PG8_MMA(1, 0, At, B0); PG8_BAR; PG8_SCHED;
;             PG8_STAGE(PG8_SB(1, 1), b3 + hstep, voffB);
;             PG8_WAIT_V(6); PG8_BAR; PG8_MMA(1, 1, At, B1); PG8_BAR;
;         }
	s_add_i32 s50, 0, 0x1c000
	s_add_u32 s24, s20, 0xa0000
	s_addc_u32 s25, s21, 0
	s_add_i32 s49, s49, s29
	v_add_u32_e32 v185, s50, v133
	v_lshl_add_u64 v[222:223], s[24:25], 0, v[138:139]
	s_mov_b32 m0, s49
	s_nop 0
	global_load_lds_dwordx4 v[222:223], off
	v_lshl_add_u64 v[222:223], s[24:25], 0, v[134:135]
	s_add_i32 m0, s49, 0x2000
	s_nop 0
	global_load_lds_dwordx4 v[222:223], off
	s_mov_b32 m0, s38
	v_lshl_add_u64 v[222:223], s[22:23], 0, v[140:141]
	ds_read_b128 v[168:171], v155 offset:49152
	ds_read_b128 v[172:175], v155 offset:50176
	ds_read_b128 v[176:179], v155 offset:51200
	ds_read_b128 v[186:189], v155 offset:52224
	ds_read_b128 v[190:193], v155 offset:53248
	ds_read_b128 v[194:197], v155 offset:54272
	ds_read_b128 v[198:201], v155 offset:55296
	ds_read_b128 v[202:205], v155 offset:56320
	global_load_lds_dwordx4 v[222:223], off
	v_lshl_add_u64 v[222:223], s[22:23], 0, v[136:137]
	s_mov_b32 m0, s39
	s_nop 0
	global_load_lds_dwordx4 v[222:223], off
	s_add_u32 s20, s20, 0xa4000
	s_addc_u32 s21, s21, 0
	s_add_i32 s22, s50, s29
	v_lshl_add_u64 v[254:255], s[20:21], 0, v[138:139]
	s_mov_b32 m0, s22
	s_nop 0
	global_load_lds_dwordx4 v[254:255], off
	v_lshl_add_u64 v[254:255], s[20:21], 0, v[134:135]
	s_add_i32 m0, s22, 0x2000
	s_nop 0
	global_load_lds_dwordx4 v[254:255], off
	s_waitcnt lgkmcnt(0)
	s_waitcnt vmcnt(8)
	s_barrier
	s_setprio 1
	v_mfma_f32_16x16x32_bf16 v[60:63], v[150:153], v[168:171], v[60:63]
	v_mfma_f32_16x16x32_bf16 v[56:59], v[160:163], v[168:171], v[56:59]
	v_mfma_f32_16x16x32_bf16 v[52:55], v[150:153], v[176:179], v[52:55]
	v_mfma_f32_16x16x32_bf16 v[44:47], v[160:163], v[176:179], v[44:47]
	v_mfma_f32_16x16x32_bf16 v[36:39], v[150:153], v[190:193], v[36:39]
	v_mfma_f32_16x16x32_bf16 v[28:31], v[160:163], v[190:193], v[28:31]
	v_mfma_f32_16x16x32_bf16 v[20:23], v[150:153], v[198:201], v[20:23]
	v_mfma_f32_16x16x32_bf16 v[12:15], v[160:163], v[198:201], v[12:15]
	v_mfma_f32_16x16x32_bf16 v[60:63], v[156:159], v[172:175], v[60:63]
	v_mfma_f32_16x16x32_bf16 v[56:59], v[164:167], v[172:175], v[56:59]
	v_mfma_f32_16x16x32_bf16 v[52:55], v[156:159], v[186:189], v[52:55]
	v_mfma_f32_16x16x32_bf16 v[44:47], v[164:167], v[186:189], v[44:47]
	v_mfma_f32_16x16x32_bf16 v[36:39], v[156:159], v[194:197], v[36:39]
	v_mfma_f32_16x16x32_bf16 v[28:31], v[164:167], v[194:197], v[28:31]
	v_mfma_f32_16x16x32_bf16 v[20:23], v[156:159], v[202:205], v[20:23]
	v_mfma_f32_16x16x32_bf16 v[12:15], v[164:167], v[202:205], v[12:15]
	v_mfma_f32_16x16x32_bf16 v[48:51], v[206:209], v[168:171], v[48:51]
	v_mfma_f32_16x16x32_bf16 v[40:43], v[214:217], v[168:171], v[40:43]
	v_mfma_f32_16x16x32_bf16 v[32:35], v[206:209], v[176:179], v[32:35]
	v_mfma_f32_16x16x32_bf16 v[24:27], v[214:217], v[176:179], v[24:27]
	v_mfma_f32_16x16x32_bf16 v[16:19], v[206:209], v[190:193], v[16:19]
	v_mfma_f32_16x16x32_bf16 v[8:11], v[214:217], v[190:193], v[8:11]
	v_mfma_f32_16x16x32_bf16 v[4:7], v[206:209], v[198:201], v[4:7]
	v_mfma_f32_16x16x32_bf16 v[0:3], v[214:217], v[198:201], v[0:3]
	v_mfma_f32_16x16x32_bf16 v[48:51], v[210:213], v[172:175], v[48:51]
	v_mfma_f32_16x16x32_bf16 v[40:43], v[218:221], v[172:175], v[40:43]
	v_mfma_f32_16x16x32_bf16 v[32:35], v[210:213], v[186:189], v[32:35]
	v_mfma_f32_16x16x32_bf16 v[24:27], v[218:221], v[186:189], v[24:27]
	v_mfma_f32_16x16x32_bf16 v[16:19], v[210:213], v[194:197], v[16:19]
	v_mfma_f32_16x16x32_bf16 v[8:11], v[218:221], v[194:197], v[8:11]
	v_mfma_f32_16x16x32_bf16 v[4:7], v[210:213], v[202:205], v[4:7]
	v_mfma_f32_16x16x32_bf16 v[0:3], v[218:221], v[202:205], v[0:3]
	s_setprio 0
	s_add_i32 s1, s1, 2
	s_add_u32 s16, s16, 0x140000
	s_addc_u32 s17, s17, 0
	s_add_u32 s18, s18, 0x800000
	s_addc_u32 s19, s19, 0
	s_cmp_gt_u32 s1, 29
	s_barrier
	s_cbranch_scc1 .LBB0_559

; #define PG8_STAGE(bufoff, gbase, voff) do { _Pragma("unroll") for (int _i = 0; _i < 2; ++_i) \
;         __builtin_amdgcn_global_load_lds((const unsigned*)((const char*)(gbase) + (voff)[_i]), (LAS unsigned*)(lds + (bufoff) + ldsw + _i * 8192), 16, 0, 0); } while (0)
; #define PG8_WAIT_V(n) asm volatile("s_waitcnt vmcnt(" #n ")" ::: "memory")
; #define PG8_BAR __builtin_amdgcn_s_barrier()
; template <class Epi>
; __device__ __forceinline__ void gemm_phase(LAS unsigned char* lds, const Gemm g, const StaticOrder& S, const Epi& E) {
;     ...
;     for (int i = 0; i < 2; ++i) { int R, C; stage_rc(tid * 16 + i * 8192, R, C); const int Rb = Epi::PERM ? ((R & ~31) + perm32(R & 31)) : R;
;         voffA[i] = (unsigned)(R * BK + C) * 2u; voffB[i] = (unsigned)(Rb * BK + C) * 2u; }
;     const size_t kstepA = (size_t)g.M * BK * 2, kstepB = (size_t)g.N * BK * 2;
;     const size_t hstep = (size_t)HALF * BK * 2;
;     const size_t tstep = 2 * hstep;
;     const unsigned ldsw = (unsigned)wid * 1024u;
;     const int aoff = lds_byte(wr * 64 + fr, fq * 8), boff = lds_byte(wc * 32 + fr, fq * 8);
;     ...
;     Unit cur, nxt; int ui = 0;
;     if (!S.next(0, cur)) return;
;     f32x4 acc[2][2][4][2];
; #pragma unroll
;     for (int a = 0; a < 2; ++a)
; #pragma unroll
;         for (int b = 0; b < 2; ++b)
; #pragma unroll
;             for (int m = 0; m < 4; ++m)
; #pragma unroll
;                 for (int n = 0; n < 2; ++n) acc[a][b][m][n] = (f32x4){0.f, 0.f, 0.f, 0.f};
;     bf16x8 At[4][2], B0[2][2], B1[2][2];
;     const char* cA = (const char*)g.A + (size_t)cur.pm * tstep; const char* cB = (const char*)g.Bt + (size_t)cur.pn * tstep;
;     PG8_STAGE(PG8_SB(0, 0), cB, voffB); PG8_STAGE(PG8_SA(0, 0), cA, voffA); PG8_STAGE(PG8_SB(0, 1), cB + hstep, voffB); PG8_STAGE(PG8_SA(0, 1), cA + hstep, voffA);
;     if (wr == 1) PG8_BAR;
;     PG8_WAIT_V(4); PG8_BAR;
;     PG8_STAGE(PG8_SB(1, 0), cB + kstepB, voffB); PG8_STAGE(PG8_SA(1, 0), cA + kstepA, voffA); PG8_STAGE(PG8_SB(1, 1), cB + hstep + kstepB, voffB);
;     PG8_WAIT_V(6); PG8_BAR;
.LBB0_754:
	s_lshl_b32 s1, s1, 5
	s_and_b32 s1, s1, 0x60
	s_lshl_b32 s7, s6, 13
	s_lshl_b32 s10, s1, 7
	s_add_u32 s8, s24, 0x40000
	s_addc_u32 s9, s25, 0
	s_add_i32 m0, s23, 0x18000
	v_lshl_add_u64 v[8:9], s[8:9], 0, v[136:137]
	s_waitcnt vmcnt(2)
	s_barrier
	global_load_lds_dwordx4 v[8:9], off
	s_add_i32 m0, s23, 0x1a000
	v_lshl_add_u64 v[8:9], s[8:9], 0, v[140:141]
	s_add_u32 s8, s26, 0x400000
	s_addc_u32 s9, s27, 0
	s_add_i32 s43, s23, 0x8000
	global_load_lds_dwordx4 v[8:9], off
	v_lshl_add_u64 v[8:9], s[8:9], 0, v[134:135]
	s_mov_b32 m0, s43
	s_add_i32 s44, s23, 0xa000
	global_load_lds_dwordx4 v[8:9], off
	v_lshl_add_u64 v[8:9], s[8:9], 0, v[138:139]
	s_add_u32 s8, s24, 0x44000
	s_mov_b32 m0, s44
	s_addc_u32 s9, s25, 0
	global_load_lds_dwordx4 v[8:9], off
	s_add_i32 m0, s23, 0x1c000
	v_lshl_add_u64 v[8:9], s[8:9], 0, v[136:137]
	global_load_lds_dwordx4 v[8:9], off
	v_lshl_add_u64 v[8:9], s[8:9], 0, v[140:141]
	s_add_i32 m0, s23, 0x1e000
	v_and_b32_e32 v7, 15, v0
	global_load_lds_dwordx4 v[8:9], off
	v_lshrrev_b32_e32 v8, 1, v0
	v_and_b32_e32 v8, 24, v8
	v_lshlrev_b32_e32 v9, 1, v8
	v_lshlrev_b32_e32 v0, 2, v0
	v_lshl_or_b32 v131, s6, 6, v7
	v_lshl_or_b32 v7, v7, 6, v9
	v_and_b32_e32 v0, 32, v0
	v_bitop3_b32 v9, v7, s7, v0 bitop3:0xde
	v_bitop3_b32 v133, v7, s10, v0 bitop3:0xde
	v_lshlrev_b32_e32 v0, 10, v1
	v_and_b32_e32 v0, 0xfffff800, v0
	v_lshl_add_u32 v0, v2, 7, v0
	v_and_b32_e32 v1, 1, v1
	v_lshl_or_b32 v0, v1, 6, v0
	v_lshl_add_u32 v142, v3, 1, v0
	v_lshlrev_b32_e32 v0, 10, v4
	v_and_b32_e32 v0, 0xfffff800, v0
	s_waitcnt vmcnt(6)
	v_lshl_add_u32 v0, v5, 7, v0
	v_and_b32_e32 v1, 1, v4
	v_lshl_or_b32 v0, v1, 6, v0
	s_add_i32 s49, 0, 0x10000
	s_add_i32 s50, 0, 0x14000
	s_sext_i32_i8 s57, s0
	s_ashr_i32 s45, s86, 31
	s_mov_b32 s48, s86
	v_or_b32_e32 v152, s1, v8
	v_mov_b32_e32 v143, v137
	v_lshl_add_u32 v144, v6, 1, v0
	v_mov_b32_e32 v145, v137
	v_mov_b64_e32 v[146:147], 0x400
	v_mov_b64_e32 v[148:149], 0x3ff
	s_mov_b64 s[0:1], 0x80000
	v_add_u32_e32 v153, s49, v133
	v_add_u32_e32 v154, 0, v9
	v_add_u32_e32 v155, s50, v133
	s_mov_b32 s51, 0x80000
	s_mov_b64 s[8:9], 0x90000
	s_mov_b32 s54, 0x90000
	s_mov_b64 s[10:11], 0xa0000
	s_mov_b32 s55, 0xa0000
	s_mov_b64 s[12:13], 0xb0000
	s_mov_b32 s56, 0xb0000
	s_barrier

; #define PG8_STAGE(bufoff, gbase, voff) do { _Pragma("unroll") for (int _i = 0; _i < 2; ++_i) \
;         __builtin_amdgcn_global_load_lds((const unsigned*)((const char*)(gbase) + (voff)[_i]), (LAS unsigned*)(lds + (bufoff) + ldsw + _i * 8192), 16, 0, 0); } while (0)
; #define PG8_LDA(dst, b, h) do { _Pragma("unroll") for (int m = 0; m < 4; ++m) _Pragma("unroll") for (int k = 0; k < 2; ++k) dst[m][k] = *(const LAS bf16x8*)(lds + PG8_SA(b, h) + aoff + m * 2048 + k * 1024); } while (0)
; #define PG8_LDB(dst, b, h) do { _Pragma("unroll") for (int n = 0; n < 2; ++n) _Pragma("unroll") for (int k = 0; k < 2; ++k) dst[n][k] = *(const LAS bf16x8*)(lds + PG8_SB(b, h) + boff + n * 2048 + k * 1024); } while (0)
; #define PG8_MMA(ai, bj, At, Bt) do { __builtin_amdgcn_s_setprio(1); _Pragma("unroll") for (int m = 0; m < 4; ++m) _Pragma("unroll") for (int n = 0; n < 2; ++n) _Pragma("unroll") for (int k = 0; k < 2; ++k) \
;         acc[ai][bj][m][n] = __builtin_amdgcn_mfma_f32_16x16x32_bf16(Bt[n][k], At[m][k], acc[ai][bj][m][n], 0, 0, 0); __builtin_amdgcn_s_setprio(0); } while (0)
; #define PG8_WAIT_V(n) asm volatile("s_waitcnt vmcnt(" #n ")" ::: "memory")
; #define PG8_WAIT_L(n) asm volatile("s_waitcnt lgkmcnt(" #n ")" ::: "memory")
; template <class Epi>
; __device__ __forceinline__ void gemm_phase(LAS unsigned char* lds, const Gemm g, const StaticOrder& S, const Epi& E) {
;     ...
;         for (int t = 0; t < nt; t += 2) {
;             const bool last = (t == nt - 2);
;             const char* a1 = cA + (size_t)(t + 1) * kstepA;
;             const char* a2 = last ? nA : cA + (size_t)(t + 2) * kstepA; const char* b2 = last ? nB : cB + (size_t)(t + 2) * kstepB;
;             const char* a3 = a2 + kstepA; const char* b3 = b2 + kstepB;
;             PG8_LDB(B0, 0, 0); PG8_SCHED; PG8_LDA(At, 0, 0); PG8_STAGE(PG8_SA(1, 1), a1 + hstep, voffA);
;             PG8_WAIT_L(8); PG8_BAR; PG8_WAIT_L(0); PG8_MMA(0, 0, At, B0); PG8_BAR; PG8_SCHED;
;             PG8_LDB(B1, 0, 1); PG8_STAGE(PG8_SB(0, 0), b2, voffB);
;             PG8_BAR; PG8_WAIT_L(0); PG8_MMA(0, 1, At, B1); PG8_BAR;
;             PG8_LDA(At, 0, 1); PG8_STAGE(PG8_SA(0, 0), a2, voffA);
;             PG8_BAR; PG8_WAIT_L(0); PG8_MMA(1, 0, At, B0); PG8_BAR; PG8_SCHED;
;             PG8_STAGE(PG8_SB(0, 1), b2 + hstep, voffB);
;             PG8_WAIT_V(6); PG8_BAR; PG8_MMA(1, 1, At, B1); PG8_BAR;
.LBB0_762:
	ds_read_b128 v[156:159], v153
	ds_read_b128 v[160:163], v153 offset:1024
	ds_read_b128 v[164:167], v153 offset:2048
	ds_read_b128 v[168:171], v153 offset:3072
	s_add_u32 s26, s24, 0x3fc000
	s_addc_u32 s27, s25, 0
	s_cmp_eq_u32 s62, 28
	s_cselect_b32 s30, s58, s26
	s_cselect_b32 s31, s17, s27
	s_cselect_b32 s27, s15, s61
	s_cselect_b32 s26, s59, s60
	s_add_u32 s28, s30, 0x400000
	s_addc_u32 s29, s31, 0
	v_lshl_add_u64 v[150:151], s[24:25], 0, v[142:143]
	s_add_i32 m0, s23, 0xc000
	ds_read_b128 v[172:175], v154
	ds_read_b128 v[176:179], v154 offset:1024
	ds_read_b128 v[184:187], v154 offset:2048
	ds_read_b128 v[188:191], v154 offset:3072
	ds_read_b128 v[192:195], v154 offset:4096
	ds_read_b128 v[196:199], v154 offset:5120
	ds_read_b128 v[200:203], v154 offset:6144
	ds_read_b128 v[204:207], v154 offset:7168
	global_load_lds_dwordx4 v[150:151], off
	v_lshl_add_u64 v[150:151], s[24:25], 0, v[144:145]
	s_add_i32 m0, s23, 0xe000
	s_nop 0
	global_load_lds_dwordx4 v[150:151], off
	ds_read_b128 v[208:211], v155
	ds_read_b128 v[212:215], v155 offset:1024
	ds_read_b128 v[216:219], v155 offset:2048
	ds_read_b128 v[220:223], v155 offset:3072
	s_waitcnt lgkmcnt(0)
	s_waitcnt vmcnt(8)
	s_barrier
	s_setprio 1
	v_mfma_f32_16x16x32_bf16 v[124:127], v[156:159], v[172:175], v[124:127]
	v_mfma_f32_16x16x32_bf16 v[120:123], v[164:167], v[172:175], v[120:123]
	v_mfma_f32_16x16x32_bf16 v[112:115], v[156:159], v[184:187], v[112:115]
	v_mfma_f32_16x16x32_bf16 v[104:107], v[164:167], v[184:187], v[104:107]
	v_mfma_f32_16x16x32_bf16 v[96:99], v[156:159], v[192:195], v[96:99]
	v_mfma_f32_16x16x32_bf16 v[88:91], v[164:167], v[192:195], v[88:91]
	v_mfma_f32_16x16x32_bf16 v[80:83], v[156:159], v[200:203], v[80:83]
	v_mfma_f32_16x16x32_bf16 v[72:75], v[164:167], v[200:203], v[72:75]
	v_mfma_f32_16x16x32_bf16 v[124:127], v[160:163], v[176:179], v[124:127]
	v_mfma_f32_16x16x32_bf16 v[120:123], v[168:171], v[176:179], v[120:123]
	v_mfma_f32_16x16x32_bf16 v[112:115], v[160:163], v[188:191], v[112:115]
	v_mfma_f32_16x16x32_bf16 v[104:107], v[168:171], v[188:191], v[104:107]
	v_mfma_f32_16x16x32_bf16 v[96:99], v[160:163], v[196:199], v[96:99]
	v_mfma_f32_16x16x32_bf16 v[88:91], v[168:171], v[196:199], v[88:91]
	v_mfma_f32_16x16x32_bf16 v[80:83], v[160:163], v[204:207], v[80:83]
	v_mfma_f32_16x16x32_bf16 v[72:75], v[168:171], v[204:207], v[72:75]
	v_mfma_f32_16x16x32_bf16 v[116:119], v[208:211], v[172:175], v[116:119]
	v_mfma_f32_16x16x32_bf16 v[108:111], v[216:219], v[172:175], v[108:111]
	v_mfma_f32_16x16x32_bf16 v[100:103], v[208:211], v[184:187], v[100:103]
	v_mfma_f32_16x16x32_bf16 v[92:95], v[216:219], v[184:187], v[92:95]
	v_mfma_f32_16x16x32_bf16 v[84:87], v[208:211], v[192:195], v[84:87]
	v_mfma_f32_16x16x32_bf16 v[76:79], v[216:219], v[192:195], v[76:79]
	v_mfma_f32_16x16x32_bf16 v[68:71], v[208:211], v[200:203], v[68:71]
	v_mfma_f32_16x16x32_bf16 v[64:67], v[216:219], v[200:203], v[64:67]
	v_mfma_f32_16x16x32_bf16 v[116:119], v[212:215], v[176:179], v[116:119]
	v_mfma_f32_16x16x32_bf16 v[108:111], v[220:223], v[176:179], v[108:111]
	v_mfma_f32_16x16x32_bf16 v[100:103], v[212:215], v[188:191], v[100:103]
	v_mfma_f32_16x16x32_bf16 v[92:95], v[220:223], v[188:191], v[92:95]
	v_mfma_f32_16x16x32_bf16 v[84:87], v[212:215], v[196:199], v[84:87]
	v_mfma_f32_16x16x32_bf16 v[76:79], v[220:223], v[196:199], v[76:79]
	v_mfma_f32_16x16x32_bf16 v[68:71], v[212:215], v[204:207], v[68:71]
	v_mfma_f32_16x16x32_bf16 v[64:67], v[220:223], v[204:207], v[64:67]
	s_setprio 0
	s_barrier
	s_add_i32 s63, s49, s38
	v_lshl_add_u64 v[150:151], s[26:27], 0, v[136:137]
	s_mov_b32 m0, s63
	s_nop 0
	global_load_lds_dwordx4 v[150:151], off
	v_lshl_add_u64 v[150:151], s[26:27], 0, v[140:141]
	s_add_i32 m0, s63, 0x2000
	s_nop 0
	global_load_lds_dwordx4 v[150:151], off
	s_mov_b32 m0, s23
	v_lshl_add_u64 v[150:151], s[30:31], 0, v[134:135]
	ds_read_b128 v[172:175], v154 offset:16384
	ds_read_b128 v[176:179], v154 offset:17408
	ds_read_b128 v[184:187], v154 offset:18432
	ds_read_b128 v[188:191], v154 offset:19456
	ds_read_b128 v[192:195], v154 offset:20480
	ds_read_b128 v[196:199], v154 offset:21504
	ds_read_b128 v[200:203], v154 offset:22528
	ds_read_b128 v[204:207], v154 offset:23552
	global_load_lds_dwordx4 v[150:151], off
	v_lshl_add_u64 v[150:151], s[30:31], 0, v[138:139]
	s_mov_b32 m0, s39
	s_nop 0
	global_load_lds_dwordx4 v[150:151], off
	s_add_u32 s64, s26, 0x4000
	s_addc_u32 s65, s27, 0
	s_add_i32 s63, s50, s38
	v_lshl_add_u64 v[150:151], s[64:65], 0, v[136:137]
	s_mov_b32 m0, s63
	s_nop 0
	global_load_lds_dwordx4 v[150:151], off
	v_lshl_add_u64 v[150:151], s[64:65], 0, v[140:141]
	s_add_i32 m0, s63, 0x2000
	s_nop 0
	global_load_lds_dwordx4 v[150:151], off
	s_waitcnt lgkmcnt(0)
	s_waitcnt vmcnt(8)
	s_barrier
; #define PG8_STAGE(bufoff, gbase, voff) do { _Pragma("unroll") for (int _i = 0; _i < 2; ++_i) \
;         __builtin_amdgcn_global_load_lds((const unsigned*)((const char*)(gbase) + (voff)[_i]), (LAS unsigned*)(lds + (bufoff) + ldsw + _i * 8192), 16, 0, 0); } while (0)
; #define PG8_LDA(dst, b, h) do { _Pragma("unroll") for (int m = 0; m < 4; ++m) _Pragma("unroll") for (int k = 0; k < 2; ++k) dst[m][k] = *(const LAS bf16x8*)(lds + PG8_SA(b, h) + aoff + m * 2048 + k * 1024); } while (0)
; #define PG8_LDB(dst, b, h) do { _Pragma("unroll") for (int n = 0; n < 2; ++n) _Pragma("unroll") for (int k = 0; k < 2; ++k) dst[n][k] = *(const LAS bf16x8*)(lds + PG8_SB(b, h) + boff + n * 2048 + k * 1024); } while (0)
; #define PG8_MMA(ai, bj, At, Bt) do { __builtin_amdgcn_s_setprio(1); _Pragma("unroll") for (int m = 0; m < 4; ++m) _Pragma("unroll") for (int n = 0; n < 2; ++n) _Pragma("unroll") for (int k = 0; k < 2; ++k) \
;         acc[ai][bj][m][n] = __builtin_amdgcn_mfma_f32_16x16x32_bf16(Bt[n][k], At[m][k], acc[ai][bj][m][n], 0, 0, 0); __builtin_amdgcn_s_setprio(0); } while (0)
; #define PG8_WAIT_V(n) asm volatile("s_waitcnt vmcnt(" #n ")" ::: "memory")
; #define PG8_WAIT_L(n) asm volatile("s_waitcnt lgkmcnt(" #n ")" ::: "memory")
; #define PG8_BAR __builtin_amdgcn_s_barrier()
; #define PG8_SCHED __builtin_amdgcn_sched_barrier(0)
; template <class Epi>
; __device__ __forceinline__ void gemm_phase(LAS unsigned char* lds, const Gemm g, const StaticOrder& S, const Epi& E) {
;     ...
;             PG8_BAR; PG8_WAIT_L(0); PG8_MMA(1, 0, At, B0); PG8_BAR; PG8_SCHED;
;             PG8_STAGE(PG8_SB(0, 1), b2 + hstep, voffB);
;             PG8_WAIT_V(6); PG8_BAR; PG8_MMA(1, 1, At, B1); PG8_BAR;
;             PG8_LDB(B0, 1, 0); PG8_SCHED; PG8_LDA(At, 1, 0); PG8_STAGE(PG8_SA(0, 1), a2 + hstep, voffA);
;             PG8_WAIT_L(8); PG8_BAR; PG8_WAIT_L(0); PG8_MMA(0, 0, At, B0); PG8_BAR; PG8_SCHED;
;             PG8_LDB(B1, 1, 1); PG8_STAGE(PG8_SB(1, 0), b3, voffB);
;             PG8_BAR; PG8_WAIT_L(0); PG8_MMA(0, 1, At, B1); PG8_BAR;
;             PG8_LDA(At, 1, 1); PG8_STAGE(PG8_SA(1, 0), a3, voffA);
;             PG8_BAR; PG8_WAIT_L(0); PG8_MMA(1, 0, At, B0); PG8_BAR; PG8_SCHED;
	s_setprio 1
	v_mfma_f32_16x16x32_bf16 v[60:63], v[156:159], v[172:175], v[60:63]
	v_mfma_f32_16x16x32_bf16 v[56:59], v[164:167], v[172:175], v[56:59]
	v_mfma_f32_16x16x32_bf16 v[52:55], v[156:159], v[184:187], v[52:55]
	v_mfma_f32_16x16x32_bf16 v[44:47], v[164:167], v[184:187], v[44:47]
	v_mfma_f32_16x16x32_bf16 v[36:39], v[156:159], v[192:195], v[36:39]
	v_mfma_f32_16x16x32_bf16 v[28:31], v[164:167], v[192:195], v[28:31]
	v_mfma_f32_16x16x32_bf16 v[20:23], v[156:159], v[200:203], v[20:23]
	v_mfma_f32_16x16x32_bf16 v[12:15], v[164:167], v[200:203], v[12:15]
	v_mfma_f32_16x16x32_bf16 v[60:63], v[160:163], v[176:179], v[60:63]
	v_mfma_f32_16x16x32_bf16 v[56:59], v[168:171], v[176:179], v[56:59]
	v_mfma_f32_16x16x32_bf16 v[52:55], v[160:163], v[188:191], v[52:55]
	v_mfma_f32_16x16x32_bf16 v[44:47], v[168:171], v[188:191], v[44:47]
	v_mfma_f32_16x16x32_bf16 v[36:39], v[160:163], v[196:199], v[36:39]
	v_mfma_f32_16x16x32_bf16 v[28:31], v[168:171], v[196:199], v[28:31]
	v_mfma_f32_16x16x32_bf16 v[20:23], v[160:163], v[204:207], v[20:23]
	v_mfma_f32_16x16x32_bf16 v[12:15], v[168:171], v[204:207], v[12:15]
	v_mfma_f32_16x16x32_bf16 v[48:51], v[208:211], v[172:175], v[48:51]
	v_mfma_f32_16x16x32_bf16 v[40:43], v[216:219], v[172:175], v[40:43]
	v_mfma_f32_16x16x32_bf16 v[32:35], v[208:211], v[184:187], v[32:35]
	v_mfma_f32_16x16x32_bf16 v[24:27], v[216:219], v[184:187], v[24:27]
	v_mfma_f32_16x16x32_bf16 v[16:19], v[208:211], v[192:195], v[16:19]
	v_mfma_f32_16x16x32_bf16 v[8:11], v[216:219], v[192:195], v[8:11]
	v_mfma_f32_16x16x32_bf16 v[4:7], v[208:211], v[200:203], v[4:7]
	v_mfma_f32_16x16x32_bf16 v[0:3], v[216:219], v[200:203], v[0:3]
	v_mfma_f32_16x16x32_bf16 v[48:51], v[212:215], v[176:179], v[48:51]
	v_mfma_f32_16x16x32_bf16 v[40:43], v[220:223], v[176:179], v[40:43]
	v_mfma_f32_16x16x32_bf16 v[32:35], v[212:215], v[188:191], v[32:35]
	v_mfma_f32_16x16x32_bf16 v[24:27], v[220:223], v[188:191], v[24:27]
	v_mfma_f32_16x16x32_bf16 v[16:19], v[212:215], v[196:199], v[16:19]
	v_mfma_f32_16x16x32_bf16 v[8:11], v[220:223], v[196:199], v[8:11]
	v_mfma_f32_16x16x32_bf16 v[4:7], v[212:215], v[204:207], v[4:7]
	v_mfma_f32_16x16x32_bf16 v[0:3], v[220:223], v[204:207], v[0:3]
	s_setprio 0
	s_add_i32 s63, 0, 0x18000
	v_add_u32_e32 v150, s63, v133
	s_barrier
	ds_read_b128 v[156:159], v150
	ds_read_b128 v[160:163], v150 offset:1024
	ds_read_b128 v[164:167], v150 offset:2048
	ds_read_b128 v[168:171], v150 offset:3072
	s_add_u32 s30, s30, 0x4000
	s_addc_u32 s31, s31, 0
	s_mov_b32 m0, s40
	v_lshl_add_u64 v[150:151], s[30:31], 0, v[134:135]
	ds_read_b128 v[172:175], v154 offset:32768
	ds_read_b128 v[176:179], v154 offset:33792
	ds_read_b128 v[184:187], v154 offset:34816
	ds_read_b128 v[188:191], v154 offset:35840
	ds_read_b128 v[192:195], v154 offset:36864
	ds_read_b128 v[196:199], v154 offset:37888
	ds_read_b128 v[200:203], v154 offset:38912
	ds_read_b128 v[204:207], v154 offset:39936
	global_load_lds_dwordx4 v[150:151], off
	v_lshl_add_u64 v[150:151], s[30:31], 0, v[138:139]
	s_mov_b32 m0, s41
	s_nop 0
	global_load_lds_dwordx4 v[150:151], off
	v_add_u32_e32 v253, 0x1c000, v133
	ds_read_b128 v[208:211], v253
	ds_read_b128 v[212:215], v253 offset:1024
	ds_read_b128 v[216:219], v253 offset:2048
	ds_read_b128 v[220:223], v253 offset:3072
	s_waitcnt lgkmcnt(0)
	s_waitcnt vmcnt(8)
	s_barrier
	s_setprio 1
	v_mfma_f32_16x16x32_bf16 v[124:127], v[156:159], v[172:175], v[124:127]
	v_mfma_f32_16x16x32_bf16 v[120:123], v[164:167], v[172:175], v[120:123]
	v_mfma_f32_16x16x32_bf16 v[112:115], v[156:159], v[184:187], v[112:115]
	v_mfma_f32_16x16x32_bf16 v[104:107], v[164:167], v[184:187], v[104:107]
	v_mfma_f32_16x16x32_bf16 v[96:99], v[156:159], v[192:195], v[96:99]
	v_mfma_f32_16x16x32_bf16 v[88:91], v[164:167], v[192:195], v[88:91]
	v_mfma_f32_16x16x32_bf16 v[80:83], v[156:159], v[200:203], v[80:83]
	v_mfma_f32_16x16x32_bf16 v[72:75], v[164:167], v[200:203], v[72:75]
	v_mfma_f32_16x16x32_bf16 v[124:127], v[160:163], v[176:179], v[124:127]
	v_mfma_f32_16x16x32_bf16 v[120:123], v[168:171], v[176:179], v[120:123]
	v_mfma_f32_16x16x32_bf16 v[112:115], v[160:163], v[188:191], v[112:115]
	v_mfma_f32_16x16x32_bf16 v[104:107], v[168:171], v[188:191], v[104:107]
	v_mfma_f32_16x16x32_bf16 v[96:99], v[160:163], v[196:199], v[96:99]
	v_mfma_f32_16x16x32_bf16 v[88:91], v[168:171], v[196:199], v[88:91]
	v_mfma_f32_16x16x32_bf16 v[80:83], v[160:163], v[204:207], v[80:83]
	v_mfma_f32_16x16x32_bf16 v[72:75], v[168:171], v[204:207], v[72:75]
	v_mfma_f32_16x16x32_bf16 v[116:119], v[208:211], v[172:175], v[116:119]
	v_mfma_f32_16x16x32_bf16 v[108:111], v[216:219], v[172:175], v[108:111]
	v_mfma_f32_16x16x32_bf16 v[100:103], v[208:211], v[184:187], v[100:103]
	v_mfma_f32_16x16x32_bf16 v[92:95], v[216:219], v[184:187], v[92:95]
	v_mfma_f32_16x16x32_bf16 v[84:87], v[208:211], v[192:195], v[84:87]
	v_mfma_f32_16x16x32_bf16 v[76:79], v[216:219], v[192:195], v[76:79]
	v_mfma_f32_16x16x32_bf16 v[68:71], v[208:211], v[200:203], v[68:71]
	v_mfma_f32_16x16x32_bf16 v[64:67], v[216:219], v[200:203], v[64:67]
	v_mfma_f32_16x16x32_bf16 v[116:119], v[212:215], v[176:179], v[116:119]
	v_mfma_f32_16x16x32_bf16 v[108:111], v[220:223], v[176:179], v[108:111]
	v_mfma_f32_16x16x32_bf16 v[100:103], v[212:215], v[188:191], v[100:103]
	v_mfma_f32_16x16x32_bf16 v[92:95], v[220:223], v[188:191], v[92:95]
	v_mfma_f32_16x16x32_bf16 v[84:87], v[212:215], v[196:199], v[84:87]
	v_mfma_f32_16x16x32_bf16 v[76:79], v[220:223], v[196:199], v[76:79]
	v_mfma_f32_16x16x32_bf16 v[68:71], v[212:215], v[204:207], v[68:71]
	v_mfma_f32_16x16x32_bf16 v[64:67], v[220:223], v[204:207], v[64:67]
	s_setprio 0
	s_barrier
; #define PG8_STAGE(bufoff, gbase, voff) do { _Pragma("unroll") for (int _i = 0; _i < 2; ++_i) \
;         __builtin_amdgcn_global_load_lds((const unsigned*)((const char*)(gbase) + (voff)[_i]), (LAS unsigned*)(lds + (bufoff) + ldsw + _i * 8192), 16, 0, 0); } while (0)
; #define PG8_LDA(dst, b, h) do { _Pragma("unroll") for (int m = 0; m < 4; ++m) _Pragma("unroll") for (int k = 0; k < 2; ++k) dst[m][k] = *(const LAS bf16x8*)(lds + PG8_SA(b, h) + aoff + m * 2048 + k * 1024); } while (0)
; #define PG8_LDB(dst, b, h) do { _Pragma("unroll") for (int n = 0; n < 2; ++n) _Pragma("unroll") for (int k = 0; k < 2; ++k) dst[n][k] = *(const LAS bf16x8*)(lds + PG8_SB(b, h) + boff + n * 2048 + k * 1024); } while (0)
; #define PG8_MMA(ai, bj, At, Bt) do { __builtin_amdgcn_s_setprio(1); _Pragma("unroll") for (int m = 0; m < 4; ++m) _Pragma("unroll") for (int n = 0; n < 2; ++n) _Pragma("unroll") for (int k = 0; k < 2; ++k) \
;         acc[ai][bj][m][n] = __builtin_amdgcn_mfma_f32_16x16x32_bf16(Bt[n][k], At[m][k], acc[ai][bj][m][n], 0, 0, 0); __builtin_amdgcn_s_setprio(0); } while (0)
; #define PG8_WAIT_V(n) asm volatile("s_waitcnt vmcnt(" #n ")" ::: "memory")
; #define PG8_WAIT_L(n) asm volatile("s_waitcnt lgkmcnt(" #n ")" ::: "memory")
; #define PG8_BAR __builtin_amdgcn_s_barrier()
; #define PG8_SCHED __builtin_amdgcn_sched_barrier(0)
; template <class Epi>
; __device__ __forceinline__ void gemm_phase(LAS unsigned char* lds, const Gemm g, const StaticOrder& S, const Epi& E) {
;     ...
;             PG8_LDB(B1, 1, 1); PG8_STAGE(PG8_SB(1, 0), b3, voffB);
;             PG8_BAR; PG8_WAIT_L(0); PG8_MMA(0, 1, At, B1); PG8_BAR;
;             PG8_LDA(At, 1, 1); PG8_STAGE(PG8_SA(1, 0), a3, voffA);
;             PG8_BAR; PG8_WAIT_L(0); PG8_MMA(1, 0, At, B0); PG8_BAR; PG8_SCHED;
;             PG8_STAGE(PG8_SB(1, 1), b3 + hstep, voffB);
;             PG8_WAIT_V(6); PG8_BAR; PG8_MMA(1, 1, At, B1); PG8_BAR;
;         }
	s_add_i32 s64, 0, 0x1c000
	s_add_u32 s30, s26, 0x40000
	v_add_u32_e32 v150, s64, v133
	s_addc_u32 s31, s27, 0
	s_add_i32 s63, s63, s38
	s_nop 0
	v_lshl_add_u64 v[150:151], s[30:31], 0, v[136:137]
	s_mov_b32 m0, s63
	s_nop 0
	global_load_lds_dwordx4 v[150:151], off
	v_lshl_add_u64 v[150:151], s[30:31], 0, v[140:141]
	s_add_i32 m0, s63, 0x2000
	s_nop 0
	global_load_lds_dwordx4 v[150:151], off
	s_mov_b32 m0, s43
	v_lshl_add_u64 v[150:151], s[28:29], 0, v[134:135]
	ds_read_b128 v[172:175], v154 offset:49152
	ds_read_b128 v[176:179], v154 offset:50176
	ds_read_b128 v[184:187], v154 offset:51200
	ds_read_b128 v[188:191], v154 offset:52224
	ds_read_b128 v[192:195], v154 offset:53248
	ds_read_b128 v[196:199], v154 offset:54272
	ds_read_b128 v[200:203], v154 offset:55296
	ds_read_b128 v[204:207], v154 offset:56320
	global_load_lds_dwordx4 v[150:151], off
	v_lshl_add_u64 v[150:151], s[28:29], 0, v[138:139]
	s_mov_b32 m0, s44
	s_nop 0
	global_load_lds_dwordx4 v[150:151], off
	s_add_u32 s26, s26, 0x44000
	s_addc_u32 s27, s27, 0
	s_add_i32 s28, s64, s38
	v_lshl_add_u64 v[150:151], s[26:27], 0, v[136:137]
	s_mov_b32 m0, s28
	s_nop 0
	global_load_lds_dwordx4 v[150:151], off
	v_lshl_add_u64 v[150:151], s[26:27], 0, v[140:141]
	s_add_i32 m0, s28, 0x2000
	s_nop 0
	global_load_lds_dwordx4 v[150:151], off
	s_waitcnt lgkmcnt(0)
	s_waitcnt vmcnt(8)
	s_barrier
	s_setprio 1
	v_mfma_f32_16x16x32_bf16 v[60:63], v[156:159], v[172:175], v[60:63]
	v_mfma_f32_16x16x32_bf16 v[56:59], v[164:167], v[172:175], v[56:59]
	v_mfma_f32_16x16x32_bf16 v[52:55], v[156:159], v[184:187], v[52:55]
	v_mfma_f32_16x16x32_bf16 v[44:47], v[164:167], v[184:187], v[44:47]
	v_mfma_f32_16x16x32_bf16 v[36:39], v[156:159], v[192:195], v[36:39]
	v_mfma_f32_16x16x32_bf16 v[28:31], v[164:167], v[192:195], v[28:31]
	v_mfma_f32_16x16x32_bf16 v[20:23], v[156:159], v[200:203], v[20:23]
	v_mfma_f32_16x16x32_bf16 v[12:15], v[164:167], v[200:203], v[12:15]
	v_mfma_f32_16x16x32_bf16 v[60:63], v[160:163], v[176:179], v[60:63]
	v_mfma_f32_16x16x32_bf16 v[56:59], v[168:171], v[176:179], v[56:59]
	v_mfma_f32_16x16x32_bf16 v[52:55], v[160:163], v[188:191], v[52:55]
	v_mfma_f32_16x16x32_bf16 v[44:47], v[168:171], v[188:191], v[44:47]
	v_mfma_f32_16x16x32_bf16 v[36:39], v[160:163], v[196:199], v[36:39]
	v_mfma_f32_16x16x32_bf16 v[28:31], v[168:171], v[196:199], v[28:31]
	v_mfma_f32_16x16x32_bf16 v[20:23], v[160:163], v[204:207], v[20:23]
	v_mfma_f32_16x16x32_bf16 v[12:15], v[168:171], v[204:207], v[12:15]
	v_mfma_f32_16x16x32_bf16 v[48:51], v[208:211], v[172:175], v[48:51]
	v_mfma_f32_16x16x32_bf16 v[40:43], v[216:219], v[172:175], v[40:43]
	v_mfma_f32_16x16x32_bf16 v[32:35], v[208:211], v[184:187], v[32:35]
	v_mfma_f32_16x16x32_bf16 v[24:27], v[216:219], v[184:187], v[24:27]
	v_mfma_f32_16x16x32_bf16 v[16:19], v[208:211], v[192:195], v[16:19]
	v_mfma_f32_16x16x32_bf16 v[8:11], v[216:219], v[192:195], v[8:11]
	v_mfma_f32_16x16x32_bf16 v[4:7], v[208:211], v[200:203], v[4:7]
	v_mfma_f32_16x16x32_bf16 v[0:3], v[216:219], v[200:203], v[0:3]
	v_mfma_f32_16x16x32_bf16 v[48:51], v[212:215], v[176:179], v[48:51]
	v_mfma_f32_16x16x32_bf16 v[40:43], v[220:223], v[176:179], v[40:43]
	v_mfma_f32_16x16x32_bf16 v[32:35], v[212:215], v[188:191], v[32:35]
	v_mfma_f32_16x16x32_bf16 v[24:27], v[220:223], v[188:191], v[24:27]
	v_mfma_f32_16x16x32_bf16 v[16:19], v[212:215], v[196:199], v[16:19]
	v_mfma_f32_16x16x32_bf16 v[8:11], v[220:223], v[196:199], v[8:11]
	v_mfma_f32_16x16x32_bf16 v[4:7], v[212:215], v[204:207], v[4:7]
	v_mfma_f32_16x16x32_bf16 v[0:3], v[220:223], v[204:207], v[0:3]
	s_setprio 0
	s_add_i32 s62, s62, 2
	s_add_u32 s60, s60, 0x80000
	s_addc_u32 s61, s61, 0
	s_add_u32 s24, s24, 0x800000
	s_addc_u32 s25, s25, 0
	s_cmp_gt_u32 s62, 29
	s_barrier
	s_cbranch_scc0 .LBB0_762
; __device__ __forceinline__ unsigned pk_bf16(float lo, float hi) { unsigned r; asm("v_cvt_pk_bf16_f32 %0, %1, %2" : "=v"(r) : "v"(lo), "v"(hi)); return r; }
; #define PG8_WAIT_V(n) asm volatile("s_waitcnt vmcnt(" #n ")" ::: "memory")
; #define PG8_BAR __builtin_amdgcn_s_barrier()
;     __device__ __forceinline__ void operator()(const f32x4 (&acc)[2][2][4][2], const Unit& u, int wr, int wc, int fr, int fq) const {
;         const int row0 = u.pm * BM + wr * 64 + fr; const int col0 = u.pn * BM + wc * 32 + 8 * fq;
; #pragma unroll
;         for (int ai = 0; ai < 2; ++ai)
; #pragma unroll
;             for (int m = 0; m < 4; ++m) { bf16_t* rowp = O + (size_t)(row0 + ai * HALF + m * 16) * ldc + col0;
; #pragma unroll
;                 for (int bj = 0; bj < 2; ++bj) { const f32x4 v0 = acc[ai][bj][m][0], v1 = acc[ai][bj][m][1];
;                     u32x4 w; w.x = pk_bf16(v0[0], v0[1]); w.y = pk_bf16(v0[2], v0[3]); w.z = pk_bf16(v1[0], v1[1]); w.w = pk_bf16(v1[2], v1[3]);
;                     *(u32x4*)(rowp + bj * HALF) = w; } }
; template <class Epi>
; __device__ __forceinline__ void gemm_phase(LAS unsigned char* lds, const Gemm g, const StaticOrder& S, const Epi& E) {
;     ...
;         cur = nxt; cA = nA; cB = nB; ++ui;
;     }
;     PG8_WAIT_V(0);
;     if (wr == 0) PG8_BAR;
;     PG8_BAR;
	v_lshl_add_u32 v156, s22, 8, v131
	v_lshl_or_b32 v150, s57, 8, v152
	v_ashrrev_i32_e32 v157, 31, v156
	v_ashrrev_i32_e32 v151, 31, v150
	v_lshlrev_b64 v[158:159], 12, v[156:157]
	v_lshl_add_u64 v[158:159], s[52:53], 0, v[158:159]
	v_lshlrev_b64 v[160:161], 1, v[150:151]
	v_lshl_add_u64 v[150:151], v[158:159], 0, v[160:161]
	v_cvt_pk_bf16_f32 v60, v60, v61
	v_cvt_pk_bf16_f32 v61, v62, v63
	v_cvt_pk_bf16_f32 v62, v56, v57
	v_add_co_u32_e32 v56, vcc, s51, v150
	v_cvt_pk_bf16_f32 v116, v116, v117
	v_cvt_pk_bf16_f32 v117, v118, v119
	v_cvt_pk_bf16_f32 v118, v108, v109
	v_or_b32_e32 v108, 16, v156
	s_nop 0
	v_addc_co_u32_e32 v57, vcc, 0, v151, vcc
	v_cvt_pk_bf16_f32 v48, v48, v49
	v_cvt_pk_bf16_f32 v49, v50, v51
	v_cvt_pk_bf16_f32 v51, v42, v43
	v_cvt_pk_bf16_f32 v42, v44, v45
	v_add_co_u32_e32 v44, vcc, s54, v150
	v_ashrrev_i32_e32 v109, 31, v108
	v_cvt_pk_bf16_f32 v100, v100, v101
	v_cvt_pk_bf16_f32 v101, v102, v103
	v_cvt_pk_bf16_f32 v102, v92, v93
	v_or_b32_e32 v92, 32, v156
	v_addc_co_u32_e32 v45, vcc, 0, v151, vcc
	v_lshlrev_b64 v[108:109], 12, v[108:109]
	v_ashrrev_i32_e32 v93, 31, v92
	v_cvt_pk_bf16_f32 v84, v84, v85
	v_cvt_pk_bf16_f32 v85, v86, v87
	v_cvt_pk_bf16_f32 v86, v76, v77
	v_or_b32_e32 v76, 48, v156
	v_cvt_pk_bf16_f32 v32, v32, v33
	v_cvt_pk_bf16_f32 v33, v34, v35
	v_cvt_pk_bf16_f32 v35, v26, v27
	v_cvt_pk_bf16_f32 v26, v28, v29
	v_add_co_u32_e32 v28, vcc, s55, v150
	v_lshl_add_u64 v[108:109], s[52:53], 0, v[108:109]
	v_lshlrev_b64 v[92:93], 12, v[92:93]
	v_ashrrev_i32_e32 v77, 31, v76
	v_cvt_pk_bf16_f32 v68, v68, v69
	v_cvt_pk_bf16_f32 v69, v70, v71
	v_cvt_pk_bf16_f32 v70, v64, v65
	v_lshl_add_u64 v[64:65], v[150:151], 0, s[0:1]
	v_addc_co_u32_e32 v29, vcc, 0, v151, vcc
	v_cvt_pk_bf16_f32 v119, v110, v111
	global_store_dwordx4 v[150:151], v[116:119], off offset:256
	v_lshl_add_u64 v[92:93], s[52:53], 0, v[92:93]
	v_lshlrev_b64 v[76:77], 12, v[76:77]
	v_lshl_add_u64 v[116:117], v[108:109], 0, v[160:161]
	v_cvt_pk_bf16_f32 v50, v40, v41
	global_store_dwordx4 v[64:65], v[48:51], off offset:256
	v_cvt_pk_bf16_f32 v16, v16, v17
	v_cvt_pk_bf16_f32 v17, v18, v19
	v_cvt_pk_bf16_f32 v19, v10, v11
	v_cvt_pk_bf16_f32 v10, v12, v13
	v_add_co_u32_e32 v12, vcc, s56, v150
	s_nop 0
	v_lshl_add_u64 v[48:49], v[150:151], 0, s[8:9]
	v_cvt_pk_bf16_f32 v103, v94, v95
	global_store_dwordx4 v[116:117], v[100:103], off offset:256
	v_lshl_add_u64 v[76:77], s[52:53], 0, v[76:77]
	v_cvt_pk_bf16_f32 v34, v24, v25
	global_store_dwordx4 v[48:49], v[32:35], off offset:256
	v_lshl_add_u64 v[100:101], v[92:93], 0, v[160:161]
	v_addc_co_u32_e32 v13, vcc, 0, v151, vcc
	v_lshl_add_u64 v[32:33], v[150:151], 0, s[10:11]
	v_cvt_pk_bf16_f32 v87, v78, v79
	global_store_dwordx4 v[100:101], v[84:87], off offset:256
	v_cvt_pk_bf16_f32 v18, v8, v9
	global_store_dwordx4 v[32:33], v[16:19], off offset:256
	s_and_b64 vcc, exec, s[6:7]
	v_lshl_add_u64 v[84:85], v[76:77], 0, v[160:161]
	v_lshl_add_u64 v[16:17], v[150:151], 0, s[12:13]
	s_mov_b32 s57, s14
	s_mov_b32 s22, s16
	s_mov_b64 s[24:25], s[20:21]
	s_mov_b64 s[26:27], s[18:19]
	v_cvt_pk_bf16_f32 v124, v124, v125
	v_cvt_pk_bf16_f32 v125, v126, v127
	v_cvt_pk_bf16_f32 v126, v120, v121
	v_cvt_pk_bf16_f32 v127, v122, v123
	global_store_dwordx4 v[150:151], v[124:127], off
	v_cvt_pk_bf16_f32 v108, v112, v113
	v_cvt_pk_bf16_f32 v109, v114, v115
	v_cvt_pk_bf16_f32 v110, v104, v105
	v_cvt_pk_bf16_f32 v111, v106, v107
	global_store_dwordx4 v[116:117], v[108:111], off
	v_cvt_pk_bf16_f32 v92, v96, v97
	v_cvt_pk_bf16_f32 v93, v98, v99
	v_cvt_pk_bf16_f32 v94, v88, v89
	v_cvt_pk_bf16_f32 v95, v90, v91
	global_store_dwordx4 v[100:101], v[92:95], off
	v_cvt_pk_bf16_f32 v76, v80, v81
	v_cvt_pk_bf16_f32 v77, v82, v83
	v_cvt_pk_bf16_f32 v78, v72, v73
	v_cvt_pk_bf16_f32 v79, v74, v75
	global_store_dwordx4 v[84:85], v[76:79], off
	v_cvt_pk_bf16_f32 v71, v66, v67
	global_store_dwordx4 v[84:85], v[68:71], off offset:256
	v_cvt_pk_bf16_f32 v63, v58, v59
	global_store_dwordx4 v[56:57], v[60:63], off
	v_cvt_pk_bf16_f32 v40, v52, v53
	v_cvt_pk_bf16_f32 v41, v54, v55
	v_cvt_pk_bf16_f32 v43, v46, v47
	global_store_dwordx4 v[44:45], v[40:43], off
	v_cvt_pk_bf16_f32 v24, v36, v37
	v_cvt_pk_bf16_f32 v25, v38, v39
	v_cvt_pk_bf16_f32 v27, v30, v31
	global_store_dwordx4 v[28:29], v[24:27], off
	v_cvt_pk_bf16_f32 v8, v20, v21
	v_cvt_pk_bf16_f32 v9, v22, v23
	v_cvt_pk_bf16_f32 v11, v14, v15
	global_store_dwordx4 v[12:13], v[8:11], off
	v_cvt_pk_bf16_f32 v4, v4, v5
	v_cvt_pk_bf16_f32 v5, v6, v7
	v_cvt_pk_bf16_f32 v6, v0, v1
	v_cvt_pk_bf16_f32 v7, v2, v3
	global_store_dwordx4 v[16:17], v[4:7], off offset:256
	s_cbranch_vccz .LBB0_755
	s_waitcnt vmcnt(0)
	s_cmpk_gt_u32 s34, 0xff
	s_cbranch_scc1 .LBB0_766
	s_barrier

; #define PG8_STAGE(bufoff, gbase, voff) do { _Pragma("unroll") for (int _i = 0; _i < 2; ++_i) \
;         __builtin_amdgcn_global_load_lds((const unsigned*)((const char*)(gbase) + (voff)[_i]), (LAS unsigned*)(lds + (bufoff) + ldsw + _i * 8192), 16, 0, 0); } while (0)
; #define PG8_WAIT_V(n) asm volatile("s_waitcnt vmcnt(" #n ")" ::: "memory")
; #define PG8_BAR __builtin_amdgcn_s_barrier()
; template <class Epi>
; __device__ __forceinline__ void gemm_phase(LAS unsigned char* lds, const Gemm g, const StaticOrder& S, const Epi& E) {
;     ...
;     for (int i = 0; i < 2; ++i) { int R, C; stage_rc(tid * 16 + i * 8192, R, C); const int Rb = Epi::PERM ? ((R & ~31) + perm32(R & 31)) : R;
;         voffA[i] = (unsigned)(R * BK + C) * 2u; voffB[i] = (unsigned)(Rb * BK + C) * 2u; }
;     const size_t kstepA = (size_t)g.M * BK * 2, kstepB = (size_t)g.N * BK * 2;
;     const size_t hstep = (size_t)HALF * BK * 2;
;     const size_t tstep = 2 * hstep;
;     const unsigned ldsw = (unsigned)wid * 1024u;
;     const int aoff = lds_byte(wr * 64 + fr, fq * 8), boff = lds_byte(wc * 32 + fr, fq * 8);
;     ...
;     Unit cur, nxt; int ui = 0;
;     if (!S.next(0, cur)) return;
;     f32x4 acc[2][2][4][2];
; #pragma unroll
;     for (int a = 0; a < 2; ++a)
; #pragma unroll
;         for (int b = 0; b < 2; ++b)
; #pragma unroll
;             for (int m = 0; m < 4; ++m)
; #pragma unroll
;                 for (int n = 0; n < 2; ++n) acc[a][b][m][n] = (f32x4){0.f, 0.f, 0.f, 0.f};
;     bf16x8 At[4][2], B0[2][2], B1[2][2];
;     const char* cA = (const char*)g.A + (size_t)cur.pm * tstep; const char* cB = (const char*)g.Bt + (size_t)cur.pn * tstep;
;     PG8_STAGE(PG8_SB(0, 0), cB, voffB); PG8_STAGE(PG8_SA(0, 0), cA, voffA); PG8_STAGE(PG8_SB(0, 1), cB + hstep, voffB); PG8_STAGE(PG8_SA(0, 1), cA + hstep, voffA);
;     if (wr == 1) PG8_BAR;
;     PG8_WAIT_V(4); PG8_BAR;
;     PG8_STAGE(PG8_SB(1, 0), cB + kstepB, voffB); PG8_STAGE(PG8_SA(1, 0), cA + kstepA, voffA); PG8_STAGE(PG8_SB(1, 1), cB + hstep + kstepB, voffB);
;     PG8_WAIT_V(6); PG8_BAR;
.LBB0_881:
	s_lshl_b32 s9, s6, 5
	s_and_b32 s37, s9, 0x60
	s_lshl_b32 s8, s1, 13
	s_lshl_b32 s10, s37, 7
	s_add_u32 s6, s16, 0x160000
	s_addc_u32 s7, s17, 0
	s_add_i32 m0, s30, 0x18000
	v_lshl_add_u64 v[8:9], s[6:7], 0, v[132:133]
	s_waitcnt vmcnt(2)
	s_barrier
	global_load_lds_dwordx4 v[8:9], off
	s_add_i32 m0, s30, 0x1a000
	v_lshl_add_u64 v[8:9], s[6:7], 0, v[130:131]
	s_add_u32 s6, s18, 0x400000
	s_addc_u32 s7, s19, 0
	s_add_i32 s38, s30, 0x8000
	global_load_lds_dwordx4 v[8:9], off
	v_lshl_add_u64 v[8:9], s[6:7], 0, v[132:133]
	s_mov_b32 m0, s38
	s_add_i32 s39, s30, 0xa000
	global_load_lds_dwordx4 v[8:9], off
	v_lshl_add_u64 v[8:9], s[6:7], 0, v[130:131]
	s_add_u32 s6, s16, 0x164000
	s_mov_b32 m0, s39
	s_addc_u32 s7, s17, 0
	global_load_lds_dwordx4 v[8:9], off
	s_add_i32 m0, s30, 0x1c000
	v_lshl_add_u64 v[8:9], s[6:7], 0, v[132:133]
	global_load_lds_dwordx4 v[8:9], off
	v_lshl_add_u64 v[8:9], s[6:7], 0, v[130:131]
	s_add_i32 m0, s30, 0x1e000
	v_and_b32_e32 v7, 15, v1
	global_load_lds_dwordx4 v[8:9], off
	v_lshrrev_b32_e32 v8, 1, v1
	v_and_b32_e32 v8, 24, v8
	v_lshlrev_b32_e32 v9, 1, v8
	v_lshlrev_b32_e32 v1, 2, v1
	v_lshl_or_b32 v146, s1, 6, v7
	v_lshl_or_b32 v7, v7, 6, v9
	v_and_b32_e32 v1, 32, v1
	v_bitop3_b32 v10, v7, s8, v1 bitop3:0xde
	v_bitop3_b32 v147, v7, s10, v1 bitop3:0xde
	v_and_or_b32 v1, s9, 32, v8
	v_lshlrev_b32_e32 v8, 1, v1
	v_lshlrev_b32_e32 v1, 10, v4
	v_and_b32_e32 v1, 0xfffff800, v1
	v_lshl_add_u32 v1, v5, 7, v1
	v_and_b32_e32 v4, 1, v4
	v_lshl_or_b32 v1, v4, 6, v1
	v_lshl_add_u32 v136, v6, 1, v1
	v_lshlrev_b32_e32 v1, 10, v0
	v_and_b32_e32 v1, 0xfffff800, v1
	s_waitcnt vmcnt(6)
	v_lshl_add_u32 v1, v2, 7, v1
	v_and_b32_e32 v0, 1, v0
	v_mov_b32_e32 v9, v133
	v_lshl_or_b32 v0, v0, 6, v1
	s_add_i32 s42, 0, 0x10000
	s_add_i32 s43, 0, 0x14000
	s_sext_i32_i16 s15, s0
	v_lshl_add_u64 v[134:135], s[2:3], 0, v[8:9]
	s_ashr_i32 s40, s86, 31
	s_mov_b32 s41, s86
	v_mov_b32_e32 v137, v133
	v_lshl_add_u32 v138, v3, 1, v0
	v_mov_b32_e32 v139, v133
	v_mov_b64_e32 v[140:141], 0x1600
	v_mov_b64_e32 v[142:143], 0x15ff
	v_add_u32_e32 v148, s42, v147
	v_add_u32_e32 v149, 0, v10
	v_add_u32_e32 v150, s43, v147
	s_barrier

; #define PG8_STAGE(bufoff, gbase, voff) do { _Pragma("unroll") for (int _i = 0; _i < 2; ++_i) \
;         __builtin_amdgcn_global_load_lds((const unsigned*)((const char*)(gbase) + (voff)[_i]), (LAS unsigned*)(lds + (bufoff) + ldsw + _i * 8192), 16, 0, 0); } while (0)
; #define PG8_LDA(dst, b, h) do { _Pragma("unroll") for (int m = 0; m < 4; ++m) _Pragma("unroll") for (int k = 0; k < 2; ++k) dst[m][k] = *(const LAS bf16x8*)(lds + PG8_SA(b, h) + aoff + m * 2048 + k * 1024); } while (0)
; #define PG8_LDB(dst, b, h) do { _Pragma("unroll") for (int n = 0; n < 2; ++n) _Pragma("unroll") for (int k = 0; k < 2; ++k) dst[n][k] = *(const LAS bf16x8*)(lds + PG8_SB(b, h) + boff + n * 2048 + k * 1024); } while (0)
; #define PG8_MMA(ai, bj, At, Bt) do { __builtin_amdgcn_s_setprio(1); _Pragma("unroll") for (int m = 0; m < 4; ++m) _Pragma("unroll") for (int n = 0; n < 2; ++n) _Pragma("unroll") for (int k = 0; k < 2; ++k) \
;         acc[ai][bj][m][n] = __builtin_amdgcn_mfma_f32_16x16x32_bf16(Bt[n][k], At[m][k], acc[ai][bj][m][n], 0, 0, 0); __builtin_amdgcn_s_setprio(0); } while (0)
; #define PG8_WAIT_V(n) asm volatile("s_waitcnt vmcnt(" #n ")" ::: "memory")
; #define PG8_WAIT_L(n) asm volatile("s_waitcnt lgkmcnt(" #n ")" ::: "memory")
; template <class Epi>
; __device__ __forceinline__ void gemm_phase(LAS unsigned char* lds, const Gemm g, const StaticOrder& S, const Epi& E) {
;     ...
;         for (int t = 0; t < nt; t += 2) {
;             const bool last = (t == nt - 2);
;             const char* a1 = cA + (size_t)(t + 1) * kstepA;
;             const char* a2 = last ? nA : cA + (size_t)(t + 2) * kstepA; const char* b2 = last ? nB : cB + (size_t)(t + 2) * kstepB;
;             const char* a3 = a2 + kstepA; const char* b3 = b2 + kstepB;
;             PG8_LDB(B0, 0, 0); PG8_SCHED; PG8_LDA(At, 0, 0); PG8_STAGE(PG8_SA(1, 1), a1 + hstep, voffA);
;             PG8_WAIT_L(8); PG8_BAR; PG8_WAIT_L(0); PG8_MMA(0, 0, At, B0); PG8_BAR; PG8_SCHED;
;             PG8_LDB(B1, 0, 1); PG8_STAGE(PG8_SB(0, 0), b2, voffB);
;             PG8_BAR; PG8_WAIT_L(0); PG8_MMA(0, 1, At, B1); PG8_BAR;
;             PG8_LDA(At, 0, 1); PG8_STAGE(PG8_SA(0, 0), a2, voffA);
;             PG8_BAR; PG8_WAIT_L(0); PG8_MMA(1, 0, At, B0); PG8_BAR; PG8_SCHED;
;             PG8_STAGE(PG8_SB(0, 1), b2 + hstep, voffB);
;             PG8_WAIT_V(6); PG8_BAR; PG8_MMA(1, 1, At, B1); PG8_BAR;
.LBB0_885:
	ds_read_b128 v[152:155], v148
	ds_read_b128 v[156:159], v148 offset:1024
	ds_read_b128 v[160:163], v148 offset:2048
	ds_read_b128 v[164:167], v148 offset:3072
	s_add_u32 s18, s16, 0x3fc000
	s_addc_u32 s19, s17, 0
	s_cmp_eq_u32 s50, 28
	s_cselect_b32 s22, s44, s18
	s_cselect_b32 s23, s9, s19
	s_cselect_b32 s18, s45, s48
	s_cselect_b32 s19, s1, s49
	s_add_u32 s20, s22, 0x400000
	s_addc_u32 s21, s23, 0
	v_lshl_add_u64 v[144:145], s[16:17], 0, v[136:137]
	s_add_i32 m0, s30, 0xc000
	ds_read_b128 v[168:171], v149
	ds_read_b128 v[172:175], v149 offset:1024
	ds_read_b128 v[176:179], v149 offset:2048
	ds_read_b128 v[184:187], v149 offset:3072
	ds_read_b128 v[188:191], v149 offset:4096
	ds_read_b128 v[192:195], v149 offset:5120
	ds_read_b128 v[196:199], v149 offset:6144
	ds_read_b128 v[200:203], v149 offset:7168
	global_load_lds_dwordx4 v[144:145], off
	v_lshl_add_u64 v[144:145], s[16:17], 0, v[138:139]
	s_add_i32 m0, s30, 0xe000
	s_nop 0
	global_load_lds_dwordx4 v[144:145], off
	ds_read_b128 v[204:207], v150
	ds_read_b128 v[208:211], v150 offset:1024
	ds_read_b128 v[212:215], v150 offset:2048
	ds_read_b128 v[216:219], v150 offset:3072
	s_waitcnt lgkmcnt(0)
	s_waitcnt vmcnt(8)
	s_barrier
	s_setprio 1
	v_mfma_f32_16x16x32_bf16 v[124:127], v[152:155], v[168:171], v[124:127]
	v_mfma_f32_16x16x32_bf16 v[120:123], v[160:163], v[168:171], v[120:123]
	v_mfma_f32_16x16x32_bf16 v[108:111], v[152:155], v[176:179], v[108:111]
	v_mfma_f32_16x16x32_bf16 v[104:107], v[160:163], v[176:179], v[104:107]
	v_mfma_f32_16x16x32_bf16 v[92:95], v[152:155], v[188:191], v[92:95]
	v_mfma_f32_16x16x32_bf16 v[88:91], v[160:163], v[188:191], v[88:91]
	v_mfma_f32_16x16x32_bf16 v[76:79], v[152:155], v[196:199], v[76:79]
	v_mfma_f32_16x16x32_bf16 v[72:75], v[160:163], v[196:199], v[72:75]
	v_mfma_f32_16x16x32_bf16 v[124:127], v[156:159], v[172:175], v[124:127]
	v_mfma_f32_16x16x32_bf16 v[120:123], v[164:167], v[172:175], v[120:123]
	v_mfma_f32_16x16x32_bf16 v[108:111], v[156:159], v[184:187], v[108:111]
	v_mfma_f32_16x16x32_bf16 v[104:107], v[164:167], v[184:187], v[104:107]
	v_mfma_f32_16x16x32_bf16 v[92:95], v[156:159], v[192:195], v[92:95]
	v_mfma_f32_16x16x32_bf16 v[88:91], v[164:167], v[192:195], v[88:91]
	v_mfma_f32_16x16x32_bf16 v[76:79], v[156:159], v[200:203], v[76:79]
	v_mfma_f32_16x16x32_bf16 v[72:75], v[164:167], v[200:203], v[72:75]
	v_mfma_f32_16x16x32_bf16 v[116:119], v[204:207], v[168:171], v[116:119]
	v_mfma_f32_16x16x32_bf16 v[112:115], v[212:215], v[168:171], v[112:115]
	v_mfma_f32_16x16x32_bf16 v[100:103], v[204:207], v[176:179], v[100:103]
	v_mfma_f32_16x16x32_bf16 v[96:99], v[212:215], v[176:179], v[96:99]
	v_mfma_f32_16x16x32_bf16 v[84:87], v[204:207], v[188:191], v[84:87]
	v_mfma_f32_16x16x32_bf16 v[80:83], v[212:215], v[188:191], v[80:83]
	v_mfma_f32_16x16x32_bf16 v[68:71], v[204:207], v[196:199], v[68:71]
	v_mfma_f32_16x16x32_bf16 v[64:67], v[212:215], v[196:199], v[64:67]
	v_mfma_f32_16x16x32_bf16 v[116:119], v[208:211], v[172:175], v[116:119]
	v_mfma_f32_16x16x32_bf16 v[112:115], v[216:219], v[172:175], v[112:115]
	v_mfma_f32_16x16x32_bf16 v[100:103], v[208:211], v[184:187], v[100:103]
	v_mfma_f32_16x16x32_bf16 v[96:99], v[216:219], v[184:187], v[96:99]
	v_mfma_f32_16x16x32_bf16 v[84:87], v[208:211], v[192:195], v[84:87]
	v_mfma_f32_16x16x32_bf16 v[80:83], v[216:219], v[192:195], v[80:83]
	v_mfma_f32_16x16x32_bf16 v[68:71], v[208:211], v[200:203], v[68:71]
	v_mfma_f32_16x16x32_bf16 v[64:67], v[216:219], v[200:203], v[64:67]
	s_setprio 0
	s_barrier
	s_add_i32 s51, s42, s27
	v_lshl_add_u64 v[144:145], s[18:19], 0, v[132:133]
	s_mov_b32 m0, s51
	s_nop 0
	global_load_lds_dwordx4 v[144:145], off
	v_lshl_add_u64 v[144:145], s[18:19], 0, v[130:131]
	s_add_i32 m0, s51, 0x2000
	s_nop 0
	global_load_lds_dwordx4 v[144:145], off
	s_mov_b32 m0, s30
	v_lshl_add_u64 v[144:145], s[22:23], 0, v[132:133]
	ds_read_b128 v[168:171], v149 offset:16384
	ds_read_b128 v[172:175], v149 offset:17408
	ds_read_b128 v[176:179], v149 offset:18432
	ds_read_b128 v[184:187], v149 offset:19456
	ds_read_b128 v[188:191], v149 offset:20480
	ds_read_b128 v[192:195], v149 offset:21504
	ds_read_b128 v[196:199], v149 offset:22528
	ds_read_b128 v[200:203], v149 offset:23552
	global_load_lds_dwordx4 v[144:145], off
	v_lshl_add_u64 v[144:145], s[22:23], 0, v[130:131]
	s_mov_b32 m0, s31
	s_nop 0
	global_load_lds_dwordx4 v[144:145], off
	s_add_u32 s54, s18, 0x4000
	s_addc_u32 s55, s19, 0
	s_add_i32 s51, s43, s27
	v_lshl_add_u64 v[144:145], s[54:55], 0, v[132:133]
	s_mov_b32 m0, s51
	s_nop 0
	global_load_lds_dwordx4 v[144:145], off
	v_lshl_add_u64 v[144:145], s[54:55], 0, v[130:131]
	s_add_i32 m0, s51, 0x2000
	s_nop 0
	global_load_lds_dwordx4 v[144:145], off
	s_waitcnt lgkmcnt(0)
	s_waitcnt vmcnt(8)
	s_barrier
; #define PG8_STAGE(bufoff, gbase, voff) do { _Pragma("unroll") for (int _i = 0; _i < 2; ++_i) \
;         __builtin_amdgcn_global_load_lds((const unsigned*)((const char*)(gbase) + (voff)[_i]), (LAS unsigned*)(lds + (bufoff) + ldsw + _i * 8192), 16, 0, 0); } while (0)
; #define PG8_LDA(dst, b, h) do { _Pragma("unroll") for (int m = 0; m < 4; ++m) _Pragma("unroll") for (int k = 0; k < 2; ++k) dst[m][k] = *(const LAS bf16x8*)(lds + PG8_SA(b, h) + aoff + m * 2048 + k * 1024); } while (0)
; #define PG8_LDB(dst, b, h) do { _Pragma("unroll") for (int n = 0; n < 2; ++n) _Pragma("unroll") for (int k = 0; k < 2; ++k) dst[n][k] = *(const LAS bf16x8*)(lds + PG8_SB(b, h) + boff + n * 2048 + k * 1024); } while (0)
; #define PG8_MMA(ai, bj, At, Bt) do { __builtin_amdgcn_s_setprio(1); _Pragma("unroll") for (int m = 0; m < 4; ++m) _Pragma("unroll") for (int n = 0; n < 2; ++n) _Pragma("unroll") for (int k = 0; k < 2; ++k) \
;         acc[ai][bj][m][n] = __builtin_amdgcn_mfma_f32_16x16x32_bf16(Bt[n][k], At[m][k], acc[ai][bj][m][n], 0, 0, 0); __builtin_amdgcn_s_setprio(0); } while (0)
; #define PG8_WAIT_V(n) asm volatile("s_waitcnt vmcnt(" #n ")" ::: "memory")
; #define PG8_WAIT_L(n) asm volatile("s_waitcnt lgkmcnt(" #n ")" ::: "memory")
; #define PG8_BAR __builtin_amdgcn_s_barrier()
; #define PG8_SCHED __builtin_amdgcn_sched_barrier(0)
; template <class Epi>
; __device__ __forceinline__ void gemm_phase(LAS unsigned char* lds, const Gemm g, const StaticOrder& S, const Epi& E) {
;     ...
;             PG8_BAR; PG8_WAIT_L(0); PG8_MMA(1, 0, At, B0); PG8_BAR; PG8_SCHED;
;             PG8_STAGE(PG8_SB(0, 1), b2 + hstep, voffB);
;             PG8_WAIT_V(6); PG8_BAR; PG8_MMA(1, 1, At, B1); PG8_BAR;
;             PG8_LDB(B0, 1, 0); PG8_SCHED; PG8_LDA(At, 1, 0); PG8_STAGE(PG8_SA(0, 1), a2 + hstep, voffA);
;             PG8_WAIT_L(8); PG8_BAR; PG8_WAIT_L(0); PG8_MMA(0, 0, At, B0); PG8_BAR; PG8_SCHED;
;             PG8_LDB(B1, 1, 1); PG8_STAGE(PG8_SB(1, 0), b3, voffB);
;             PG8_BAR; PG8_WAIT_L(0); PG8_MMA(0, 1, At, B1); PG8_BAR;
;             PG8_LDA(At, 1, 1); PG8_STAGE(PG8_SA(1, 0), a3, voffA);
;             PG8_BAR; PG8_WAIT_L(0); PG8_MMA(1, 0, At, B0); PG8_BAR; PG8_SCHED;
	s_setprio 1
	v_mfma_f32_16x16x32_bf16 v[60:63], v[152:155], v[168:171], v[60:63]
	v_mfma_f32_16x16x32_bf16 v[56:59], v[160:163], v[168:171], v[56:59]
	v_mfma_f32_16x16x32_bf16 v[44:47], v[152:155], v[176:179], v[44:47]
	v_mfma_f32_16x16x32_bf16 v[40:43], v[160:163], v[176:179], v[40:43]
	v_mfma_f32_16x16x32_bf16 v[28:31], v[152:155], v[188:191], v[28:31]
	v_mfma_f32_16x16x32_bf16 v[24:27], v[160:163], v[188:191], v[24:27]
	v_mfma_f32_16x16x32_bf16 v[12:15], v[152:155], v[196:199], v[12:15]
	v_mfma_f32_16x16x32_bf16 v[8:11], v[160:163], v[196:199], v[8:11]
	v_mfma_f32_16x16x32_bf16 v[60:63], v[156:159], v[172:175], v[60:63]
	v_mfma_f32_16x16x32_bf16 v[56:59], v[164:167], v[172:175], v[56:59]
	v_mfma_f32_16x16x32_bf16 v[44:47], v[156:159], v[184:187], v[44:47]
	v_mfma_f32_16x16x32_bf16 v[40:43], v[164:167], v[184:187], v[40:43]
	v_mfma_f32_16x16x32_bf16 v[28:31], v[156:159], v[192:195], v[28:31]
	v_mfma_f32_16x16x32_bf16 v[24:27], v[164:167], v[192:195], v[24:27]
	v_mfma_f32_16x16x32_bf16 v[12:15], v[156:159], v[200:203], v[12:15]
	v_mfma_f32_16x16x32_bf16 v[8:11], v[164:167], v[200:203], v[8:11]
	v_mfma_f32_16x16x32_bf16 v[52:55], v[204:207], v[168:171], v[52:55]
	v_mfma_f32_16x16x32_bf16 v[48:51], v[212:215], v[168:171], v[48:51]
	v_mfma_f32_16x16x32_bf16 v[36:39], v[204:207], v[176:179], v[36:39]
	v_mfma_f32_16x16x32_bf16 v[32:35], v[212:215], v[176:179], v[32:35]
	v_mfma_f32_16x16x32_bf16 v[20:23], v[204:207], v[188:191], v[20:23]
	v_mfma_f32_16x16x32_bf16 v[16:19], v[212:215], v[188:191], v[16:19]
	v_mfma_f32_16x16x32_bf16 v[4:7], v[204:207], v[196:199], v[4:7]
	v_mfma_f32_16x16x32_bf16 v[0:3], v[212:215], v[196:199], v[0:3]
	v_mfma_f32_16x16x32_bf16 v[52:55], v[208:211], v[172:175], v[52:55]
	v_mfma_f32_16x16x32_bf16 v[48:51], v[216:219], v[172:175], v[48:51]
	v_mfma_f32_16x16x32_bf16 v[36:39], v[208:211], v[184:187], v[36:39]
	v_mfma_f32_16x16x32_bf16 v[32:35], v[216:219], v[184:187], v[32:35]
	v_mfma_f32_16x16x32_bf16 v[20:23], v[208:211], v[192:195], v[20:23]
	v_mfma_f32_16x16x32_bf16 v[16:19], v[216:219], v[192:195], v[16:19]
	v_mfma_f32_16x16x32_bf16 v[4:7], v[208:211], v[200:203], v[4:7]
	v_mfma_f32_16x16x32_bf16 v[0:3], v[216:219], v[200:203], v[0:3]
	s_setprio 0
	s_add_i32 s51, 0, 0x18000
	v_add_u32_e32 v144, s51, v147
	s_barrier
	ds_read_b128 v[152:155], v144
	ds_read_b128 v[156:159], v144 offset:1024
	ds_read_b128 v[160:163], v144 offset:2048
	ds_read_b128 v[164:167], v144 offset:3072
	s_add_u32 s22, s22, 0x4000
	s_addc_u32 s23, s23, 0
	s_mov_b32 m0, s34
	v_lshl_add_u64 v[144:145], s[22:23], 0, v[132:133]
	ds_read_b128 v[168:171], v149 offset:32768
	ds_read_b128 v[172:175], v149 offset:33792
	ds_read_b128 v[176:179], v149 offset:34816
	ds_read_b128 v[184:187], v149 offset:35840
	ds_read_b128 v[188:191], v149 offset:36864
	ds_read_b128 v[192:195], v149 offset:37888
	ds_read_b128 v[196:199], v149 offset:38912
	ds_read_b128 v[200:203], v149 offset:39936
	global_load_lds_dwordx4 v[144:145], off
	v_lshl_add_u64 v[144:145], s[22:23], 0, v[130:131]
	s_mov_b32 m0, s35
	s_nop 0
	global_load_lds_dwordx4 v[144:145], off
	v_add_u32_e32 v253, 0x1c000, v147
	ds_read_b128 v[204:207], v253
	ds_read_b128 v[208:211], v253 offset:1024
	ds_read_b128 v[212:215], v253 offset:2048
	ds_read_b128 v[216:219], v253 offset:3072
	s_waitcnt lgkmcnt(0)
	s_waitcnt vmcnt(8)
	s_barrier
	s_setprio 1
	v_mfma_f32_16x16x32_bf16 v[124:127], v[152:155], v[168:171], v[124:127]
	v_mfma_f32_16x16x32_bf16 v[120:123], v[160:163], v[168:171], v[120:123]
	v_mfma_f32_16x16x32_bf16 v[108:111], v[152:155], v[176:179], v[108:111]
	v_mfma_f32_16x16x32_bf16 v[104:107], v[160:163], v[176:179], v[104:107]
	v_mfma_f32_16x16x32_bf16 v[92:95], v[152:155], v[188:191], v[92:95]
	v_mfma_f32_16x16x32_bf16 v[88:91], v[160:163], v[188:191], v[88:91]
	v_mfma_f32_16x16x32_bf16 v[76:79], v[152:155], v[196:199], v[76:79]
	v_mfma_f32_16x16x32_bf16 v[72:75], v[160:163], v[196:199], v[72:75]
	v_mfma_f32_16x16x32_bf16 v[124:127], v[156:159], v[172:175], v[124:127]
	v_mfma_f32_16x16x32_bf16 v[120:123], v[164:167], v[172:175], v[120:123]
	v_mfma_f32_16x16x32_bf16 v[108:111], v[156:159], v[184:187], v[108:111]
	v_mfma_f32_16x16x32_bf16 v[104:107], v[164:167], v[184:187], v[104:107]
	v_mfma_f32_16x16x32_bf16 v[92:95], v[156:159], v[192:195], v[92:95]
	v_mfma_f32_16x16x32_bf16 v[88:91], v[164:167], v[192:195], v[88:91]
	v_mfma_f32_16x16x32_bf16 v[76:79], v[156:159], v[200:203], v[76:79]
	v_mfma_f32_16x16x32_bf16 v[72:75], v[164:167], v[200:203], v[72:75]
	v_mfma_f32_16x16x32_bf16 v[116:119], v[204:207], v[168:171], v[116:119]
	v_mfma_f32_16x16x32_bf16 v[112:115], v[212:215], v[168:171], v[112:115]
	v_mfma_f32_16x16x32_bf16 v[100:103], v[204:207], v[176:179], v[100:103]
	v_mfma_f32_16x16x32_bf16 v[96:99], v[212:215], v[176:179], v[96:99]
	v_mfma_f32_16x16x32_bf16 v[84:87], v[204:207], v[188:191], v[84:87]
	v_mfma_f32_16x16x32_bf16 v[80:83], v[212:215], v[188:191], v[80:83]
	v_mfma_f32_16x16x32_bf16 v[68:71], v[204:207], v[196:199], v[68:71]
	v_mfma_f32_16x16x32_bf16 v[64:67], v[212:215], v[196:199], v[64:67]
	v_mfma_f32_16x16x32_bf16 v[116:119], v[208:211], v[172:175], v[116:119]
	v_mfma_f32_16x16x32_bf16 v[112:115], v[216:219], v[172:175], v[112:115]
	v_mfma_f32_16x16x32_bf16 v[100:103], v[208:211], v[184:187], v[100:103]
	v_mfma_f32_16x16x32_bf16 v[96:99], v[216:219], v[184:187], v[96:99]
	v_mfma_f32_16x16x32_bf16 v[84:87], v[208:211], v[192:195], v[84:87]
	v_mfma_f32_16x16x32_bf16 v[80:83], v[216:219], v[192:195], v[80:83]
	v_mfma_f32_16x16x32_bf16 v[68:71], v[208:211], v[200:203], v[68:71]
	v_mfma_f32_16x16x32_bf16 v[64:67], v[216:219], v[200:203], v[64:67]
	s_setprio 0
	s_barrier
; __device__ __forceinline__ unsigned pk_bf16(float lo, float hi) { unsigned r; asm("v_cvt_pk_bf16_f32 %0, %1, %2" : "=v"(r) : "v"(lo), "v"(hi)); return r; }
; __device__ __forceinline__ size_t blk_off(int row, int col, int nrows) { return ((size_t)(col >> 6) * nrows + row) * 64 + (col & 63); }
; __device__ __forceinline__ float sigmoidf_fast(float v) { return __builtin_amdgcn_rcpf(1.0f + __expf(-v)); }
; #define PG8_STAGE(bufoff, gbase, voff) do { _Pragma("unroll") for (int _i = 0; _i < 2; ++_i) \
;         __builtin_amdgcn_global_load_lds((const unsigned*)((const char*)(gbase) + (voff)[_i]), (LAS unsigned*)(lds + (bufoff) + ldsw + _i * 8192), 16, 0, 0); } while (0)
; #define PG8_WAIT_V(n) asm volatile("s_waitcnt vmcnt(" #n ")" ::: "memory")
;     __device__ __forceinline__ void operator()(const f32x4 (&acc)[2][2][4][2], const Unit& u, int wr, int wc, int fr, int fq) const {
;         const int row0 = u.pm * BM + wr * 64 + fr; const int col0 = u.pn * HALF + wc * 32 + 8 * fq;
; #pragma unroll
;         for (int ai = 0; ai < 2; ++ai)
; #pragma unroll
;             for (int m = 0; m < 4; ++m) { bf16_t* rowp = O + blk_off(row0 + ai * HALF + m * 16, col0, nrows);
;                 float v[8];
; #pragma unroll
;                 for (int bj = 0; bj < 2; ++bj)
; #pragma unroll
;                     for (int j = 0; j < 4; ++j) { const float g = acc[ai][bj][m][0][j], up = acc[ai][bj][m][1][j]; v[bj * 4 + j] = g * sigmoidf_fast(g) * up; }
;                 u32x4 w; w.x = pk_bf16(v[0], v[1]); w.y = pk_bf16(v[2], v[3]); w.z = pk_bf16(v[4], v[5]); w.w = pk_bf16(v[6], v[7]);
; template <class Epi>
; __device__ __forceinline__ void gemm_phase(LAS unsigned char* lds, const Gemm g, const StaticOrder& S, const Epi& E) {
;     ...
;             PG8_LDB(B0, 1, 0); PG8_SCHED; PG8_LDA(At, 1, 0); PG8_STAGE(PG8_SA(0, 1), a2 + hstep, voffA);
;             PG8_WAIT_L(8); PG8_BAR; PG8_WAIT_L(0); PG8_MMA(0, 0, At, B0); PG8_BAR; PG8_SCHED;
;             PG8_LDB(B1, 1, 1); PG8_STAGE(PG8_SB(1, 0), b3, voffB);
;             PG8_BAR; PG8_WAIT_L(0); PG8_MMA(0, 1, At, B1); PG8_BAR;
;             PG8_LDA(At, 1, 1); PG8_STAGE(PG8_SA(1, 0), a3, voffA);
;             PG8_BAR; PG8_WAIT_L(0); PG8_MMA(1, 0, At, B0); PG8_BAR; PG8_SCHED;
;             PG8_STAGE(PG8_SB(1, 1), b3 + hstep, voffB);
;             PG8_WAIT_V(6); PG8_BAR; PG8_MMA(1, 1, At, B1); PG8_BAR;
;         }
	s_add_i32 s54, 0, 0x1c000
	s_add_u32 s22, s18, 0x160000
	v_add_u32_e32 v144, s54, v147
	s_addc_u32 s23, s19, 0
	s_add_i32 s51, s51, s27
	s_nop 0
	v_lshl_add_u64 v[144:145], s[22:23], 0, v[132:133]
	s_mov_b32 m0, s51
	s_nop 0
	global_load_lds_dwordx4 v[144:145], off
	v_lshl_add_u64 v[144:145], s[22:23], 0, v[130:131]
	s_add_i32 m0, s51, 0x2000
	s_nop 0
	global_load_lds_dwordx4 v[144:145], off
	s_mov_b32 m0, s38
	v_lshl_add_u64 v[144:145], s[20:21], 0, v[132:133]
	ds_read_b128 v[168:171], v149 offset:49152
	ds_read_b128 v[172:175], v149 offset:50176
	ds_read_b128 v[176:179], v149 offset:51200
	ds_read_b128 v[184:187], v149 offset:52224
	ds_read_b128 v[188:191], v149 offset:53248
	ds_read_b128 v[192:195], v149 offset:54272
	ds_read_b128 v[196:199], v149 offset:55296
	ds_read_b128 v[200:203], v149 offset:56320
	global_load_lds_dwordx4 v[144:145], off
	v_lshl_add_u64 v[144:145], s[20:21], 0, v[130:131]
	s_mov_b32 m0, s39
	s_nop 0
	global_load_lds_dwordx4 v[144:145], off
	s_add_u32 s18, s18, 0x164000
	s_addc_u32 s19, s19, 0
	s_add_i32 s20, s54, s27
	v_lshl_add_u64 v[144:145], s[18:19], 0, v[132:133]
	s_mov_b32 m0, s20
	s_nop 0
	global_load_lds_dwordx4 v[144:145], off
	v_lshl_add_u64 v[144:145], s[18:19], 0, v[130:131]
	s_add_i32 m0, s20, 0x2000
	s_nop 0
	global_load_lds_dwordx4 v[144:145], off
	s_waitcnt lgkmcnt(0)
	s_waitcnt vmcnt(8)
	s_barrier
	s_setprio 1
	v_mfma_f32_16x16x32_bf16 v[60:63], v[152:155], v[168:171], v[60:63]
	v_mfma_f32_16x16x32_bf16 v[56:59], v[160:163], v[168:171], v[56:59]
	v_mfma_f32_16x16x32_bf16 v[44:47], v[152:155], v[176:179], v[44:47]
	v_mfma_f32_16x16x32_bf16 v[40:43], v[160:163], v[176:179], v[40:43]
	v_mfma_f32_16x16x32_bf16 v[28:31], v[152:155], v[188:191], v[28:31]
	v_mfma_f32_16x16x32_bf16 v[24:27], v[160:163], v[188:191], v[24:27]
	v_mfma_f32_16x16x32_bf16 v[12:15], v[152:155], v[196:199], v[12:15]
	v_mfma_f32_16x16x32_bf16 v[8:11], v[160:163], v[196:199], v[8:11]
	v_mfma_f32_16x16x32_bf16 v[60:63], v[156:159], v[172:175], v[60:63]
	v_mfma_f32_16x16x32_bf16 v[56:59], v[164:167], v[172:175], v[56:59]
	v_mfma_f32_16x16x32_bf16 v[44:47], v[156:159], v[184:187], v[44:47]
	v_mfma_f32_16x16x32_bf16 v[40:43], v[164:167], v[184:187], v[40:43]
	v_mfma_f32_16x16x32_bf16 v[28:31], v[156:159], v[192:195], v[28:31]
	v_mfma_f32_16x16x32_bf16 v[24:27], v[164:167], v[192:195], v[24:27]
	v_mfma_f32_16x16x32_bf16 v[12:15], v[156:159], v[200:203], v[12:15]
	v_mfma_f32_16x16x32_bf16 v[8:11], v[164:167], v[200:203], v[8:11]
	v_mfma_f32_16x16x32_bf16 v[52:55], v[204:207], v[168:171], v[52:55]
	v_mfma_f32_16x16x32_bf16 v[48:51], v[212:215], v[168:171], v[48:51]
	v_mfma_f32_16x16x32_bf16 v[36:39], v[204:207], v[176:179], v[36:39]
	v_mfma_f32_16x16x32_bf16 v[32:35], v[212:215], v[176:179], v[32:35]
	v_mfma_f32_16x16x32_bf16 v[20:23], v[204:207], v[188:191], v[20:23]
	v_mfma_f32_16x16x32_bf16 v[16:19], v[212:215], v[188:191], v[16:19]
	v_mfma_f32_16x16x32_bf16 v[4:7], v[204:207], v[196:199], v[4:7]
	v_mfma_f32_16x16x32_bf16 v[0:3], v[212:215], v[196:199], v[0:3]
	v_mfma_f32_16x16x32_bf16 v[52:55], v[208:211], v[172:175], v[52:55]
	v_mfma_f32_16x16x32_bf16 v[48:51], v[216:219], v[172:175], v[48:51]
	v_mfma_f32_16x16x32_bf16 v[36:39], v[208:211], v[184:187], v[36:39]
	v_mfma_f32_16x16x32_bf16 v[32:35], v[216:219], v[184:187], v[32:35]
	v_mfma_f32_16x16x32_bf16 v[20:23], v[208:211], v[192:195], v[20:23]
	v_mfma_f32_16x16x32_bf16 v[16:19], v[216:219], v[192:195], v[16:19]
	v_mfma_f32_16x16x32_bf16 v[4:7], v[208:211], v[200:203], v[4:7]
	v_mfma_f32_16x16x32_bf16 v[0:3], v[216:219], v[200:203], v[0:3]
	s_setprio 0
	s_add_i32 s50, s50, 2
	s_add_u32 s48, s48, 0x2c0000
	s_addc_u32 s49, s49, 0
	s_add_u32 s16, s16, 0x800000
	s_addc_u32 s17, s17, 0
	s_cmp_gt_u32 s50, 29
	s_barrier
	s_cbranch_scc0 .LBB0_885
	s_lshl_b32 s1, s15, 7
	v_mul_f32_e32 v151, 0xbfb8aa3b, v124
	s_or_b32 s1, s1, s37
	v_exp_f32_e32 v151, v151
	v_mul_f32_e32 v152, 0xbfb8aa3b, v125
	v_lshl_add_u32 v144, s14, 8, v146
	s_ashr_i32 s14, s1, 6
	v_exp_f32_e32 v154, v152
	s_ashr_i32 s15, s14, 31
	s_lshl_b64 s[14:15], s[14:15], 15
	v_ashrrev_i32_e32 v145, 31, v144
	v_lshl_add_u64 v[152:153], s[14:15], 0, v[144:145]
	v_add_f32_e32 v145, 1.0, v151
	v_rcp_f32_e32 v145, v145
	v_add_f32_e32 v151, 1.0, v154
	v_rcp_f32_e32 v151, v151
	v_lshlrev_b64 v[152:153], 7, v[152:153]
	v_mul_f32_e32 v124, v124, v145
	v_mul_f32_e32 v120, v120, v124
	v_mul_f32_e32 v124, v125, v151
	v_mul_f32_e32 v125, 0xbfb8aa3b, v126
	v_exp_f32_e32 v125, v125
	v_mul_f32_e32 v145, 0xbfb8aa3b, v127
	v_exp_f32_e32 v145, v145
	v_mul_f32_e32 v121, v121, v124
	v_add_f32_e32 v124, 1.0, v125
	v_rcp_f32_e32 v124, v124
	v_add_f32_e32 v125, 1.0, v145
	v_mul_f32_e32 v145, 0xbfb8aa3b, v116
	v_rcp_f32_e32 v125, v125
	v_exp_f32_e32 v145, v145
	v_mul_f32_e32 v124, v126, v124
	v_mul_f32_e32 v122, v122, v124
	v_mul_f32_e32 v124, v127, v125
	v_add_f32_e32 v125, 1.0, v145
	v_rcp_f32_e32 v125, v125
	v_mul_f32_e32 v126, 0xbfb8aa3b, v117
	v_exp_f32_e32 v126, v126
	v_mul_f32_e32 v123, v123, v124
	v_mul_f32_e32 v116, v116, v125
	v_mul_f32_e32 v124, v112, v116
	v_mul_f32_e32 v116, 0xbfb8aa3b, v118
	v_add_f32_e32 v112, 1.0, v126
	v_exp_f32_e32 v116, v116
	v_mul_f32_e32 v125, 0xbfb8aa3b, v119
	v_rcp_f32_e32 v112, v112
	v_exp_f32_e32 v125, v125
	v_add_f32_e32 v116, 1.0, v116
	v_rcp_f32_e32 v116, v116
	v_mul_f32_e32 v112, v117, v112
	v_add_f32_e32 v117, 1.0, v125
	v_rcp_f32_e32 v117, v117
	v_mul_f32_e32 v125, v113, v112
	v_mul_f32_e32 v112, v118, v116
	v_mul_f32_e32 v118, v114, v112
	v_mul_f32_e32 v112, v119, v117
	v_mul_f32_e32 v115, v115, v112
	v_lshl_add_u64 v[116:117], v[134:135], 0, v[152:153]
	v_cvt_pk_bf16_f32 v114, v124, v125
; __device__ __forceinline__ unsigned pk_bf16(float lo, float hi) { unsigned r; asm("v_cvt_pk_bf16_f32 %0, %1, %2" : "=v"(r) : "v"(lo), "v"(hi)); return r; }
; __device__ __forceinline__ size_t blk_off(int row, int col, int nrows) { return ((size_t)(col >> 6) * nrows + row) * 64 + (col & 63); }
; __device__ __forceinline__ float sigmoidf_fast(float v) { return __builtin_amdgcn_rcpf(1.0f + __expf(-v)); }
;     __device__ __forceinline__ void operator()(const f32x4 (&acc)[2][2][4][2], const Unit& u, int wr, int wc, int fr, int fq) const {
;         const int row0 = u.pm * BM + wr * 64 + fr; const int col0 = u.pn * HALF + wc * 32 + 8 * fq;
; #pragma unroll
;         for (int ai = 0; ai < 2; ++ai)
; #pragma unroll
;             for (int m = 0; m < 4; ++m) { bf16_t* rowp = O + blk_off(row0 + ai * HALF + m * 16, col0, nrows);
;                 float v[8];
; #pragma unroll
;                 for (int bj = 0; bj < 2; ++bj)
; #pragma unroll
;                     for (int j = 0; j < 4; ++j) { const float g = acc[ai][bj][m][0][j], up = acc[ai][bj][m][1][j]; v[bj * 4 + j] = g * sigmoidf_fast(g) * up; }
;                 u32x4 w; w.x = pk_bf16(v[0], v[1]); w.y = pk_bf16(v[2], v[3]); w.z = pk_bf16(v[4], v[5]); w.w = pk_bf16(v[6], v[7]);
;                 *(u32x4*)rowp = w; }
	v_cvt_pk_bf16_f32 v112, v120, v121
	v_cvt_pk_bf16_f32 v113, v122, v123
	v_cvt_pk_bf16_f32 v115, v118, v115
	global_store_dwordx4 v[116:117], v[112:115], off
	s_and_b64 vcc, exec, s[6:7]
	s_mov_b64 s[16:17], s[12:13]
	v_mul_f32_e32 v114, 0xbfb8aa3b, v108
	v_exp_f32_e32 v114, v114
	v_mul_f32_e32 v115, 0xbfb8aa3b, v109
	v_exp_f32_e32 v115, v115
	v_or_b32_e32 v112, 16, v144
	v_add_f32_e32 v114, 1.0, v114
	v_rcp_f32_e32 v114, v114
	v_add_f32_e32 v115, 1.0, v115
	v_rcp_f32_e32 v115, v115
	v_ashrrev_i32_e32 v113, 31, v112
	v_mul_f32_e32 v108, v108, v114
	v_mul_f32_e32 v104, v104, v108
	v_mul_f32_e32 v108, v109, v115
	v_mul_f32_e32 v109, 0xbfb8aa3b, v110
	v_exp_f32_e32 v109, v109
	v_mul_f32_e32 v114, 0xbfb8aa3b, v111
	v_exp_f32_e32 v114, v114
	v_mul_f32_e32 v105, v105, v108
	v_add_f32_e32 v108, 1.0, v109
	v_rcp_f32_e32 v108, v108
	v_add_f32_e32 v109, 1.0, v114
	v_mul_f32_e32 v114, 0xbfb8aa3b, v100
	v_rcp_f32_e32 v109, v109
	v_exp_f32_e32 v114, v114
	v_mul_f32_e32 v108, v110, v108
	v_mul_f32_e32 v106, v106, v108
	v_mul_f32_e32 v108, v111, v109
	v_add_f32_e32 v109, 1.0, v114
	v_rcp_f32_e32 v109, v109
	v_mul_f32_e32 v110, 0xbfb8aa3b, v101
	v_exp_f32_e32 v110, v110
	v_mul_f32_e32 v107, v107, v108
	v_mul_f32_e32 v100, v100, v109
	v_mul_f32_e32 v108, v96, v100
	v_mul_f32_e32 v100, 0xbfb8aa3b, v102
	v_add_f32_e32 v96, 1.0, v110
	v_exp_f32_e32 v100, v100
	v_mul_f32_e32 v109, 0xbfb8aa3b, v103
	v_rcp_f32_e32 v96, v96
	v_exp_f32_e32 v109, v109
	v_add_f32_e32 v100, 1.0, v100
	v_rcp_f32_e32 v100, v100
	v_mul_f32_e32 v96, v101, v96
	v_add_f32_e32 v101, 1.0, v109
	v_rcp_f32_e32 v101, v101
	v_lshl_add_u64 v[112:113], s[14:15], 0, v[112:113]
	v_mul_f32_e32 v109, v97, v96
	v_mul_f32_e32 v96, v102, v100
	v_lshlrev_b64 v[112:113], 7, v[112:113]
	v_mul_f32_e32 v102, v98, v96
	v_mul_f32_e32 v96, v103, v101
	v_mul_f32_e32 v99, v99, v96
	v_lshl_add_u64 v[100:101], v[134:135], 0, v[112:113]
	v_cvt_pk_bf16_f32 v98, v108, v109
	v_cvt_pk_bf16_f32 v96, v104, v105
	v_cvt_pk_bf16_f32 v97, v106, v107
	v_cvt_pk_bf16_f32 v99, v102, v99
	global_store_dwordx4 v[100:101], v[96:99], off
	s_mov_b64 s[18:19], s[10:11]
	s_nop 0
	v_mul_f32_e32 v98, 0xbfb8aa3b, v92
	v_exp_f32_e32 v98, v98
	v_mul_f32_e32 v99, 0xbfb8aa3b, v93
	v_exp_f32_e32 v99, v99
	v_or_b32_e32 v96, 32, v144
	v_add_f32_e32 v98, 1.0, v98
	v_rcp_f32_e32 v98, v98
	v_add_f32_e32 v99, 1.0, v99
	v_rcp_f32_e32 v99, v99
	v_ashrrev_i32_e32 v97, 31, v96
	v_mul_f32_e32 v92, v92, v98
	v_mul_f32_e32 v88, v88, v92
	v_mul_f32_e32 v92, v93, v99
	v_mul_f32_e32 v93, 0xbfb8aa3b, v94
	v_exp_f32_e32 v93, v93
	v_mul_f32_e32 v98, 0xbfb8aa3b, v95
	v_exp_f32_e32 v98, v98
	v_mul_f32_e32 v89, v89, v92
	v_add_f32_e32 v92, 1.0, v93
	v_rcp_f32_e32 v92, v92
	v_add_f32_e32 v93, 1.0, v98
	v_mul_f32_e32 v98, 0xbfb8aa3b, v84
	v_rcp_f32_e32 v93, v93
	v_exp_f32_e32 v98, v98
	v_mul_f32_e32 v92, v94, v92
	v_mul_f32_e32 v90, v90, v92
	v_mul_f32_e32 v92, v95, v93
	v_add_f32_e32 v93, 1.0, v98
	v_rcp_f32_e32 v93, v93
	v_mul_f32_e32 v94, 0xbfb8aa3b, v85
	v_exp_f32_e32 v94, v94
	v_mul_f32_e32 v91, v91, v92
	v_mul_f32_e32 v84, v84, v93
	v_mul_f32_e32 v92, v80, v84
	v_mul_f32_e32 v84, 0xbfb8aa3b, v86
	v_add_f32_e32 v80, 1.0, v94
	v_exp_f32_e32 v84, v84
	v_mul_f32_e32 v93, 0xbfb8aa3b, v87
	v_rcp_f32_e32 v80, v80
	v_exp_f32_e32 v93, v93
	v_add_f32_e32 v84, 1.0, v84
	v_rcp_f32_e32 v84, v84
	v_mul_f32_e32 v80, v85, v80
	v_add_f32_e32 v85, 1.0, v93
	v_rcp_f32_e32 v85, v85
	v_lshl_add_u64 v[96:97], s[14:15], 0, v[96:97]
	v_mul_f32_e32 v93, v81, v80
	v_mul_f32_e32 v80, v86, v84
	v_lshlrev_b64 v[96:97], 7, v[96:97]
	v_mul_f32_e32 v86, v82, v80
	v_mul_f32_e32 v80, v87, v85
	v_mul_f32_e32 v83, v83, v80
	v_lshl_add_u64 v[84:85], v[134:135], 0, v[96:97]
	v_cvt_pk_bf16_f32 v82, v92, v93
	v_cvt_pk_bf16_f32 v80, v88, v89
	v_cvt_pk_bf16_f32 v81, v90, v91
	v_cvt_pk_bf16_f32 v83, v86, v83
	global_store_dwordx4 v[84:85], v[80:83], off
	s_nop 1
	v_mul_f32_e32 v82, 0xbfb8aa3b, v76
	v_exp_f32_e32 v82, v82
	v_mul_f32_e32 v83, 0xbfb8aa3b, v77
	v_exp_f32_e32 v83, v83
	v_or_b32_e32 v80, 48, v144
	v_add_f32_e32 v82, 1.0, v82
	v_rcp_f32_e32 v82, v82
	v_add_f32_e32 v83, 1.0, v83
	v_rcp_f32_e32 v83, v83
	v_ashrrev_i32_e32 v81, 31, v80
	v_mul_f32_e32 v76, v76, v82
	v_mul_f32_e32 v72, v72, v76
	v_mul_f32_e32 v76, v77, v83
	v_mul_f32_e32 v77, 0xbfb8aa3b, v78
	v_exp_f32_e32 v77, v77
	v_mul_f32_e32 v82, 0xbfb8aa3b, v79
	v_exp_f32_e32 v82, v82
	v_mul_f32_e32 v73, v73, v76
	v_add_f32_e32 v76, 1.0, v77
	v_rcp_f32_e32 v76, v76
	v_add_f32_e32 v77, 1.0, v82
	v_mul_f32_e32 v82, 0xbfb8aa3b, v68
	v_rcp_f32_e32 v77, v77
	v_exp_f32_e32 v82, v82
	v_mul_f32_e32 v76, v78, v76
	v_mul_f32_e32 v74, v74, v76
	v_mul_f32_e32 v76, v79, v77
	v_add_f32_e32 v77, 1.0, v82
	v_rcp_f32_e32 v77, v77
	v_mul_f32_e32 v78, 0xbfb8aa3b, v69
	v_exp_f32_e32 v78, v78
	v_mul_f32_e32 v75, v75, v76
	v_mul_f32_e32 v68, v68, v77
	v_mul_f32_e32 v76, v64, v68
	v_mul_f32_e32 v68, 0xbfb8aa3b, v70
	v_add_f32_e32 v64, 1.0, v78
	v_exp_f32_e32 v68, v68
	v_mul_f32_e32 v77, 0xbfb8aa3b, v71
	v_rcp_f32_e32 v64, v64
	v_exp_f32_e32 v77, v77
	v_add_f32_e32 v68, 1.0, v68
	v_rcp_f32_e32 v68, v68
	v_mul_f32_e32 v64, v69, v64
	v_add_f32_e32 v69, 1.0, v77
	v_rcp_f32_e32 v69, v69
	v_lshl_add_u64 v[80:81], s[14:15], 0, v[80:81]
	v_mul_f32_e32 v77, v65, v64
	v_mul_f32_e32 v64, v70, v68
	v_lshlrev_b64 v[80:81], 7, v[80:81]
	v_mul_f32_e32 v70, v66, v64
	v_mul_f32_e32 v64, v71, v69
	v_mul_f32_e32 v67, v67, v64
	v_lshl_add_u64 v[68:69], v[134:135], 0, v[80:81]
	v_cvt_pk_bf16_f32 v66, v76, v77
	v_cvt_pk_bf16_f32 v64, v72, v73
	v_cvt_pk_bf16_f32 v65, v74, v75
	v_cvt_pk_bf16_f32 v67, v70, v67
	global_store_dwordx4 v[68:69], v[64:67], off
	s_nop 1
	v_mul_f32_e32 v66, 0xbfb8aa3b, v60
; __device__ __forceinline__ unsigned pk_bf16(float lo, float hi) { unsigned r; asm("v_cvt_pk_bf16_f32 %0, %1, %2" : "=v"(r) : "v"(lo), "v"(hi)); return r; }
; __device__ __forceinline__ size_t blk_off(int row, int col, int nrows) { return ((size_t)(col >> 6) * nrows + row) * 64 + (col & 63); }
; __device__ __forceinline__ float sigmoidf_fast(float v) { return __builtin_amdgcn_rcpf(1.0f + __expf(-v)); }
;     __device__ __forceinline__ void operator()(const f32x4 (&acc)[2][2][4][2], const Unit& u, int wr, int wc, int fr, int fq) const {
;         const int row0 = u.pm * BM + wr * 64 + fr; const int col0 = u.pn * HALF + wc * 32 + 8 * fq;
; #pragma unroll
;         for (int ai = 0; ai < 2; ++ai)
; #pragma unroll
;             for (int m = 0; m < 4; ++m) { bf16_t* rowp = O + blk_off(row0 + ai * HALF + m * 16, col0, nrows);
;                 float v[8];
; #pragma unroll
;                 for (int bj = 0; bj < 2; ++bj)
; #pragma unroll
;                     for (int j = 0; j < 4; ++j) { const float g = acc[ai][bj][m][0][j], up = acc[ai][bj][m][1][j]; v[bj * 4 + j] = g * sigmoidf_fast(g) * up; }
;                 u32x4 w; w.x = pk_bf16(v[0], v[1]); w.y = pk_bf16(v[2], v[3]); w.z = pk_bf16(v[4], v[5]); w.w = pk_bf16(v[6], v[7]);
;                 *(u32x4*)rowp = w; }
;     }
	v_exp_f32_e32 v66, v66
	v_mul_f32_e32 v67, 0xbfb8aa3b, v61
	v_exp_f32_e32 v67, v67
	v_add_u32_e32 v64, 0x80, v144
	v_add_f32_e32 v66, 1.0, v66
	v_rcp_f32_e32 v66, v66
	v_add_f32_e32 v67, 1.0, v67
	v_rcp_f32_e32 v67, v67
	v_ashrrev_i32_e32 v65, 31, v64
	v_mul_f32_e32 v60, v60, v66
	v_mul_f32_e32 v56, v56, v60
	v_mul_f32_e32 v60, v61, v67
	v_mul_f32_e32 v61, 0xbfb8aa3b, v62
	v_exp_f32_e32 v61, v61
	v_mul_f32_e32 v66, 0xbfb8aa3b, v63
	v_exp_f32_e32 v66, v66
	v_mul_f32_e32 v57, v57, v60
	v_add_f32_e32 v60, 1.0, v61
	v_rcp_f32_e32 v60, v60
	v_add_f32_e32 v61, 1.0, v66
	v_mul_f32_e32 v66, 0xbfb8aa3b, v52
	v_rcp_f32_e32 v61, v61
	v_exp_f32_e32 v66, v66
	v_mul_f32_e32 v60, v62, v60
	v_mul_f32_e32 v58, v58, v60
	v_mul_f32_e32 v60, v63, v61
	v_add_f32_e32 v61, 1.0, v66
	v_rcp_f32_e32 v61, v61
	v_mul_f32_e32 v62, 0xbfb8aa3b, v53
	v_exp_f32_e32 v62, v62
	v_mul_f32_e32 v59, v59, v60
	v_mul_f32_e32 v52, v52, v61
	v_mul_f32_e32 v60, v48, v52
	v_mul_f32_e32 v52, 0xbfb8aa3b, v54
	v_add_f32_e32 v48, 1.0, v62
	v_exp_f32_e32 v52, v52
	v_mul_f32_e32 v61, 0xbfb8aa3b, v55
	v_rcp_f32_e32 v48, v48
	v_exp_f32_e32 v61, v61
	v_add_f32_e32 v52, 1.0, v52
	v_rcp_f32_e32 v52, v52
	v_mul_f32_e32 v48, v53, v48
	v_add_f32_e32 v53, 1.0, v61
	v_rcp_f32_e32 v53, v53
	v_lshl_add_u64 v[64:65], s[14:15], 0, v[64:65]
	v_mul_f32_e32 v61, v49, v48
	v_mul_f32_e32 v48, v54, v52
	v_lshlrev_b64 v[64:65], 7, v[64:65]
	v_mul_f32_e32 v54, v50, v48
	v_mul_f32_e32 v48, v55, v53
	v_mul_f32_e32 v51, v51, v48
	v_lshl_add_u64 v[52:53], v[134:135], 0, v[64:65]
	v_cvt_pk_bf16_f32 v50, v60, v61
	v_cvt_pk_bf16_f32 v48, v56, v57
	v_cvt_pk_bf16_f32 v49, v58, v59
	v_cvt_pk_bf16_f32 v51, v54, v51
	global_store_dwordx4 v[52:53], v[48:51], off
	s_nop 1
	v_mul_f32_e32 v50, 0xbfb8aa3b, v44
	v_exp_f32_e32 v50, v50
	v_mul_f32_e32 v51, 0xbfb8aa3b, v45
	v_exp_f32_e32 v51, v51
	v_add_u32_e32 v48, 0x90, v144
	v_add_f32_e32 v50, 1.0, v50
	v_rcp_f32_e32 v50, v50
	v_add_f32_e32 v51, 1.0, v51
	v_rcp_f32_e32 v51, v51
	v_ashrrev_i32_e32 v49, 31, v48
	v_mul_f32_e32 v44, v44, v50
	v_mul_f32_e32 v40, v40, v44
	v_mul_f32_e32 v44, v45, v51
	v_mul_f32_e32 v45, 0xbfb8aa3b, v46
	v_exp_f32_e32 v45, v45
	v_mul_f32_e32 v50, 0xbfb8aa3b, v47
	v_exp_f32_e32 v50, v50
	v_mul_f32_e32 v41, v41, v44
	v_add_f32_e32 v44, 1.0, v45
	v_rcp_f32_e32 v44, v44
	v_add_f32_e32 v45, 1.0, v50
	v_mul_f32_e32 v50, 0xbfb8aa3b, v36
	v_rcp_f32_e32 v45, v45
	v_exp_f32_e32 v50, v50
	v_mul_f32_e32 v44, v46, v44
	v_mul_f32_e32 v42, v42, v44
	v_mul_f32_e32 v44, v47, v45
	v_add_f32_e32 v45, 1.0, v50
	v_rcp_f32_e32 v45, v45
	v_mul_f32_e32 v46, 0xbfb8aa3b, v37
	v_exp_f32_e32 v46, v46
	v_mul_f32_e32 v43, v43, v44
	v_mul_f32_e32 v36, v36, v45
	v_mul_f32_e32 v44, v32, v36
	v_mul_f32_e32 v36, 0xbfb8aa3b, v38
	v_add_f32_e32 v32, 1.0, v46
	v_exp_f32_e32 v36, v36
	v_mul_f32_e32 v45, 0xbfb8aa3b, v39
	v_rcp_f32_e32 v32, v32
	v_exp_f32_e32 v45, v45
	v_add_f32_e32 v36, 1.0, v36
	v_rcp_f32_e32 v36, v36
	v_mul_f32_e32 v32, v37, v32
	v_add_f32_e32 v37, 1.0, v45
	v_rcp_f32_e32 v37, v37
	v_lshl_add_u64 v[48:49], s[14:15], 0, v[48:49]
	v_mul_f32_e32 v45, v33, v32
	v_mul_f32_e32 v32, v38, v36
	v_lshlrev_b64 v[48:49], 7, v[48:49]
	v_mul_f32_e32 v38, v34, v32
	v_mul_f32_e32 v32, v39, v37
	v_mul_f32_e32 v35, v35, v32
	v_lshl_add_u64 v[36:37], v[134:135], 0, v[48:49]
	v_cvt_pk_bf16_f32 v34, v44, v45
	v_cvt_pk_bf16_f32 v32, v40, v41
	v_cvt_pk_bf16_f32 v33, v42, v43
	v_cvt_pk_bf16_f32 v35, v38, v35
	global_store_dwordx4 v[36:37], v[32:35], off
	s_nop 1
	v_mul_f32_e32 v34, 0xbfb8aa3b, v28
	v_exp_f32_e32 v34, v34
	v_mul_f32_e32 v35, 0xbfb8aa3b, v29
	v_exp_f32_e32 v35, v35
	v_add_u32_e32 v32, 0xa0, v144
	v_add_f32_e32 v34, 1.0, v34
	v_rcp_f32_e32 v34, v34
	v_add_f32_e32 v35, 1.0, v35
	v_rcp_f32_e32 v35, v35
	v_ashrrev_i32_e32 v33, 31, v32
	v_mul_f32_e32 v28, v28, v34
	v_mul_f32_e32 v24, v24, v28
	v_mul_f32_e32 v28, v29, v35
	v_mul_f32_e32 v29, 0xbfb8aa3b, v30
	v_exp_f32_e32 v29, v29
	v_mul_f32_e32 v34, 0xbfb8aa3b, v31
	v_exp_f32_e32 v34, v34
	v_mul_f32_e32 v25, v25, v28
	v_add_f32_e32 v28, 1.0, v29
	v_rcp_f32_e32 v28, v28
	v_add_f32_e32 v29, 1.0, v34
	v_mul_f32_e32 v34, 0xbfb8aa3b, v20
	v_rcp_f32_e32 v29, v29
	v_exp_f32_e32 v34, v34
	v_mul_f32_e32 v28, v30, v28
	v_mul_f32_e32 v26, v26, v28
	v_mul_f32_e32 v28, v31, v29
	v_add_f32_e32 v29, 1.0, v34
	v_rcp_f32_e32 v29, v29
	v_mul_f32_e32 v30, 0xbfb8aa3b, v21
	v_exp_f32_e32 v30, v30
	v_mul_f32_e32 v27, v27, v28
	v_mul_f32_e32 v20, v20, v29
	v_mul_f32_e32 v28, v16, v20
	v_mul_f32_e32 v20, 0xbfb8aa3b, v22
	v_add_f32_e32 v16, 1.0, v30
	v_exp_f32_e32 v20, v20
	v_mul_f32_e32 v29, 0xbfb8aa3b, v23
	v_rcp_f32_e32 v16, v16
	v_exp_f32_e32 v29, v29
	v_add_f32_e32 v20, 1.0, v20
	v_rcp_f32_e32 v20, v20
	v_mul_f32_e32 v16, v21, v16
	v_add_f32_e32 v21, 1.0, v29
	v_rcp_f32_e32 v21, v21
	v_lshl_add_u64 v[32:33], s[14:15], 0, v[32:33]
	v_mul_f32_e32 v29, v17, v16
	v_mul_f32_e32 v16, v22, v20
	v_lshlrev_b64 v[32:33], 7, v[32:33]
	v_mul_f32_e32 v22, v18, v16
	v_mul_f32_e32 v16, v23, v21
	v_mul_f32_e32 v19, v19, v16
	v_lshl_add_u64 v[20:21], v[134:135], 0, v[32:33]
	v_cvt_pk_bf16_f32 v18, v28, v29
	v_cvt_pk_bf16_f32 v16, v24, v25
	v_cvt_pk_bf16_f32 v17, v26, v27
	v_cvt_pk_bf16_f32 v19, v22, v19
	global_store_dwordx4 v[20:21], v[16:19], off
	s_nop 1
	v_mul_f32_e32 v18, 0xbfb8aa3b, v12
	v_exp_f32_e32 v18, v18
	v_mul_f32_e32 v19, 0xbfb8aa3b, v13
	v_exp_f32_e32 v19, v19
	v_add_u32_e32 v16, 0xb0, v144
	v_add_f32_e32 v18, 1.0, v18
	v_rcp_f32_e32 v18, v18
	v_add_f32_e32 v19, 1.0, v19
	v_rcp_f32_e32 v19, v19
	v_ashrrev_i32_e32 v17, 31, v16
	v_mul_f32_e32 v12, v12, v18
	v_mul_f32_e32 v8, v8, v12
	v_mul_f32_e32 v12, v13, v19
	v_mul_f32_e32 v13, 0xbfb8aa3b, v14
	v_exp_f32_e32 v13, v13
	v_mul_f32_e32 v18, 0xbfb8aa3b, v15
	v_exp_f32_e32 v18, v18
	v_mul_f32_e32 v9, v9, v12
	v_add_f32_e32 v12, 1.0, v13
	v_rcp_f32_e32 v12, v12
	v_add_f32_e32 v13, 1.0, v18
	v_mul_f32_e32 v18, 0xbfb8aa3b, v4
	v_rcp_f32_e32 v13, v13
	v_exp_f32_e32 v18, v18
	v_mul_f32_e32 v12, v14, v12
	v_mul_f32_e32 v10, v10, v12
	v_mul_f32_e32 v12, v15, v13
	v_add_f32_e32 v13, 1.0, v18
	v_rcp_f32_e32 v13, v13
	v_mul_f32_e32 v14, 0xbfb8aa3b, v5
	v_exp_f32_e32 v14, v14
	v_mul_f32_e32 v11, v11, v12
	v_mul_f32_e32 v4, v4, v13
	v_mul_f32_e32 v12, v0, v4
	v_mul_f32_e32 v4, 0xbfb8aa3b, v6
	v_add_f32_e32 v0, 1.0, v14
	v_exp_f32_e32 v4, v4
	v_mul_f32_e32 v13, 0xbfb8aa3b, v7
	v_rcp_f32_e32 v0, v0
	v_exp_f32_e32 v13, v13
	v_add_f32_e32 v4, 1.0, v4
	v_rcp_f32_e32 v4, v4
	v_mul_f32_e32 v0, v5, v0
	v_add_f32_e32 v5, 1.0, v13
	v_rcp_f32_e32 v5, v5
	v_lshl_add_u64 v[16:17], s[14:15], 0, v[16:17]
	v_mul_f32_e32 v13, v1, v0
	v_mul_f32_e32 v0, v6, v4
	v_lshlrev_b64 v[16:17], 7, v[16:17]
	v_mul_f32_e32 v6, v2, v0
	v_mul_f32_e32 v0, v7, v5
	v_mul_f32_e32 v3, v3, v0
	v_lshl_add_u64 v[4:5], v[134:135], 0, v[16:17]
	s_mov_b32 s15, s0
	s_mov_b32 s14, s8
	v_cvt_pk_bf16_f32 v0, v8, v9
	v_cvt_pk_bf16_f32 v1, v10, v11
	v_cvt_pk_bf16_f32 v2, v12, v13
	v_cvt_pk_bf16_f32 v3, v6, v3
	global_store_dwordx4 v[4:5], v[0:3], off
	s_cbranch_vccz .LBB0_882
; #define PG8_WAIT_V(n) asm volatile("s_waitcnt vmcnt(" #n ")" ::: "memory")
; #define PG8_BAR __builtin_amdgcn_s_barrier()
; template <class Epi>
; __device__ __forceinline__ void gemm_phase(LAS unsigned char* lds, const Gemm g, const StaticOrder& S, const Epi& E) {
;     ...
;     PG8_WAIT_V(0);
;     if (wr == 0) PG8_BAR;
;     PG8_BAR;
	s_waitcnt vmcnt(0)
	s_cmpk_gt_u32 s24, 0xff
	s_cbranch_scc1 .LBB0_889
	s_barrier

; #define PG8_STAGE(bufoff, gbase, voff) do { _Pragma("unroll") for (int _i = 0; _i < 2; ++_i) \
;         __builtin_amdgcn_global_load_lds((const unsigned*)((const char*)(gbase) + (voff)[_i]), (LAS unsigned*)(lds + (bufoff) + ldsw + _i * 8192), 16, 0, 0); } while (0)
; #define PG8_WAIT_V(n) asm volatile("s_waitcnt vmcnt(" #n ")" ::: "memory")
; #define PG8_BAR __builtin_amdgcn_s_barrier()
; template <class Epi>
; __device__ __forceinline__ void gemm_phase(LAS unsigned char* lds, const Gemm g, const StaticOrder& S, const Epi& E) {
;     ...
;     for (int i = 0; i < 2; ++i) { int R, C; stage_rc(tid * 16 + i * 8192, R, C); const int Rb = Epi::PERM ? ((R & ~31) + perm32(R & 31)) : R;
;         voffA[i] = (unsigned)(R * BK + C) * 2u; voffB[i] = (unsigned)(Rb * BK + C) * 2u; }
;     const size_t kstepA = (size_t)g.M * BK * 2, kstepB = (size_t)g.N * BK * 2;
;     const size_t hstep = (size_t)HALF * BK * 2;
;     const size_t tstep = 2 * hstep;
;     const unsigned ldsw = (unsigned)wid * 1024u;
;     const int aoff = lds_byte(wr * 64 + fr, fq * 8), boff = lds_byte(wc * 32 + fr, fq * 8);
;     ...
;     const char* cA = (const char*)g.A + (size_t)cur.pm * tstep; const char* cB = (const char*)g.Bt + (size_t)cur.pn * tstep;
;     PG8_STAGE(PG8_SB(0, 0), cB, voffB); PG8_STAGE(PG8_SA(0, 0), cA, voffA); PG8_STAGE(PG8_SB(0, 1), cB + hstep, voffB); PG8_STAGE(PG8_SA(0, 1), cA + hstep, voffA);
;     if (wr == 1) PG8_BAR;
;     PG8_WAIT_V(4); PG8_BAR;
;     PG8_STAGE(PG8_SB(1, 0), cB + kstepB, voffB); PG8_STAGE(PG8_SA(1, 0), cA + kstepA, voffA); PG8_STAGE(PG8_SB(1, 1), cB + hstep + kstepB, voffB);
;     PG8_WAIT_V(6); PG8_BAR;
.LBB0_949:
	s_lshl_b32 s1, s1, 5
	s_and_b32 s1, s1, 0x60
	s_lshl_b32 s5, s4, 13
	s_lshl_b32 s8, s1, 7
	s_add_u32 s6, s22, 0x40000
	s_addc_u32 s7, s23, 0
	s_add_i32 m0, s21, 0x18000
	v_lshl_add_u64 v[8:9], s[6:7], 0, v[132:133]
	s_waitcnt vmcnt(2)
	s_barrier
	global_load_lds_dwordx4 v[8:9], off
	s_add_i32 m0, s21, 0x1a000
	v_lshl_add_u64 v[8:9], s[6:7], 0, v[136:137]
	s_add_u32 s6, s24, 0x400000
	s_addc_u32 s7, s25, 0
	s_add_i32 s41, s21, 0x8000
	global_load_lds_dwordx4 v[8:9], off
	v_lshl_add_u64 v[8:9], s[6:7], 0, v[130:131]
	s_mov_b32 m0, s41
	s_add_i32 s42, s21, 0xa000
	global_load_lds_dwordx4 v[8:9], off
	v_lshl_add_u64 v[8:9], s[6:7], 0, v[134:135]
	s_add_u32 s6, s22, 0x44000
	s_mov_b32 m0, s42
	s_addc_u32 s7, s23, 0
	global_load_lds_dwordx4 v[8:9], off
	s_add_i32 m0, s21, 0x1c000
	v_lshl_add_u64 v[8:9], s[6:7], 0, v[132:133]
	global_load_lds_dwordx4 v[8:9], off
	v_lshl_add_u64 v[8:9], s[6:7], 0, v[136:137]
	s_add_i32 m0, s21, 0x1e000
	v_and_b32_e32 v7, 15, v0
	global_load_lds_dwordx4 v[8:9], off
	v_lshrrev_b32_e32 v8, 1, v0
	v_and_b32_e32 v8, 24, v8
	v_lshlrev_b32_e32 v9, 1, v8
	v_lshlrev_b32_e32 v0, 2, v0
	v_lshl_or_b32 v148, s4, 6, v7
	v_lshl_or_b32 v7, v7, 6, v9
	v_and_b32_e32 v0, 32, v0
	v_bitop3_b32 v9, v7, s5, v0 bitop3:0xde
	v_bitop3_b32 v149, v7, s8, v0 bitop3:0xde
	v_lshlrev_b32_e32 v0, 10, v1
	v_and_b32_e32 v0, 0xfffff800, v0
	v_lshl_add_u32 v0, v2, 7, v0
	v_and_b32_e32 v1, 1, v1
	v_lshl_or_b32 v0, v1, 6, v0
	v_lshl_add_u32 v138, v3, 1, v0
	v_lshlrev_b32_e32 v0, 10, v4
	v_and_b32_e32 v0, 0xfffff800, v0
	s_waitcnt vmcnt(6)
	v_lshl_add_u32 v0, v5, 7, v0
	v_and_b32_e32 v1, 1, v4
	v_lshl_or_b32 v0, v1, 6, v0
	s_add_i32 s45, 0, 0x10000
	s_add_i32 s48, 0, 0x14000
	s_sext_i32_i8 s55, s0
	s_ashr_i32 s43, s86, 31
	s_mov_b32 s44, s86
	v_or_b32_e32 v150, s1, v8
	v_mov_b32_e32 v139, v133
	v_lshl_add_u32 v140, v6, 1, v0
	v_mov_b32_e32 v141, v133
	v_mov_b64_e32 v[142:143], 0x400
	v_mov_b64_e32 v[144:145], 0x3ff
	s_mov_b64 s[0:1], 0x80000
	v_add_u32_e32 v151, s45, v149
	v_add_u32_e32 v152, 0, v9
	v_add_u32_e32 v153, s48, v149
	s_mov_b32 s49, 0x80000
	s_mov_b64 s[6:7], 0x90000
	s_mov_b32 s50, 0x90000
	s_mov_b64 s[8:9], 0xa0000
	s_mov_b32 s51, 0xa0000
	s_mov_b64 s[10:11], 0xb0000
	s_mov_b32 s54, 0xb0000
	s_barrier

; #define PG8_STAGE(bufoff, gbase, voff) do { _Pragma("unroll") for (int _i = 0; _i < 2; ++_i) \
;         __builtin_amdgcn_global_load_lds((const unsigned*)((const char*)(gbase) + (voff)[_i]), (LAS unsigned*)(lds + (bufoff) + ldsw + _i * 8192), 16, 0, 0); } while (0)
; #define PG8_LDA(dst, b, h) do { _Pragma("unroll") for (int m = 0; m < 4; ++m) _Pragma("unroll") for (int k = 0; k < 2; ++k) dst[m][k] = *(const LAS bf16x8*)(lds + PG8_SA(b, h) + aoff + m * 2048 + k * 1024); } while (0)
; #define PG8_LDB(dst, b, h) do { _Pragma("unroll") for (int n = 0; n < 2; ++n) _Pragma("unroll") for (int k = 0; k < 2; ++k) dst[n][k] = *(const LAS bf16x8*)(lds + PG8_SB(b, h) + boff + n * 2048 + k * 1024); } while (0)
; #define PG8_MMA(ai, bj, At, Bt) do { __builtin_amdgcn_s_setprio(1); _Pragma("unroll") for (int m = 0; m < 4; ++m) _Pragma("unroll") for (int n = 0; n < 2; ++n) _Pragma("unroll") for (int k = 0; k < 2; ++k) \
;         acc[ai][bj][m][n] = __builtin_amdgcn_mfma_f32_16x16x32_bf16(Bt[n][k], At[m][k], acc[ai][bj][m][n], 0, 0, 0); __builtin_amdgcn_s_setprio(0); } while (0)
; #define PG8_WAIT_V(n) asm volatile("s_waitcnt vmcnt(" #n ")" ::: "memory")
; #define PG8_WAIT_L(n) asm volatile("s_waitcnt lgkmcnt(" #n ")" ::: "memory")
; template <class Epi>
; __device__ __forceinline__ void gemm_phase(LAS unsigned char* lds, const Gemm g, const StaticOrder& S, const Epi& E) {
;     ...
;         for (int t = 0; t < nt; t += 2) {
;             const bool last = (t == nt - 2);
;             const char* a1 = cA + (size_t)(t + 1) * kstepA;
;             const char* a2 = last ? nA : cA + (size_t)(t + 2) * kstepA; const char* b2 = last ? nB : cB + (size_t)(t + 2) * kstepB;
;             const char* a3 = a2 + kstepA; const char* b3 = b2 + kstepB;
;             PG8_LDB(B0, 0, 0); PG8_SCHED; PG8_LDA(At, 0, 0); PG8_STAGE(PG8_SA(1, 1), a1 + hstep, voffA);
;             PG8_WAIT_L(8); PG8_BAR; PG8_WAIT_L(0); PG8_MMA(0, 0, At, B0); PG8_BAR; PG8_SCHED;
;             PG8_LDB(B1, 0, 1); PG8_STAGE(PG8_SB(0, 0), b2, voffB);
;             PG8_BAR; PG8_WAIT_L(0); PG8_MMA(0, 1, At, B1); PG8_BAR;
;             PG8_LDA(At, 0, 1); PG8_STAGE(PG8_SA(0, 0), a2, voffA);
;             PG8_BAR; PG8_WAIT_L(0); PG8_MMA(1, 0, At, B0); PG8_BAR; PG8_SCHED;
;             PG8_STAGE(PG8_SB(0, 1), b2 + hstep, voffB);
;             PG8_WAIT_V(6); PG8_BAR; PG8_MMA(1, 1, At, B1); PG8_BAR;
.LBB0_957:
	ds_read_b128 v[154:157], v151
	ds_read_b128 v[158:161], v151 offset:1024
	ds_read_b128 v[162:165], v151 offset:2048
	ds_read_b128 v[166:169], v151 offset:3072
	s_add_u32 s24, s22, 0x3fc000
	s_addc_u32 s25, s23, 0
	s_cmpk_eq_i32 s60, 0x54
	s_cselect_b32 s28, s56, s24
	s_cselect_b32 s29, s15, s25
	s_cselect_b32 s25, s13, s59
	s_cselect_b32 s24, s57, s58
	s_add_u32 s26, s28, 0x400000
	s_addc_u32 s27, s29, 0
	v_lshl_add_u64 v[146:147], s[22:23], 0, v[138:139]
	s_add_i32 m0, s21, 0xc000
	ds_read_b128 v[170:173], v152
	ds_read_b128 v[174:177], v152 offset:1024
	ds_read_b128 v[184:187], v152 offset:2048
	ds_read_b128 v[188:191], v152 offset:3072
	ds_read_b128 v[192:195], v152 offset:4096
	ds_read_b128 v[196:199], v152 offset:5120
	ds_read_b128 v[200:203], v152 offset:6144
	ds_read_b128 v[204:207], v152 offset:7168
	global_load_lds_dwordx4 v[146:147], off
	v_lshl_add_u64 v[146:147], s[22:23], 0, v[140:141]
	s_add_i32 m0, s21, 0xe000
	s_nop 0
	global_load_lds_dwordx4 v[146:147], off
	ds_read_b128 v[208:211], v153
	ds_read_b128 v[212:215], v153 offset:1024
	ds_read_b128 v[216:219], v153 offset:2048
	ds_read_b128 v[220:223], v153 offset:3072
	s_waitcnt lgkmcnt(0)
	s_waitcnt vmcnt(8)
	s_barrier
	s_setprio 1
	v_mfma_f32_16x16x32_bf16 v[124:127], v[154:157], v[170:173], v[124:127]
	v_mfma_f32_16x16x32_bf16 v[120:123], v[162:165], v[170:173], v[120:123]
	v_mfma_f32_16x16x32_bf16 v[112:115], v[154:157], v[184:187], v[112:115]
	v_mfma_f32_16x16x32_bf16 v[104:107], v[162:165], v[184:187], v[104:107]
	v_mfma_f32_16x16x32_bf16 v[96:99], v[154:157], v[192:195], v[96:99]
	v_mfma_f32_16x16x32_bf16 v[88:91], v[162:165], v[192:195], v[88:91]
	v_mfma_f32_16x16x32_bf16 v[80:83], v[154:157], v[200:203], v[80:83]
	v_mfma_f32_16x16x32_bf16 v[72:75], v[162:165], v[200:203], v[72:75]
	v_mfma_f32_16x16x32_bf16 v[124:127], v[158:161], v[174:177], v[124:127]
	v_mfma_f32_16x16x32_bf16 v[120:123], v[166:169], v[174:177], v[120:123]
	v_mfma_f32_16x16x32_bf16 v[112:115], v[158:161], v[188:191], v[112:115]
	v_mfma_f32_16x16x32_bf16 v[104:107], v[166:169], v[188:191], v[104:107]
	v_mfma_f32_16x16x32_bf16 v[96:99], v[158:161], v[196:199], v[96:99]
	v_mfma_f32_16x16x32_bf16 v[88:91], v[166:169], v[196:199], v[88:91]
	v_mfma_f32_16x16x32_bf16 v[80:83], v[158:161], v[204:207], v[80:83]
	v_mfma_f32_16x16x32_bf16 v[72:75], v[166:169], v[204:207], v[72:75]
	v_mfma_f32_16x16x32_bf16 v[116:119], v[208:211], v[170:173], v[116:119]
	v_mfma_f32_16x16x32_bf16 v[108:111], v[216:219], v[170:173], v[108:111]
	v_mfma_f32_16x16x32_bf16 v[100:103], v[208:211], v[184:187], v[100:103]
	v_mfma_f32_16x16x32_bf16 v[92:95], v[216:219], v[184:187], v[92:95]
	v_mfma_f32_16x16x32_bf16 v[84:87], v[208:211], v[192:195], v[84:87]
	v_mfma_f32_16x16x32_bf16 v[76:79], v[216:219], v[192:195], v[76:79]
	v_mfma_f32_16x16x32_bf16 v[68:71], v[208:211], v[200:203], v[68:71]
	v_mfma_f32_16x16x32_bf16 v[64:67], v[216:219], v[200:203], v[64:67]
	v_mfma_f32_16x16x32_bf16 v[116:119], v[212:215], v[174:177], v[116:119]
	v_mfma_f32_16x16x32_bf16 v[108:111], v[220:223], v[174:177], v[108:111]
	v_mfma_f32_16x16x32_bf16 v[100:103], v[212:215], v[188:191], v[100:103]
	v_mfma_f32_16x16x32_bf16 v[92:95], v[220:223], v[188:191], v[92:95]
	v_mfma_f32_16x16x32_bf16 v[84:87], v[212:215], v[196:199], v[84:87]
	v_mfma_f32_16x16x32_bf16 v[76:79], v[220:223], v[196:199], v[76:79]
	v_mfma_f32_16x16x32_bf16 v[68:71], v[212:215], v[204:207], v[68:71]
	v_mfma_f32_16x16x32_bf16 v[64:67], v[220:223], v[204:207], v[64:67]
	s_setprio 0
	s_barrier
	s_add_i32 s61, s45, s36
	v_lshl_add_u64 v[146:147], s[24:25], 0, v[132:133]
	s_mov_b32 m0, s61
	s_nop 0
	global_load_lds_dwordx4 v[146:147], off
	v_lshl_add_u64 v[146:147], s[24:25], 0, v[136:137]
	s_add_i32 m0, s61, 0x2000
	s_nop 0
	global_load_lds_dwordx4 v[146:147], off
	s_mov_b32 m0, s21
	v_lshl_add_u64 v[146:147], s[28:29], 0, v[130:131]
	ds_read_b128 v[170:173], v152 offset:16384
	ds_read_b128 v[174:177], v152 offset:17408
	ds_read_b128 v[184:187], v152 offset:18432
	ds_read_b128 v[188:191], v152 offset:19456
	ds_read_b128 v[192:195], v152 offset:20480
	ds_read_b128 v[196:199], v152 offset:21504
	ds_read_b128 v[200:203], v152 offset:22528
	ds_read_b128 v[204:207], v152 offset:23552
	global_load_lds_dwordx4 v[146:147], off
	v_lshl_add_u64 v[146:147], s[28:29], 0, v[134:135]
	s_mov_b32 m0, s37
	s_nop 0
	global_load_lds_dwordx4 v[146:147], off
	s_add_u32 s62, s24, 0x4000
	s_addc_u32 s63, s25, 0
	s_add_i32 s61, s48, s36
	v_lshl_add_u64 v[146:147], s[62:63], 0, v[132:133]
	s_mov_b32 m0, s61
	s_nop 0
	global_load_lds_dwordx4 v[146:147], off
	v_lshl_add_u64 v[146:147], s[62:63], 0, v[136:137]
	s_add_i32 m0, s61, 0x2000
	s_nop 0
	global_load_lds_dwordx4 v[146:147], off
	s_waitcnt lgkmcnt(0)
	s_waitcnt vmcnt(8)
	s_barrier
; #define PG8_STAGE(bufoff, gbase, voff) do { _Pragma("unroll") for (int _i = 0; _i < 2; ++_i) \
;         __builtin_amdgcn_global_load_lds((const unsigned*)((const char*)(gbase) + (voff)[_i]), (LAS unsigned*)(lds + (bufoff) + ldsw + _i * 8192), 16, 0, 0); } while (0)
; #define PG8_LDA(dst, b, h) do { _Pragma("unroll") for (int m = 0; m < 4; ++m) _Pragma("unroll") for (int k = 0; k < 2; ++k) dst[m][k] = *(const LAS bf16x8*)(lds + PG8_SA(b, h) + aoff + m * 2048 + k * 1024); } while (0)
; #define PG8_LDB(dst, b, h) do { _Pragma("unroll") for (int n = 0; n < 2; ++n) _Pragma("unroll") for (int k = 0; k < 2; ++k) dst[n][k] = *(const LAS bf16x8*)(lds + PG8_SB(b, h) + boff + n * 2048 + k * 1024); } while (0)
; #define PG8_MMA(ai, bj, At, Bt) do { __builtin_amdgcn_s_setprio(1); _Pragma("unroll") for (int m = 0; m < 4; ++m) _Pragma("unroll") for (int n = 0; n < 2; ++n) _Pragma("unroll") for (int k = 0; k < 2; ++k) \
;         acc[ai][bj][m][n] = __builtin_amdgcn_mfma_f32_16x16x32_bf16(Bt[n][k], At[m][k], acc[ai][bj][m][n], 0, 0, 0); __builtin_amdgcn_s_setprio(0); } while (0)
; #define PG8_WAIT_V(n) asm volatile("s_waitcnt vmcnt(" #n ")" ::: "memory")
; #define PG8_WAIT_L(n) asm volatile("s_waitcnt lgkmcnt(" #n ")" ::: "memory")
; #define PG8_BAR __builtin_amdgcn_s_barrier()
; #define PG8_SCHED __builtin_amdgcn_sched_barrier(0)
; template <class Epi>
; __device__ __forceinline__ void gemm_phase(LAS unsigned char* lds, const Gemm g, const StaticOrder& S, const Epi& E) {
;     ...
;             PG8_BAR; PG8_WAIT_L(0); PG8_MMA(1, 0, At, B0); PG8_BAR; PG8_SCHED;
;             PG8_STAGE(PG8_SB(0, 1), b2 + hstep, voffB);
;             PG8_WAIT_V(6); PG8_BAR; PG8_MMA(1, 1, At, B1); PG8_BAR;
;             PG8_LDB(B0, 1, 0); PG8_SCHED; PG8_LDA(At, 1, 0); PG8_STAGE(PG8_SA(0, 1), a2 + hstep, voffA);
;             PG8_WAIT_L(8); PG8_BAR; PG8_WAIT_L(0); PG8_MMA(0, 0, At, B0); PG8_BAR; PG8_SCHED;
;             PG8_LDB(B1, 1, 1); PG8_STAGE(PG8_SB(1, 0), b3, voffB);
;             PG8_BAR; PG8_WAIT_L(0); PG8_MMA(0, 1, At, B1); PG8_BAR;
;             PG8_LDA(At, 1, 1); PG8_STAGE(PG8_SA(1, 0), a3, voffA);
;             PG8_BAR; PG8_WAIT_L(0); PG8_MMA(1, 0, At, B0); PG8_BAR; PG8_SCHED;
	s_setprio 1
	v_mfma_f32_16x16x32_bf16 v[60:63], v[154:157], v[170:173], v[60:63]
	v_mfma_f32_16x16x32_bf16 v[56:59], v[162:165], v[170:173], v[56:59]
	v_mfma_f32_16x16x32_bf16 v[52:55], v[154:157], v[184:187], v[52:55]
	v_mfma_f32_16x16x32_bf16 v[44:47], v[162:165], v[184:187], v[44:47]
	v_mfma_f32_16x16x32_bf16 v[36:39], v[154:157], v[192:195], v[36:39]
	v_mfma_f32_16x16x32_bf16 v[28:31], v[162:165], v[192:195], v[28:31]
	v_mfma_f32_16x16x32_bf16 v[20:23], v[154:157], v[200:203], v[20:23]
	v_mfma_f32_16x16x32_bf16 v[12:15], v[162:165], v[200:203], v[12:15]
	v_mfma_f32_16x16x32_bf16 v[60:63], v[158:161], v[174:177], v[60:63]
	v_mfma_f32_16x16x32_bf16 v[56:59], v[166:169], v[174:177], v[56:59]
	v_mfma_f32_16x16x32_bf16 v[52:55], v[158:161], v[188:191], v[52:55]
	v_mfma_f32_16x16x32_bf16 v[44:47], v[166:169], v[188:191], v[44:47]
	v_mfma_f32_16x16x32_bf16 v[36:39], v[158:161], v[196:199], v[36:39]
	v_mfma_f32_16x16x32_bf16 v[28:31], v[166:169], v[196:199], v[28:31]
	v_mfma_f32_16x16x32_bf16 v[20:23], v[158:161], v[204:207], v[20:23]
	v_mfma_f32_16x16x32_bf16 v[12:15], v[166:169], v[204:207], v[12:15]
	v_mfma_f32_16x16x32_bf16 v[48:51], v[208:211], v[170:173], v[48:51]
	v_mfma_f32_16x16x32_bf16 v[40:43], v[216:219], v[170:173], v[40:43]
	v_mfma_f32_16x16x32_bf16 v[32:35], v[208:211], v[184:187], v[32:35]
	v_mfma_f32_16x16x32_bf16 v[24:27], v[216:219], v[184:187], v[24:27]
	v_mfma_f32_16x16x32_bf16 v[16:19], v[208:211], v[192:195], v[16:19]
	v_mfma_f32_16x16x32_bf16 v[8:11], v[216:219], v[192:195], v[8:11]
	v_mfma_f32_16x16x32_bf16 v[4:7], v[208:211], v[200:203], v[4:7]
	v_mfma_f32_16x16x32_bf16 v[0:3], v[216:219], v[200:203], v[0:3]
	v_mfma_f32_16x16x32_bf16 v[48:51], v[212:215], v[174:177], v[48:51]
	v_mfma_f32_16x16x32_bf16 v[40:43], v[220:223], v[174:177], v[40:43]
	v_mfma_f32_16x16x32_bf16 v[32:35], v[212:215], v[188:191], v[32:35]
	v_mfma_f32_16x16x32_bf16 v[24:27], v[220:223], v[188:191], v[24:27]
	v_mfma_f32_16x16x32_bf16 v[16:19], v[212:215], v[196:199], v[16:19]
	v_mfma_f32_16x16x32_bf16 v[8:11], v[220:223], v[196:199], v[8:11]
	v_mfma_f32_16x16x32_bf16 v[4:7], v[212:215], v[204:207], v[4:7]
	v_mfma_f32_16x16x32_bf16 v[0:3], v[220:223], v[204:207], v[0:3]
	s_setprio 0
	s_add_i32 s61, 0, 0x18000
	v_add_u32_e32 v146, s61, v149
	s_barrier
	ds_read_b128 v[154:157], v146
	ds_read_b128 v[158:161], v146 offset:1024
	ds_read_b128 v[162:165], v146 offset:2048
	ds_read_b128 v[166:169], v146 offset:3072
	s_add_u32 s28, s28, 0x4000
	s_addc_u32 s29, s29, 0
	s_mov_b32 m0, s38
	v_lshl_add_u64 v[146:147], s[28:29], 0, v[130:131]
	ds_read_b128 v[170:173], v152 offset:32768
	ds_read_b128 v[174:177], v152 offset:33792
	ds_read_b128 v[184:187], v152 offset:34816
	ds_read_b128 v[188:191], v152 offset:35840
	ds_read_b128 v[192:195], v152 offset:36864
	ds_read_b128 v[196:199], v152 offset:37888
	ds_read_b128 v[200:203], v152 offset:38912
	ds_read_b128 v[204:207], v152 offset:39936
	global_load_lds_dwordx4 v[146:147], off
	v_lshl_add_u64 v[146:147], s[28:29], 0, v[134:135]
	s_mov_b32 m0, s39
	s_nop 0
	global_load_lds_dwordx4 v[146:147], off
	v_add_u32_e32 v253, 0x1c000, v149
	ds_read_b128 v[208:211], v253
	ds_read_b128 v[212:215], v253 offset:1024
	ds_read_b128 v[216:219], v253 offset:2048
	ds_read_b128 v[220:223], v253 offset:3072
	s_waitcnt lgkmcnt(0)
	s_waitcnt vmcnt(8)
	s_barrier
	s_setprio 1
	v_mfma_f32_16x16x32_bf16 v[124:127], v[154:157], v[170:173], v[124:127]
	v_mfma_f32_16x16x32_bf16 v[120:123], v[162:165], v[170:173], v[120:123]
	v_mfma_f32_16x16x32_bf16 v[112:115], v[154:157], v[184:187], v[112:115]
	v_mfma_f32_16x16x32_bf16 v[104:107], v[162:165], v[184:187], v[104:107]
	v_mfma_f32_16x16x32_bf16 v[96:99], v[154:157], v[192:195], v[96:99]
	v_mfma_f32_16x16x32_bf16 v[88:91], v[162:165], v[192:195], v[88:91]
	v_mfma_f32_16x16x32_bf16 v[80:83], v[154:157], v[200:203], v[80:83]
	v_mfma_f32_16x16x32_bf16 v[72:75], v[162:165], v[200:203], v[72:75]
	v_mfma_f32_16x16x32_bf16 v[124:127], v[158:161], v[174:177], v[124:127]
	v_mfma_f32_16x16x32_bf16 v[120:123], v[166:169], v[174:177], v[120:123]
	v_mfma_f32_16x16x32_bf16 v[112:115], v[158:161], v[188:191], v[112:115]
	v_mfma_f32_16x16x32_bf16 v[104:107], v[166:169], v[188:191], v[104:107]
	v_mfma_f32_16x16x32_bf16 v[96:99], v[158:161], v[196:199], v[96:99]
	v_mfma_f32_16x16x32_bf16 v[88:91], v[166:169], v[196:199], v[88:91]
	v_mfma_f32_16x16x32_bf16 v[80:83], v[158:161], v[204:207], v[80:83]
	v_mfma_f32_16x16x32_bf16 v[72:75], v[166:169], v[204:207], v[72:75]
	v_mfma_f32_16x16x32_bf16 v[116:119], v[208:211], v[170:173], v[116:119]
	v_mfma_f32_16x16x32_bf16 v[108:111], v[216:219], v[170:173], v[108:111]
	v_mfma_f32_16x16x32_bf16 v[100:103], v[208:211], v[184:187], v[100:103]
	v_mfma_f32_16x16x32_bf16 v[92:95], v[216:219], v[184:187], v[92:95]
	v_mfma_f32_16x16x32_bf16 v[84:87], v[208:211], v[192:195], v[84:87]
	v_mfma_f32_16x16x32_bf16 v[76:79], v[216:219], v[192:195], v[76:79]
	v_mfma_f32_16x16x32_bf16 v[68:71], v[208:211], v[200:203], v[68:71]
	v_mfma_f32_16x16x32_bf16 v[64:67], v[216:219], v[200:203], v[64:67]
	v_mfma_f32_16x16x32_bf16 v[116:119], v[212:215], v[174:177], v[116:119]
	v_mfma_f32_16x16x32_bf16 v[108:111], v[220:223], v[174:177], v[108:111]
	v_mfma_f32_16x16x32_bf16 v[100:103], v[212:215], v[188:191], v[100:103]
	v_mfma_f32_16x16x32_bf16 v[92:95], v[220:223], v[188:191], v[92:95]
	v_mfma_f32_16x16x32_bf16 v[84:87], v[212:215], v[196:199], v[84:87]
	v_mfma_f32_16x16x32_bf16 v[76:79], v[220:223], v[196:199], v[76:79]
	v_mfma_f32_16x16x32_bf16 v[68:71], v[212:215], v[204:207], v[68:71]
	v_mfma_f32_16x16x32_bf16 v[64:67], v[220:223], v[204:207], v[64:67]
	s_setprio 0
	s_barrier
; #define PG8_STAGE(bufoff, gbase, voff) do { _Pragma("unroll") for (int _i = 0; _i < 2; ++_i) \
;         __builtin_amdgcn_global_load_lds((const unsigned*)((const char*)(gbase) + (voff)[_i]), (LAS unsigned*)(lds + (bufoff) + ldsw + _i * 8192), 16, 0, 0); } while (0)
; #define PG8_LDA(dst, b, h) do { _Pragma("unroll") for (int m = 0; m < 4; ++m) _Pragma("unroll") for (int k = 0; k < 2; ++k) dst[m][k] = *(const LAS bf16x8*)(lds + PG8_SA(b, h) + aoff + m * 2048 + k * 1024); } while (0)
; #define PG8_LDB(dst, b, h) do { _Pragma("unroll") for (int n = 0; n < 2; ++n) _Pragma("unroll") for (int k = 0; k < 2; ++k) dst[n][k] = *(const LAS bf16x8*)(lds + PG8_SB(b, h) + boff + n * 2048 + k * 1024); } while (0)
; #define PG8_MMA(ai, bj, At, Bt) do { __builtin_amdgcn_s_setprio(1); _Pragma("unroll") for (int m = 0; m < 4; ++m) _Pragma("unroll") for (int n = 0; n < 2; ++n) _Pragma("unroll") for (int k = 0; k < 2; ++k) \
;         acc[ai][bj][m][n] = __builtin_amdgcn_mfma_f32_16x16x32_bf16(Bt[n][k], At[m][k], acc[ai][bj][m][n], 0, 0, 0); __builtin_amdgcn_s_setprio(0); } while (0)
; #define PG8_WAIT_V(n) asm volatile("s_waitcnt vmcnt(" #n ")" ::: "memory")
; #define PG8_WAIT_L(n) asm volatile("s_waitcnt lgkmcnt(" #n ")" ::: "memory")
; #define PG8_BAR __builtin_amdgcn_s_barrier()
; #define PG8_SCHED __builtin_amdgcn_sched_barrier(0)
; template <class Epi>
; __device__ __forceinline__ void gemm_phase(LAS unsigned char* lds, const Gemm g, const StaticOrder& S, const Epi& E) {
;     ...
;             PG8_LDB(B1, 1, 1); PG8_STAGE(PG8_SB(1, 0), b3, voffB);
;             PG8_BAR; PG8_WAIT_L(0); PG8_MMA(0, 1, At, B1); PG8_BAR;
;             PG8_LDA(At, 1, 1); PG8_STAGE(PG8_SA(1, 0), a3, voffA);
;             PG8_BAR; PG8_WAIT_L(0); PG8_MMA(1, 0, At, B0); PG8_BAR; PG8_SCHED;
;             PG8_STAGE(PG8_SB(1, 1), b3 + hstep, voffB);
;             PG8_WAIT_V(6); PG8_BAR; PG8_MMA(1, 1, At, B1); PG8_BAR;
;         }
	s_add_i32 s62, 0, 0x1c000
	s_add_u32 s28, s24, 0x40000
	v_add_u32_e32 v146, s62, v149
	s_addc_u32 s29, s25, 0
	s_add_i32 s61, s61, s36
	s_nop 0
	v_lshl_add_u64 v[146:147], s[28:29], 0, v[132:133]
	s_mov_b32 m0, s61
	s_nop 0
	global_load_lds_dwordx4 v[146:147], off
	v_lshl_add_u64 v[146:147], s[28:29], 0, v[136:137]
	s_add_i32 m0, s61, 0x2000
	s_nop 0
	global_load_lds_dwordx4 v[146:147], off
	s_mov_b32 m0, s41
	v_lshl_add_u64 v[146:147], s[26:27], 0, v[130:131]
	ds_read_b128 v[170:173], v152 offset:49152
	ds_read_b128 v[174:177], v152 offset:50176
	ds_read_b128 v[184:187], v152 offset:51200
	ds_read_b128 v[188:191], v152 offset:52224
	ds_read_b128 v[192:195], v152 offset:53248
	ds_read_b128 v[196:199], v152 offset:54272
	ds_read_b128 v[200:203], v152 offset:55296
	ds_read_b128 v[204:207], v152 offset:56320
	global_load_lds_dwordx4 v[146:147], off
	v_lshl_add_u64 v[146:147], s[26:27], 0, v[134:135]
	s_mov_b32 m0, s42
	s_nop 0
	global_load_lds_dwordx4 v[146:147], off
	s_add_u32 s24, s24, 0x44000
	s_addc_u32 s25, s25, 0
	s_add_i32 s26, s62, s36
	v_lshl_add_u64 v[146:147], s[24:25], 0, v[132:133]
	s_mov_b32 m0, s26
	s_nop 0
	global_load_lds_dwordx4 v[146:147], off
	v_lshl_add_u64 v[146:147], s[24:25], 0, v[136:137]
	s_add_i32 m0, s26, 0x2000
	s_nop 0
	global_load_lds_dwordx4 v[146:147], off
	s_waitcnt lgkmcnt(0)
	s_waitcnt vmcnt(8)
	s_barrier
	s_setprio 1
	v_mfma_f32_16x16x32_bf16 v[60:63], v[154:157], v[170:173], v[60:63]
	v_mfma_f32_16x16x32_bf16 v[56:59], v[162:165], v[170:173], v[56:59]
	v_mfma_f32_16x16x32_bf16 v[52:55], v[154:157], v[184:187], v[52:55]
	v_mfma_f32_16x16x32_bf16 v[44:47], v[162:165], v[184:187], v[44:47]
	v_mfma_f32_16x16x32_bf16 v[36:39], v[154:157], v[192:195], v[36:39]
	v_mfma_f32_16x16x32_bf16 v[28:31], v[162:165], v[192:195], v[28:31]
	v_mfma_f32_16x16x32_bf16 v[20:23], v[154:157], v[200:203], v[20:23]
	v_mfma_f32_16x16x32_bf16 v[12:15], v[162:165], v[200:203], v[12:15]
	v_mfma_f32_16x16x32_bf16 v[60:63], v[158:161], v[174:177], v[60:63]
	v_mfma_f32_16x16x32_bf16 v[56:59], v[166:169], v[174:177], v[56:59]
	v_mfma_f32_16x16x32_bf16 v[52:55], v[158:161], v[188:191], v[52:55]
	v_mfma_f32_16x16x32_bf16 v[44:47], v[166:169], v[188:191], v[44:47]
	v_mfma_f32_16x16x32_bf16 v[36:39], v[158:161], v[196:199], v[36:39]
	v_mfma_f32_16x16x32_bf16 v[28:31], v[166:169], v[196:199], v[28:31]
	v_mfma_f32_16x16x32_bf16 v[20:23], v[158:161], v[204:207], v[20:23]
	v_mfma_f32_16x16x32_bf16 v[12:15], v[166:169], v[204:207], v[12:15]
	v_mfma_f32_16x16x32_bf16 v[48:51], v[208:211], v[170:173], v[48:51]
	v_mfma_f32_16x16x32_bf16 v[40:43], v[216:219], v[170:173], v[40:43]
	v_mfma_f32_16x16x32_bf16 v[32:35], v[208:211], v[184:187], v[32:35]
	v_mfma_f32_16x16x32_bf16 v[24:27], v[216:219], v[184:187], v[24:27]
	v_mfma_f32_16x16x32_bf16 v[16:19], v[208:211], v[192:195], v[16:19]
	v_mfma_f32_16x16x32_bf16 v[8:11], v[216:219], v[192:195], v[8:11]
	v_mfma_f32_16x16x32_bf16 v[4:7], v[208:211], v[200:203], v[4:7]
	v_mfma_f32_16x16x32_bf16 v[0:3], v[216:219], v[200:203], v[0:3]
	v_mfma_f32_16x16x32_bf16 v[48:51], v[212:215], v[174:177], v[48:51]
	v_mfma_f32_16x16x32_bf16 v[40:43], v[220:223], v[174:177], v[40:43]
	v_mfma_f32_16x16x32_bf16 v[32:35], v[212:215], v[188:191], v[32:35]
	v_mfma_f32_16x16x32_bf16 v[24:27], v[220:223], v[188:191], v[24:27]
	v_mfma_f32_16x16x32_bf16 v[16:19], v[212:215], v[196:199], v[16:19]
	v_mfma_f32_16x16x32_bf16 v[8:11], v[220:223], v[196:199], v[8:11]
	v_mfma_f32_16x16x32_bf16 v[4:7], v[212:215], v[204:207], v[4:7]
	v_mfma_f32_16x16x32_bf16 v[0:3], v[220:223], v[204:207], v[0:3]
	s_setprio 0
	s_add_i32 s60, s60, 2
	s_add_u32 s58, s58, 0x80000
	s_addc_u32 s59, s59, 0
	s_add_u32 s22, s22, 0x800000
	s_addc_u32 s23, s23, 0
	s_cmpk_gt_u32 s60, 0x55
	s_barrier
	s_cbranch_scc0 .LBB0_957
; __device__ __forceinline__ unsigned pk_bf16(float lo, float hi) { unsigned r; asm("v_cvt_pk_bf16_f32 %0, %1, %2" : "=v"(r) : "v"(lo), "v"(hi)); return r; }
;     __device__ __forceinline__ void operator()(const f32x4 (&acc)[2][2][4][2], const Unit& u, int wr, int wc, int fr, int fq) const {
;         const int row0 = u.pm * BM + wr * 64 + fr; const int col0 = u.pn * BM + wc * 32 + 8 * fq;
; #pragma unroll
;         for (int ai = 0; ai < 2; ++ai)
; #pragma unroll
;             for (int m = 0; m < 4; ++m) { bf16_t* rowp = O + (size_t)(row0 + ai * HALF + m * 16) * ldc + col0;
; #pragma unroll
;                 for (int bj = 0; bj < 2; ++bj) { const f32x4 v0 = acc[ai][bj][m][0], v1 = acc[ai][bj][m][1];
;                     u32x4 w; w.x = pk_bf16(v0[0], v0[1]); w.y = pk_bf16(v0[2], v0[3]); w.z = pk_bf16(v1[0], v1[1]); w.w = pk_bf16(v1[2], v1[3]);
;                     *(u32x4*)(rowp + bj * HALF) = w; } }
;     }
	v_lshl_add_u32 v154, s20, 8, v148
	v_lshl_or_b32 v146, s55, 8, v150
	v_ashrrev_i32_e32 v155, 31, v154
	v_ashrrev_i32_e32 v147, 31, v146
	v_lshlrev_b64 v[156:157], 12, v[154:155]
	v_lshl_add_u64 v[156:157], s[52:53], 0, v[156:157]
	v_lshlrev_b64 v[158:159], 1, v[146:147]
	v_lshl_add_u64 v[146:147], v[156:157], 0, v[158:159]
	v_cvt_pk_bf16_f32 v60, v60, v61
	v_cvt_pk_bf16_f32 v61, v62, v63
	v_cvt_pk_bf16_f32 v62, v56, v57
	v_add_co_u32_e32 v56, vcc, s49, v146
	v_cvt_pk_bf16_f32 v116, v116, v117
	v_cvt_pk_bf16_f32 v117, v118, v119
	v_cvt_pk_bf16_f32 v118, v108, v109
	v_or_b32_e32 v108, 16, v154
	s_nop 0
	v_addc_co_u32_e32 v57, vcc, 0, v147, vcc
	v_cvt_pk_bf16_f32 v48, v48, v49
	v_cvt_pk_bf16_f32 v49, v50, v51
	v_cvt_pk_bf16_f32 v51, v42, v43
	v_cvt_pk_bf16_f32 v42, v44, v45
	v_add_co_u32_e32 v44, vcc, s50, v146
	v_ashrrev_i32_e32 v109, 31, v108
	v_cvt_pk_bf16_f32 v100, v100, v101
	v_cvt_pk_bf16_f32 v101, v102, v103
	v_cvt_pk_bf16_f32 v102, v92, v93
	v_or_b32_e32 v92, 32, v154
	v_addc_co_u32_e32 v45, vcc, 0, v147, vcc
	v_lshlrev_b64 v[108:109], 12, v[108:109]
	v_ashrrev_i32_e32 v93, 31, v92
	v_cvt_pk_bf16_f32 v84, v84, v85
	v_cvt_pk_bf16_f32 v85, v86, v87
	v_cvt_pk_bf16_f32 v86, v76, v77
	v_or_b32_e32 v76, 48, v154
	v_cvt_pk_bf16_f32 v32, v32, v33
	v_cvt_pk_bf16_f32 v33, v34, v35
	v_cvt_pk_bf16_f32 v35, v26, v27
	v_cvt_pk_bf16_f32 v26, v28, v29
	v_add_co_u32_e32 v28, vcc, s51, v146
	v_lshl_add_u64 v[108:109], s[52:53], 0, v[108:109]
	v_lshlrev_b64 v[92:93], 12, v[92:93]
	v_ashrrev_i32_e32 v77, 31, v76
	v_cvt_pk_bf16_f32 v68, v68, v69
	v_cvt_pk_bf16_f32 v69, v70, v71
	v_cvt_pk_bf16_f32 v70, v64, v65
	v_lshl_add_u64 v[64:65], v[146:147], 0, s[0:1]
	v_addc_co_u32_e32 v29, vcc, 0, v147, vcc
	v_cvt_pk_bf16_f32 v119, v110, v111
	global_store_dwordx4 v[146:147], v[116:119], off offset:256
	v_lshl_add_u64 v[92:93], s[52:53], 0, v[92:93]
	v_lshlrev_b64 v[76:77], 12, v[76:77]
	v_lshl_add_u64 v[116:117], v[108:109], 0, v[158:159]
	v_cvt_pk_bf16_f32 v50, v40, v41
	global_store_dwordx4 v[64:65], v[48:51], off offset:256
	v_cvt_pk_bf16_f32 v16, v16, v17
	v_cvt_pk_bf16_f32 v17, v18, v19
	v_cvt_pk_bf16_f32 v19, v10, v11
	v_cvt_pk_bf16_f32 v10, v12, v13
	v_add_co_u32_e32 v12, vcc, s54, v146
	s_nop 0
	v_lshl_add_u64 v[48:49], v[146:147], 0, s[6:7]
	v_cvt_pk_bf16_f32 v103, v94, v95
	global_store_dwordx4 v[116:117], v[100:103], off offset:256
	v_lshl_add_u64 v[76:77], s[52:53], 0, v[76:77]
	v_cvt_pk_bf16_f32 v34, v24, v25
	global_store_dwordx4 v[48:49], v[32:35], off offset:256
	v_lshl_add_u64 v[100:101], v[92:93], 0, v[158:159]
	v_addc_co_u32_e32 v13, vcc, 0, v147, vcc
	v_lshl_add_u64 v[32:33], v[146:147], 0, s[8:9]
	v_cvt_pk_bf16_f32 v87, v78, v79
	global_store_dwordx4 v[100:101], v[84:87], off offset:256
	v_cvt_pk_bf16_f32 v18, v8, v9
	global_store_dwordx4 v[32:33], v[16:19], off offset:256
	s_and_b64 vcc, exec, s[4:5]
	v_lshl_add_u64 v[84:85], v[76:77], 0, v[158:159]
	v_lshl_add_u64 v[16:17], v[146:147], 0, s[10:11]
	s_mov_b32 s55, s12
	s_mov_b32 s20, s14
	s_mov_b64 s[22:23], s[18:19]
	s_mov_b64 s[24:25], s[16:17]
	v_cvt_pk_bf16_f32 v124, v124, v125
	v_cvt_pk_bf16_f32 v125, v126, v127
	v_cvt_pk_bf16_f32 v126, v120, v121
	v_cvt_pk_bf16_f32 v127, v122, v123
	global_store_dwordx4 v[146:147], v[124:127], off
	v_cvt_pk_bf16_f32 v108, v112, v113
	v_cvt_pk_bf16_f32 v109, v114, v115
	v_cvt_pk_bf16_f32 v110, v104, v105
	v_cvt_pk_bf16_f32 v111, v106, v107
	global_store_dwordx4 v[116:117], v[108:111], off
	v_cvt_pk_bf16_f32 v92, v96, v97
	v_cvt_pk_bf16_f32 v93, v98, v99
	v_cvt_pk_bf16_f32 v94, v88, v89
	v_cvt_pk_bf16_f32 v95, v90, v91
	global_store_dwordx4 v[100:101], v[92:95], off
	v_cvt_pk_bf16_f32 v76, v80, v81
	v_cvt_pk_bf16_f32 v77, v82, v83
	v_cvt_pk_bf16_f32 v78, v72, v73
	v_cvt_pk_bf16_f32 v79, v74, v75
	global_store_dwordx4 v[84:85], v[76:79], off
	v_cvt_pk_bf16_f32 v71, v66, v67
	global_store_dwordx4 v[84:85], v[68:71], off offset:256
	v_cvt_pk_bf16_f32 v63, v58, v59
	global_store_dwordx4 v[56:57], v[60:63], off
	v_cvt_pk_bf16_f32 v40, v52, v53
	v_cvt_pk_bf16_f32 v41, v54, v55
	v_cvt_pk_bf16_f32 v43, v46, v47
	global_store_dwordx4 v[44:45], v[40:43], off
	v_cvt_pk_bf16_f32 v24, v36, v37
	v_cvt_pk_bf16_f32 v25, v38, v39
	v_cvt_pk_bf16_f32 v27, v30, v31
	global_store_dwordx4 v[28:29], v[24:27], off
	v_cvt_pk_bf16_f32 v8, v20, v21
	v_cvt_pk_bf16_f32 v9, v22, v23
	v_cvt_pk_bf16_f32 v11, v14, v15
	global_store_dwordx4 v[12:13], v[8:11], off
	v_cvt_pk_bf16_f32 v4, v4, v5
	v_cvt_pk_bf16_f32 v5, v6, v7
	v_cvt_pk_bf16_f32 v6, v0, v1
	v_cvt_pk_bf16_f32 v7, v2, v3
	global_store_dwordx4 v[16:17], v[4:7], off offset:256
	s_cbranch_vccz .LBB0_950
	s_waitcnt vmcnt(0)
	s_cmpk_gt_u32 s30, 0xff
	s_cbranch_scc1 .LBB0_961
	s_barrier

; __global__ void __launch_bounds__(512, 2) mega_fwd(Params p) {
	.amdhsa_kernel _Z8mega_fwd6Params
		.amdhsa_group_segment_fixed_size 0
		.amdhsa_private_segment_fixed_size 0
		.amdhsa_kernarg_size 456
		.amdhsa_user_sgpr_count 2
		.amdhsa_user_sgpr_dispatch_ptr 0
		.amdhsa_user_sgpr_queue_ptr 0
		.amdhsa_user_sgpr_kernarg_segment_ptr 1
		.amdhsa_user_sgpr_dispatch_id 0
		.amdhsa_user_sgpr_kernarg_preload_length 0
		.amdhsa_user_sgpr_kernarg_preload_offset 0
		.amdhsa_user_sgpr_private_segment_size 0
		.amdhsa_uses_dynamic_stack 0
		.amdhsa_enable_private_segment 0
		.amdhsa_system_sgpr_workgroup_id_x 1
		.amdhsa_system_sgpr_workgroup_id_y 0
		.amdhsa_system_sgpr_workgroup_id_z 0
		.amdhsa_system_sgpr_workgroup_info 0
		.amdhsa_system_vgpr_workitem_id 2
		.amdhsa_next_free_vgpr 256
		.amdhsa_next_free_sgpr 98
		.amdhsa_accum_offset 256
		.amdhsa_reserve_vcc 1
		.amdhsa_float_round_mode_32 0
		.amdhsa_float_round_mode_16_64 0
		.amdhsa_float_denorm_mode_32 3
		.amdhsa_float_denorm_mode_16_64 3
		.amdhsa_dx10_clamp 1
		.amdhsa_ieee_mode 1
		.amdhsa_fp16_overflow 0
		.amdhsa_tg_split 0
		.amdhsa_exception_fp_ieee_invalid_op 0
		.amdhsa_exception_fp_denorm_src 0
		.amdhsa_exception_fp_ieee_div_zero 0
		.amdhsa_exception_fp_ieee_overflow 0
		.amdhsa_exception_fp_ieee_underflow 0
		.amdhsa_exception_fp_ieee_inexact 0
		.amdhsa_exception_int_div_zero 0
	.end_amdhsa_kernel

; __global__ void __launch_bounds__(512, 2) mega_fwd(Params p) {
amdhsa.kernels:
  - .agpr_count:     0
    .args:
      - .offset:         0
        .size:           200
        .value_kind:     by_value
      - .offset:         200
        .size:           4
        .value_kind:     hidden_block_count_x
      - .offset:         204
        .size:           4
        .value_kind:     hidden_block_count_y
      - .offset:         208
        .size:           4
        .value_kind:     hidden_block_count_z
      - .offset:         212
        .size:           2
        .value_kind:     hidden_group_size_x
      - .offset:         214
        .size:           2
        .value_kind:     hidden_group_size_y
      - .offset:         216
        .size:           2
        .value_kind:     hidden_group_size_z
      - .offset:         218
        .size:           2
        .value_kind:     hidden_remainder_x
      - .offset:         220
        .size:           2
        .value_kind:     hidden_remainder_y
      - .offset:         222
        .size:           2
        .value_kind:     hidden_remainder_z
      - .offset:         240
        .size:           8
        .value_kind:     hidden_global_offset_x
      - .offset:         248
        .size:           8
        .value_kind:     hidden_global_offset_y
      - .offset:         256
        .size:           8
        .value_kind:     hidden_global_offset_z
      - .offset:         264
        .size:           2
        .value_kind:     hidden_grid_dims
      - .offset:         288
        .size:           8
        .value_kind:     hidden_multigrid_sync_arg
      - .offset:         320
        .size:           4
        .value_kind:     hidden_dynamic_lds_size
    .group_segment_fixed_size: 0
    .kernarg_segment_align: 8
    .kernarg_segment_size: 456
    .language:       OpenCL C
    .language_version:
      - 2
      - 0
    .max_flat_workgroup_size: 512
    .name:           _Z8mega_fwd6Params
    .private_segment_fixed_size: 0
    .sgpr_count:     104
    .sgpr_spill_count: 46
    .symbol:         _Z8mega_fwd6Params.kd
    .uniform_work_group_size: 1
    .uses_dynamic_stack: false
    .vgpr_count:     256
    .vgpr_spill_count: 0
    .wavefront_size: 64
